# GEMM K-loop: the barrier that closes each MFMA block is issued two MFMAs early (tail at s_setprio 2), on top of the diff-attention block order change
# speedup vs baseline: 1.0087x; 1.0049x over previous
.LBB0_359:
	ds_read_b128 v[130:133], v185
	ds_read_b128 v[134:137], v185 offset:1024
	ds_read_b128 v[138:141], v185 offset:2048
	ds_read_b128 v[142:145], v185 offset:3072
	ds_read_b128 v[146:149], v187
	ds_read_b128 v[150:153], v187 offset:1024
	ds_read_b128 v[154:157], v187 offset:2048
	ds_read_b128 v[192:195], v187 offset:3072
	s_add_u32 s30, s28, 0xfff80080
	s_addc_u32 s31, s29, -1
	s_cmp_eq_u32 s76, 28
	s_cselect_b32 s35, s6, s31
	s_cselect_b32 s34, s21, s30
	s_cselect_b32 s31, s19, s75
	s_cselect_b32 s30, s73, s74
	v_lshl_add_u64 v[158:159], s[28:29], 0, v[174:175]
	s_add_i32 m0, s27, 0xc000
	ds_read_b128 v[196:199], v189
	ds_read_b128 v[200:203], v189 offset:1024
	ds_read_b128 v[204:207], v189 offset:2048
	ds_read_b128 v[208:211], v189 offset:3072
	ds_read_b128 v[212:215], v189 offset:4096
	ds_read_b128 v[216:219], v189 offset:5120
	ds_read_b128 v[220:223], v189 offset:6144
	ds_read_b128 v[224:227], v189 offset:7168
	global_load_lds_dwordx4 v[158:159], off
	v_lshl_add_u64 v[158:159], s[28:29], 0, v[172:173]
	s_add_i32 m0, s27, 0xe000
	s_nop 0
	global_load_lds_dwordx4 v[158:159], off
	s_waitcnt vmcnt(8)
	s_waitcnt lgkmcnt(0)
	s_barrier
	s_setprio 1
	s_waitcnt lgkmcnt(0)
	v_mfma_f32_16x16x32_bf16 v[124:127], v[130:133], v[196:199], v[124:127]
	v_mfma_f32_16x16x32_bf16 v[120:123], v[138:141], v[196:199], v[120:123]
	v_mfma_f32_16x16x32_bf16 v[112:115], v[130:133], v[204:207], v[112:115]
	v_mfma_f32_16x16x32_bf16 v[104:107], v[138:141], v[204:207], v[104:107]
	v_mfma_f32_16x16x32_bf16 v[96:99], v[130:133], v[212:215], v[96:99]
	v_mfma_f32_16x16x32_bf16 v[88:91], v[138:141], v[212:215], v[88:91]
	v_mfma_f32_16x16x32_bf16 v[80:83], v[130:133], v[220:223], v[80:83]
	v_mfma_f32_16x16x32_bf16 v[72:75], v[138:141], v[220:223], v[72:75]
	v_mfma_f32_16x16x32_bf16 v[124:127], v[134:137], v[200:203], v[124:127]
	v_mfma_f32_16x16x32_bf16 v[120:123], v[142:145], v[200:203], v[120:123]
	v_mfma_f32_16x16x32_bf16 v[112:115], v[134:137], v[208:211], v[112:115]
	v_mfma_f32_16x16x32_bf16 v[104:107], v[142:145], v[208:211], v[104:107]
	v_mfma_f32_16x16x32_bf16 v[96:99], v[134:137], v[216:219], v[96:99]
	v_mfma_f32_16x16x32_bf16 v[88:91], v[142:145], v[216:219], v[88:91]
	v_mfma_f32_16x16x32_bf16 v[80:83], v[134:137], v[224:227], v[80:83]
	v_mfma_f32_16x16x32_bf16 v[72:75], v[142:145], v[224:227], v[72:75]
	s_setprio 0
	s_setprio 1
	v_mfma_f32_16x16x32_bf16 v[116:119], v[146:149], v[196:199], v[116:119]
	v_mfma_f32_16x16x32_bf16 v[108:111], v[154:157], v[196:199], v[108:111]
	v_mfma_f32_16x16x32_bf16 v[100:103], v[146:149], v[204:207], v[100:103]
	v_mfma_f32_16x16x32_bf16 v[92:95], v[154:157], v[204:207], v[92:95]
	v_mfma_f32_16x16x32_bf16 v[84:87], v[146:149], v[212:215], v[84:87]
	v_mfma_f32_16x16x32_bf16 v[76:79], v[154:157], v[212:215], v[76:79]
	v_mfma_f32_16x16x32_bf16 v[68:71], v[146:149], v[220:223], v[68:71]
	v_mfma_f32_16x16x32_bf16 v[64:67], v[154:157], v[220:223], v[64:67]
	v_mfma_f32_16x16x32_bf16 v[116:119], v[150:153], v[200:203], v[116:119]
	v_mfma_f32_16x16x32_bf16 v[108:111], v[192:195], v[200:203], v[108:111]
	v_mfma_f32_16x16x32_bf16 v[100:103], v[150:153], v[208:211], v[100:103]
	v_mfma_f32_16x16x32_bf16 v[92:95], v[192:195], v[208:211], v[92:95]
	v_mfma_f32_16x16x32_bf16 v[84:87], v[150:153], v[216:219], v[84:87]
	v_mfma_f32_16x16x32_bf16 v[76:79], v[192:195], v[216:219], v[76:79]
	s_barrier
	s_setprio 2
	v_mfma_f32_16x16x32_bf16 v[68:71], v[150:153], v[224:227], v[68:71]
	v_mfma_f32_16x16x32_bf16 v[64:67], v[192:195], v[224:227], v[64:67]
	s_setprio 0
	s_add_i32 s77, s57, s67
	v_lshl_add_u64 v[158:159], s[30:31], 0, v[162:163]
	s_mov_b32 m0, s77
	ds_read_b128 v[196:199], v189 offset:16384
	ds_read_b128 v[200:203], v189 offset:17408
	ds_read_b128 v[204:207], v189 offset:18432
	ds_read_b128 v[208:211], v189 offset:19456
	ds_read_b128 v[212:215], v189 offset:20480
	ds_read_b128 v[216:219], v189 offset:21504
	ds_read_b128 v[220:223], v189 offset:22528
	ds_read_b128 v[224:227], v189 offset:23552
	global_load_lds_dwordx4 v[158:159], off
	s_add_i32 m0, s77, 0x2000
	s_add_u32 s78, s30, 0x80000
	v_lshl_add_u64 v[228:229], s[30:31], 0, v[166:167]
	s_addc_u32 s79, s31, 0
	s_add_i32 s77, s58, s67
	global_load_lds_dwordx4 v[228:229], off
	v_lshl_add_u64 v[230:231], s[78:79], 0, v[162:163]
	s_mov_b32 m0, s77
	v_lshl_add_u64 v[232:233], s[34:35], 0, v[164:165]
	global_load_lds_dwordx4 v[230:231], off
	v_lshl_add_u64 v[230:231], s[78:79], 0, v[166:167]
	s_add_i32 m0, s77, 0x2000
	s_nop 0
	global_load_lds_dwordx4 v[230:231], off
	v_lshl_add_u64 v[230:231], s[34:35], 0, v[160:161]
	s_mov_b32 m0, s27
	s_nop 0
	global_load_lds_dwordx4 v[230:231], off
	s_mov_b32 m0, s41
	s_nop 0
	global_load_lds_dwordx4 v[232:233], off
	s_waitcnt vmcnt(8)
	s_waitcnt lgkmcnt(0)
	s_barrier
	s_setprio 1
	s_waitcnt lgkmcnt(0)
	v_mfma_f32_16x16x32_bf16 v[60:63], v[130:133], v[196:199], v[60:63]
	v_mfma_f32_16x16x32_bf16 v[56:59], v[138:141], v[196:199], v[56:59]
	v_mfma_f32_16x16x32_bf16 v[48:51], v[130:133], v[204:207], v[48:51]
	v_mfma_f32_16x16x32_bf16 v[40:43], v[138:141], v[204:207], v[40:43]
	v_mfma_f32_16x16x32_bf16 v[32:35], v[130:133], v[212:215], v[32:35]
	v_mfma_f32_16x16x32_bf16 v[24:27], v[138:141], v[212:215], v[24:27]
	v_mfma_f32_16x16x32_bf16 v[16:19], v[130:133], v[220:223], v[16:19]
	v_mfma_f32_16x16x32_bf16 v[8:11], v[138:141], v[220:223], v[8:11]
	v_mfma_f32_16x16x32_bf16 v[60:63], v[134:137], v[200:203], v[60:63]
	v_mfma_f32_16x16x32_bf16 v[56:59], v[142:145], v[200:203], v[56:59]
	v_mfma_f32_16x16x32_bf16 v[48:51], v[134:137], v[208:211], v[48:51]
	v_mfma_f32_16x16x32_bf16 v[40:43], v[142:145], v[208:211], v[40:43]
	v_mfma_f32_16x16x32_bf16 v[32:35], v[134:137], v[216:219], v[32:35]
	v_mfma_f32_16x16x32_bf16 v[24:27], v[142:145], v[216:219], v[24:27]
	v_mfma_f32_16x16x32_bf16 v[16:19], v[134:137], v[224:227], v[16:19]
	v_mfma_f32_16x16x32_bf16 v[8:11], v[142:145], v[224:227], v[8:11]
	s_setprio 0
	s_setprio 1
	v_mfma_f32_16x16x32_bf16 v[52:55], v[146:149], v[196:199], v[52:55]
	v_mfma_f32_16x16x32_bf16 v[44:47], v[154:157], v[196:199], v[44:47]
	v_mfma_f32_16x16x32_bf16 v[36:39], v[146:149], v[204:207], v[36:39]
	v_mfma_f32_16x16x32_bf16 v[28:31], v[154:157], v[204:207], v[28:31]
	v_mfma_f32_16x16x32_bf16 v[20:23], v[146:149], v[212:215], v[20:23]
	v_mfma_f32_16x16x32_bf16 v[12:15], v[154:157], v[212:215], v[12:15]
	v_mfma_f32_16x16x32_bf16 v[4:7], v[146:149], v[220:223], v[4:7]
	v_mfma_f32_16x16x32_bf16 v[0:3], v[154:157], v[220:223], v[0:3]
	v_mfma_f32_16x16x32_bf16 v[52:55], v[150:153], v[200:203], v[52:55]
	v_mfma_f32_16x16x32_bf16 v[44:47], v[192:195], v[200:203], v[44:47]
	v_mfma_f32_16x16x32_bf16 v[36:39], v[150:153], v[208:211], v[36:39]
	v_mfma_f32_16x16x32_bf16 v[28:31], v[192:195], v[208:211], v[28:31]
	v_mfma_f32_16x16x32_bf16 v[20:23], v[150:153], v[216:219], v[20:23]
	v_mfma_f32_16x16x32_bf16 v[12:15], v[192:195], v[216:219], v[12:15]
	s_barrier
	s_setprio 2
	v_mfma_f32_16x16x32_bf16 v[4:7], v[150:153], v[224:227], v[4:7]
	v_mfma_f32_16x16x32_bf16 v[0:3], v[192:195], v[224:227], v[0:3]
	s_setprio 0
	s_add_i32 s77, 0, 0x18000
	v_add_u32_e32 v129, s77, v181
	s_add_i32 s78, 0, 0x1c000
	ds_read_b128 v[130:133], v129
	ds_read_b128 v[134:137], v129 offset:1024
	ds_read_b128 v[138:141], v129 offset:2048
	ds_read_b128 v[142:145], v129 offset:3072
	v_add_u32_e32 v129, s78, v181
	ds_read_b128 v[146:149], v129
	ds_read_b128 v[150:153], v129 offset:1024
	ds_read_b128 v[154:157], v129 offset:2048
	ds_read_b128 v[192:195], v129 offset:3072
	s_add_u32 s34, s34, 0x80000
	s_addc_u32 s35, s35, 0
	s_mov_b32 m0, s42
	v_lshl_add_u64 v[234:235], s[34:35], 0, v[160:161]
	ds_read_b128 v[196:199], v189 offset:32768
	ds_read_b128 v[200:203], v189 offset:33792
	ds_read_b128 v[204:207], v189 offset:34816
	ds_read_b128 v[208:211], v189 offset:35840
	ds_read_b128 v[212:215], v189 offset:36864
	ds_read_b128 v[216:219], v189 offset:37888
	ds_read_b128 v[220:223], v189 offset:38912
	ds_read_b128 v[224:227], v189 offset:39936
	global_load_lds_dwordx4 v[234:235], off
	v_lshl_add_u64 v[234:235], s[34:35], 0, v[164:165]
	s_mov_b32 m0, s43
	s_nop 0
	global_load_lds_dwordx4 v[234:235], off
	s_waitcnt vmcnt(8)
	s_waitcnt lgkmcnt(0)
	s_barrier
	s_setprio 1
	s_waitcnt lgkmcnt(0)
	v_mfma_f32_16x16x32_bf16 v[124:127], v[130:133], v[196:199], v[124:127]
	v_mfma_f32_16x16x32_bf16 v[120:123], v[138:141], v[196:199], v[120:123]
	v_mfma_f32_16x16x32_bf16 v[112:115], v[130:133], v[204:207], v[112:115]
	v_mfma_f32_16x16x32_bf16 v[104:107], v[138:141], v[204:207], v[104:107]
	v_mfma_f32_16x16x32_bf16 v[96:99], v[130:133], v[212:215], v[96:99]
	v_mfma_f32_16x16x32_bf16 v[88:91], v[138:141], v[212:215], v[88:91]
	v_mfma_f32_16x16x32_bf16 v[80:83], v[130:133], v[220:223], v[80:83]
	v_mfma_f32_16x16x32_bf16 v[72:75], v[138:141], v[220:223], v[72:75]
	v_mfma_f32_16x16x32_bf16 v[124:127], v[134:137], v[200:203], v[124:127]
	v_mfma_f32_16x16x32_bf16 v[120:123], v[142:145], v[200:203], v[120:123]
	v_mfma_f32_16x16x32_bf16 v[112:115], v[134:137], v[208:211], v[112:115]
	v_mfma_f32_16x16x32_bf16 v[104:107], v[142:145], v[208:211], v[104:107]
	v_mfma_f32_16x16x32_bf16 v[96:99], v[134:137], v[216:219], v[96:99]
	v_mfma_f32_16x16x32_bf16 v[88:91], v[142:145], v[216:219], v[88:91]
	v_mfma_f32_16x16x32_bf16 v[80:83], v[134:137], v[224:227], v[80:83]
	v_mfma_f32_16x16x32_bf16 v[72:75], v[142:145], v[224:227], v[72:75]
	s_setprio 0
	s_setprio 1
	v_mfma_f32_16x16x32_bf16 v[116:119], v[146:149], v[196:199], v[116:119]
	v_mfma_f32_16x16x32_bf16 v[108:111], v[154:157], v[196:199], v[108:111]
	v_mfma_f32_16x16x32_bf16 v[100:103], v[146:149], v[204:207], v[100:103]
	v_mfma_f32_16x16x32_bf16 v[92:95], v[154:157], v[204:207], v[92:95]
	v_mfma_f32_16x16x32_bf16 v[84:87], v[146:149], v[212:215], v[84:87]
	v_mfma_f32_16x16x32_bf16 v[76:79], v[154:157], v[212:215], v[76:79]
	v_mfma_f32_16x16x32_bf16 v[68:71], v[146:149], v[220:223], v[68:71]
	v_mfma_f32_16x16x32_bf16 v[64:67], v[154:157], v[220:223], v[64:67]
	v_mfma_f32_16x16x32_bf16 v[116:119], v[150:153], v[200:203], v[116:119]
	v_mfma_f32_16x16x32_bf16 v[108:111], v[192:195], v[200:203], v[108:111]
	v_mfma_f32_16x16x32_bf16 v[100:103], v[150:153], v[208:211], v[100:103]
	v_mfma_f32_16x16x32_bf16 v[92:95], v[192:195], v[208:211], v[92:95]
	v_mfma_f32_16x16x32_bf16 v[84:87], v[150:153], v[216:219], v[84:87]
	v_mfma_f32_16x16x32_bf16 v[76:79], v[192:195], v[216:219], v[76:79]
	s_barrier
	s_setprio 2
	v_mfma_f32_16x16x32_bf16 v[68:71], v[150:153], v[224:227], v[68:71]
	v_mfma_f32_16x16x32_bf16 v[64:67], v[192:195], v[224:227], v[64:67]
	s_setprio 0
	s_add_i32 s34, s77, s67
	v_lshl_add_u64 v[158:159], v[158:159], 0, s[12:13]
	s_mov_b32 m0, s34
	ds_read_b128 v[196:199], v189 offset:49152
	ds_read_b128 v[200:203], v189 offset:50176
	ds_read_b128 v[204:207], v189 offset:51200
	ds_read_b128 v[208:211], v189 offset:52224
	ds_read_b128 v[212:215], v189 offset:53248
	ds_read_b128 v[216:219], v189 offset:54272
	ds_read_b128 v[220:223], v189 offset:55296
	ds_read_b128 v[224:227], v189 offset:56320
	global_load_lds_dwordx4 v[158:159], off
	s_add_i32 m0, s34, 0x2000
	s_add_u32 s30, s30, 0x80080
	v_lshl_add_u64 v[158:159], v[228:229], 0, s[12:13]
	s_addc_u32 s31, s31, 0
	s_add_i32 s34, s78, s67
	global_load_lds_dwordx4 v[158:159], off
	v_lshl_add_u64 v[158:159], s[30:31], 0, v[162:163]
	s_mov_b32 m0, s34
	s_nop 0
	global_load_lds_dwordx4 v[158:159], off
	v_lshl_add_u64 v[158:159], s[30:31], 0, v[166:167]
	s_add_i32 m0, s34, 0x2000
	s_nop 0
	global_load_lds_dwordx4 v[158:159], off
	v_lshl_add_u64 v[158:159], v[230:231], 0, s[12:13]
	s_mov_b32 m0, s45
	s_nop 0
	global_load_lds_dwordx4 v[158:159], off
	v_lshl_add_u64 v[158:159], v[232:233], 0, s[12:13]
	s_mov_b32 m0, s47
	s_nop 0
	global_load_lds_dwordx4 v[158:159], off
	s_waitcnt vmcnt(8)
	s_waitcnt lgkmcnt(0)
	s_barrier
	s_setprio 1
	s_waitcnt lgkmcnt(0)
	v_mfma_f32_16x16x32_bf16 v[60:63], v[130:133], v[196:199], v[60:63]
	v_mfma_f32_16x16x32_bf16 v[56:59], v[138:141], v[196:199], v[56:59]
	v_mfma_f32_16x16x32_bf16 v[48:51], v[130:133], v[204:207], v[48:51]
	v_mfma_f32_16x16x32_bf16 v[40:43], v[138:141], v[204:207], v[40:43]
	v_mfma_f32_16x16x32_bf16 v[32:35], v[130:133], v[212:215], v[32:35]
	v_mfma_f32_16x16x32_bf16 v[24:27], v[138:141], v[212:215], v[24:27]
	v_mfma_f32_16x16x32_bf16 v[16:19], v[130:133], v[220:223], v[16:19]
	v_mfma_f32_16x16x32_bf16 v[8:11], v[138:141], v[220:223], v[8:11]
	v_mfma_f32_16x16x32_bf16 v[60:63], v[134:137], v[200:203], v[60:63]
	v_mfma_f32_16x16x32_bf16 v[56:59], v[142:145], v[200:203], v[56:59]
	v_mfma_f32_16x16x32_bf16 v[48:51], v[134:137], v[208:211], v[48:51]
	v_mfma_f32_16x16x32_bf16 v[40:43], v[142:145], v[208:211], v[40:43]
	v_mfma_f32_16x16x32_bf16 v[32:35], v[134:137], v[216:219], v[32:35]
	v_mfma_f32_16x16x32_bf16 v[24:27], v[142:145], v[216:219], v[24:27]
	v_mfma_f32_16x16x32_bf16 v[16:19], v[134:137], v[224:227], v[16:19]
	v_mfma_f32_16x16x32_bf16 v[8:11], v[142:145], v[224:227], v[8:11]
	s_setprio 0
	s_setprio 1
	v_mfma_f32_16x16x32_bf16 v[52:55], v[146:149], v[196:199], v[52:55]
	v_mfma_f32_16x16x32_bf16 v[44:47], v[154:157], v[196:199], v[44:47]
	v_mfma_f32_16x16x32_bf16 v[36:39], v[146:149], v[204:207], v[36:39]
	v_mfma_f32_16x16x32_bf16 v[28:31], v[154:157], v[204:207], v[28:31]
	v_mfma_f32_16x16x32_bf16 v[20:23], v[146:149], v[212:215], v[20:23]
	v_mfma_f32_16x16x32_bf16 v[12:15], v[154:157], v[212:215], v[12:15]
	v_mfma_f32_16x16x32_bf16 v[4:7], v[146:149], v[220:223], v[4:7]
	v_mfma_f32_16x16x32_bf16 v[0:3], v[154:157], v[220:223], v[0:3]
	v_mfma_f32_16x16x32_bf16 v[52:55], v[150:153], v[200:203], v[52:55]
	v_mfma_f32_16x16x32_bf16 v[44:47], v[192:195], v[200:203], v[44:47]
	v_mfma_f32_16x16x32_bf16 v[36:39], v[150:153], v[208:211], v[36:39]
	v_mfma_f32_16x16x32_bf16 v[28:31], v[192:195], v[208:211], v[28:31]
	v_mfma_f32_16x16x32_bf16 v[20:23], v[150:153], v[216:219], v[20:23]
	v_mfma_f32_16x16x32_bf16 v[12:15], v[192:195], v[216:219], v[12:15]
	s_barrier
	s_setprio 2
	v_mfma_f32_16x16x32_bf16 v[4:7], v[150:153], v[224:227], v[4:7]
	v_mfma_f32_16x16x32_bf16 v[0:3], v[192:195], v[224:227], v[0:3]
	s_setprio 0
	s_add_i32 s76, s76, 2
	s_add_u32 s74, s74, 0x100
	s_addc_u32 s75, s75, 0
	s_add_u32 s28, s28, 0x100
	s_addc_u32 s29, s29, 0
	s_cmp_gt_u32 s76, 29
	s_cbranch_scc0 .LBB0_359
	s_and_b64 vcc, exec, s[14:15]
	s_cbranch_vccz .LBB0_362
	s_barrier

.LBB0_1192:
	ds_read_b128 v[128:131], v215
	ds_read_b128 v[132:135], v215 offset:1024
	ds_read_b128 v[136:139], v215 offset:2048
	ds_read_b128 v[158:161], v215 offset:3072
	ds_read_b128 v[162:165], v216
	ds_read_b128 v[166:169], v216 offset:1024
	ds_read_b128 v[170:173], v216 offset:2048
	ds_read_b128 v[174:177], v216 offset:3072
	s_add_u32 s24, s22, 0xfff80080
	s_addc_u32 s25, s23, -1
	s_cmp_eq_u32 s30, 28
	s_cselect_b32 s27, s3, s25
	s_cselect_b32 s26, s15, s24
	s_cselect_b32 s25, s13, s29
	s_cselect_b32 s24, s21, s28
	v_lshl_add_u64 v[210:211], s[22:23], 0, v[152:153]
	s_add_i32 m0, s38, 0xc000
	ds_read_b128 v[178:181], v217
	ds_read_b128 v[182:185], v217 offset:1024
	ds_read_b128 v[186:189], v217 offset:2048
	ds_read_b128 v[190:193], v217 offset:3072
	ds_read_b128 v[194:197], v217 offset:4096
	ds_read_b128 v[198:201], v217 offset:5120
	ds_read_b128 v[202:205], v217 offset:6144
	ds_read_b128 v[206:209], v217 offset:7168
	global_load_lds_dwordx4 v[210:211], off
	v_lshl_add_u64 v[210:211], s[22:23], 0, v[150:151]
	s_add_i32 m0, s38, 0xe000
	s_nop 0
	global_load_lds_dwordx4 v[210:211], off
	s_waitcnt vmcnt(8)
	s_waitcnt lgkmcnt(0)
	s_barrier
	s_setprio 1
	s_waitcnt lgkmcnt(0)
	v_mfma_f32_16x16x32_bf16 v[124:127], v[128:131], v[178:181], v[124:127]
	v_mfma_f32_16x16x32_bf16 v[120:123], v[136:139], v[178:181], v[120:123]
	v_mfma_f32_16x16x32_bf16 v[116:119], v[128:131], v[186:189], v[116:119]
	v_mfma_f32_16x16x32_bf16 v[112:115], v[136:139], v[186:189], v[112:115]
	v_mfma_f32_16x16x32_bf16 v[108:111], v[128:131], v[194:197], v[108:111]
	v_mfma_f32_16x16x32_bf16 v[104:107], v[136:139], v[194:197], v[104:107]
	v_mfma_f32_16x16x32_bf16 v[100:103], v[128:131], v[202:205], v[100:103]
	v_mfma_f32_16x16x32_bf16 v[96:99], v[136:139], v[202:205], v[96:99]
	v_mfma_f32_16x16x32_bf16 v[124:127], v[132:135], v[182:185], v[124:127]
	v_mfma_f32_16x16x32_bf16 v[120:123], v[158:161], v[182:185], v[120:123]
	v_mfma_f32_16x16x32_bf16 v[116:119], v[132:135], v[190:193], v[116:119]
	v_mfma_f32_16x16x32_bf16 v[112:115], v[158:161], v[190:193], v[112:115]
	v_mfma_f32_16x16x32_bf16 v[108:111], v[132:135], v[198:201], v[108:111]
	v_mfma_f32_16x16x32_bf16 v[104:107], v[158:161], v[198:201], v[104:107]
	v_mfma_f32_16x16x32_bf16 v[100:103], v[132:135], v[206:209], v[100:103]
	v_mfma_f32_16x16x32_bf16 v[96:99], v[158:161], v[206:209], v[96:99]
	s_setprio 0
	s_setprio 1
	v_mfma_f32_16x16x32_bf16 v[60:63], v[162:165], v[178:181], v[60:63]
	v_mfma_f32_16x16x32_bf16 v[56:59], v[170:173], v[178:181], v[56:59]
	v_mfma_f32_16x16x32_bf16 v[52:55], v[162:165], v[186:189], v[52:55]
	v_mfma_f32_16x16x32_bf16 v[48:51], v[170:173], v[186:189], v[48:51]
	v_mfma_f32_16x16x32_bf16 v[44:47], v[162:165], v[194:197], v[44:47]
	v_mfma_f32_16x16x32_bf16 v[40:43], v[170:173], v[194:197], v[40:43]
	v_mfma_f32_16x16x32_bf16 v[36:39], v[162:165], v[202:205], v[36:39]
	v_mfma_f32_16x16x32_bf16 v[32:35], v[170:173], v[202:205], v[32:35]
	v_mfma_f32_16x16x32_bf16 v[60:63], v[166:169], v[182:185], v[60:63]
	v_mfma_f32_16x16x32_bf16 v[56:59], v[174:177], v[182:185], v[56:59]
	v_mfma_f32_16x16x32_bf16 v[52:55], v[166:169], v[190:193], v[52:55]
	v_mfma_f32_16x16x32_bf16 v[48:51], v[174:177], v[190:193], v[48:51]
	v_mfma_f32_16x16x32_bf16 v[44:47], v[166:169], v[198:201], v[44:47]
	v_mfma_f32_16x16x32_bf16 v[40:43], v[174:177], v[198:201], v[40:43]
	s_barrier
	s_setprio 2
	v_mfma_f32_16x16x32_bf16 v[36:39], v[166:169], v[206:209], v[36:39]
	v_mfma_f32_16x16x32_bf16 v[32:35], v[174:177], v[206:209], v[32:35]
	s_setprio 0
	s_add_i32 s31, s60, s67
	v_lshl_add_u64 v[210:211], s[24:25], 0, v[142:143]
	s_mov_b32 m0, s31
	ds_read_b128 v[178:181], v217 offset:16384
	ds_read_b128 v[182:185], v217 offset:17408
	ds_read_b128 v[186:189], v217 offset:18432
	ds_read_b128 v[190:193], v217 offset:19456
	ds_read_b128 v[194:197], v217 offset:20480
	ds_read_b128 v[198:201], v217 offset:21504
	ds_read_b128 v[202:205], v217 offset:22528
	ds_read_b128 v[206:209], v217 offset:23552
	global_load_lds_dwordx4 v[210:211], off
	s_add_i32 m0, s31, 0x2000
	s_add_u32 s74, s24, 0x80000
	v_lshl_add_u64 v[212:213], s[24:25], 0, v[146:147]
	s_addc_u32 s75, s25, 0
	s_add_i32 s31, s61, s67
	global_load_lds_dwordx4 v[212:213], off
	v_lshl_add_u64 v[220:221], s[74:75], 0, v[142:143]
	s_mov_b32 m0, s31
	v_lshl_add_u64 v[222:223], s[26:27], 0, v[144:145]
	global_load_lds_dwordx4 v[220:221], off
	v_lshl_add_u64 v[220:221], s[74:75], 0, v[146:147]
	s_add_i32 m0, s31, 0x2000
	s_nop 0
	global_load_lds_dwordx4 v[220:221], off
	v_lshl_add_u64 v[220:221], s[26:27], 0, v[140:141]
	s_mov_b32 m0, s38
	s_nop 0
	global_load_lds_dwordx4 v[220:221], off
	s_mov_b32 m0, s39
	s_nop 0
	global_load_lds_dwordx4 v[222:223], off
	s_waitcnt vmcnt(8)
	s_waitcnt lgkmcnt(0)
	s_barrier
	s_setprio 1
	s_waitcnt lgkmcnt(0)
	v_mfma_f32_16x16x32_bf16 v[92:95], v[128:131], v[178:181], v[92:95]
	v_mfma_f32_16x16x32_bf16 v[88:91], v[136:139], v[178:181], v[88:91]
	v_mfma_f32_16x16x32_bf16 v[84:87], v[128:131], v[186:189], v[84:87]
	v_mfma_f32_16x16x32_bf16 v[80:83], v[136:139], v[186:189], v[80:83]
	v_mfma_f32_16x16x32_bf16 v[76:79], v[128:131], v[194:197], v[76:79]
	v_mfma_f32_16x16x32_bf16 v[72:75], v[136:139], v[194:197], v[72:75]
	v_mfma_f32_16x16x32_bf16 v[68:71], v[128:131], v[202:205], v[68:71]
	v_mfma_f32_16x16x32_bf16 v[64:67], v[136:139], v[202:205], v[64:67]
	v_mfma_f32_16x16x32_bf16 v[92:95], v[132:135], v[182:185], v[92:95]
	v_mfma_f32_16x16x32_bf16 v[88:91], v[158:161], v[182:185], v[88:91]
	v_mfma_f32_16x16x32_bf16 v[84:87], v[132:135], v[190:193], v[84:87]
	v_mfma_f32_16x16x32_bf16 v[80:83], v[158:161], v[190:193], v[80:83]
	v_mfma_f32_16x16x32_bf16 v[76:79], v[132:135], v[198:201], v[76:79]
	v_mfma_f32_16x16x32_bf16 v[72:75], v[158:161], v[198:201], v[72:75]
	v_mfma_f32_16x16x32_bf16 v[68:71], v[132:135], v[206:209], v[68:71]
	v_mfma_f32_16x16x32_bf16 v[64:67], v[158:161], v[206:209], v[64:67]
	s_setprio 0
	s_setprio 1
	v_mfma_f32_16x16x32_bf16 v[28:31], v[162:165], v[178:181], v[28:31]
	v_mfma_f32_16x16x32_bf16 v[24:27], v[170:173], v[178:181], v[24:27]
	v_mfma_f32_16x16x32_bf16 v[20:23], v[162:165], v[186:189], v[20:23]
	v_mfma_f32_16x16x32_bf16 v[16:19], v[170:173], v[186:189], v[16:19]
	v_mfma_f32_16x16x32_bf16 v[12:15], v[162:165], v[194:197], v[12:15]
	v_mfma_f32_16x16x32_bf16 v[8:11], v[170:173], v[194:197], v[8:11]
	v_mfma_f32_16x16x32_bf16 v[4:7], v[162:165], v[202:205], v[4:7]
	v_mfma_f32_16x16x32_bf16 v[0:3], v[170:173], v[202:205], v[0:3]
	v_mfma_f32_16x16x32_bf16 v[28:31], v[166:169], v[182:185], v[28:31]
	v_mfma_f32_16x16x32_bf16 v[24:27], v[174:177], v[182:185], v[24:27]
	v_mfma_f32_16x16x32_bf16 v[20:23], v[166:169], v[190:193], v[20:23]
	v_mfma_f32_16x16x32_bf16 v[16:19], v[174:177], v[190:193], v[16:19]
	v_mfma_f32_16x16x32_bf16 v[12:15], v[166:169], v[198:201], v[12:15]
	v_mfma_f32_16x16x32_bf16 v[8:11], v[174:177], v[198:201], v[8:11]
	s_barrier
	s_setprio 2
	v_mfma_f32_16x16x32_bf16 v[4:7], v[166:169], v[206:209], v[4:7]
	v_mfma_f32_16x16x32_bf16 v[0:3], v[174:177], v[206:209], v[0:3]
	s_setprio 0
	s_add_i32 s31, 0, 0x18000
	v_add_u32_e32 v148, s31, v214
	s_add_i32 s74, 0, 0x1c000
	ds_read_b128 v[128:131], v148
	ds_read_b128 v[132:135], v148 offset:1024
	ds_read_b128 v[136:139], v148 offset:2048
	ds_read_b128 v[158:161], v148 offset:3072
	v_add_u32_e32 v148, s74, v214
	ds_read_b128 v[162:165], v148
	ds_read_b128 v[166:169], v148 offset:1024
	ds_read_b128 v[170:173], v148 offset:2048
	ds_read_b128 v[174:177], v148 offset:3072
	s_add_u32 s26, s26, 0x80000
	s_addc_u32 s27, s27, 0
	s_mov_b32 m0, s40
	v_lshl_add_u64 v[224:225], s[26:27], 0, v[140:141]
	ds_read_b128 v[178:181], v217 offset:32768
	ds_read_b128 v[182:185], v217 offset:33792
	ds_read_b128 v[186:189], v217 offset:34816
	ds_read_b128 v[190:193], v217 offset:35840
	ds_read_b128 v[194:197], v217 offset:36864
	ds_read_b128 v[198:201], v217 offset:37888
	ds_read_b128 v[202:205], v217 offset:38912
	ds_read_b128 v[206:209], v217 offset:39936
	global_load_lds_dwordx4 v[224:225], off
	v_lshl_add_u64 v[224:225], s[26:27], 0, v[144:145]
	s_mov_b32 m0, s41
	s_nop 0
	global_load_lds_dwordx4 v[224:225], off
	s_waitcnt vmcnt(8)
	s_waitcnt lgkmcnt(0)
	s_barrier
	s_setprio 1
	s_waitcnt lgkmcnt(0)
	v_mfma_f32_16x16x32_bf16 v[124:127], v[128:131], v[178:181], v[124:127]
	v_mfma_f32_16x16x32_bf16 v[120:123], v[136:139], v[178:181], v[120:123]
	v_mfma_f32_16x16x32_bf16 v[116:119], v[128:131], v[186:189], v[116:119]
	v_mfma_f32_16x16x32_bf16 v[112:115], v[136:139], v[186:189], v[112:115]
	v_mfma_f32_16x16x32_bf16 v[108:111], v[128:131], v[194:197], v[108:111]
	v_mfma_f32_16x16x32_bf16 v[104:107], v[136:139], v[194:197], v[104:107]
	v_mfma_f32_16x16x32_bf16 v[100:103], v[128:131], v[202:205], v[100:103]
	v_mfma_f32_16x16x32_bf16 v[96:99], v[136:139], v[202:205], v[96:99]
	v_mfma_f32_16x16x32_bf16 v[124:127], v[132:135], v[182:185], v[124:127]
	v_mfma_f32_16x16x32_bf16 v[120:123], v[158:161], v[182:185], v[120:123]
	v_mfma_f32_16x16x32_bf16 v[116:119], v[132:135], v[190:193], v[116:119]
	v_mfma_f32_16x16x32_bf16 v[112:115], v[158:161], v[190:193], v[112:115]
	v_mfma_f32_16x16x32_bf16 v[108:111], v[132:135], v[198:201], v[108:111]
	v_mfma_f32_16x16x32_bf16 v[104:107], v[158:161], v[198:201], v[104:107]
	v_mfma_f32_16x16x32_bf16 v[100:103], v[132:135], v[206:209], v[100:103]
	v_mfma_f32_16x16x32_bf16 v[96:99], v[158:161], v[206:209], v[96:99]
	s_setprio 0
	s_setprio 1
	v_mfma_f32_16x16x32_bf16 v[60:63], v[162:165], v[178:181], v[60:63]
	v_mfma_f32_16x16x32_bf16 v[56:59], v[170:173], v[178:181], v[56:59]
	v_mfma_f32_16x16x32_bf16 v[52:55], v[162:165], v[186:189], v[52:55]
	v_mfma_f32_16x16x32_bf16 v[48:51], v[170:173], v[186:189], v[48:51]
	v_mfma_f32_16x16x32_bf16 v[44:47], v[162:165], v[194:197], v[44:47]
	v_mfma_f32_16x16x32_bf16 v[40:43], v[170:173], v[194:197], v[40:43]
	v_mfma_f32_16x16x32_bf16 v[36:39], v[162:165], v[202:205], v[36:39]
	v_mfma_f32_16x16x32_bf16 v[32:35], v[170:173], v[202:205], v[32:35]
	v_mfma_f32_16x16x32_bf16 v[60:63], v[166:169], v[182:185], v[60:63]
	v_mfma_f32_16x16x32_bf16 v[56:59], v[174:177], v[182:185], v[56:59]
	v_mfma_f32_16x16x32_bf16 v[52:55], v[166:169], v[190:193], v[52:55]
	v_mfma_f32_16x16x32_bf16 v[48:51], v[174:177], v[190:193], v[48:51]
	v_mfma_f32_16x16x32_bf16 v[44:47], v[166:169], v[198:201], v[44:47]
	v_mfma_f32_16x16x32_bf16 v[40:43], v[174:177], v[198:201], v[40:43]
	s_barrier
	s_setprio 2
	v_mfma_f32_16x16x32_bf16 v[36:39], v[166:169], v[206:209], v[36:39]
	v_mfma_f32_16x16x32_bf16 v[32:35], v[174:177], v[206:209], v[32:35]
	s_setprio 0
	s_add_i32 s26, s31, s67
	v_lshl_add_u64 v[210:211], v[210:211], 0, s[6:7]
	s_mov_b32 m0, s26
	ds_read_b128 v[178:181], v217 offset:49152
	ds_read_b128 v[182:185], v217 offset:50176
	ds_read_b128 v[186:189], v217 offset:51200
	ds_read_b128 v[190:193], v217 offset:52224
	ds_read_b128 v[194:197], v217 offset:53248
	ds_read_b128 v[198:201], v217 offset:54272
	ds_read_b128 v[202:205], v217 offset:55296
	ds_read_b128 v[206:209], v217 offset:56320
	global_load_lds_dwordx4 v[210:211], off
	s_add_i32 m0, s26, 0x2000
	s_add_u32 s24, s24, 0x80080
	v_lshl_add_u64 v[210:211], v[212:213], 0, s[6:7]
	s_addc_u32 s25, s25, 0
	s_add_i32 s26, s74, s67
	global_load_lds_dwordx4 v[210:211], off
	v_lshl_add_u64 v[210:211], s[24:25], 0, v[142:143]
	s_mov_b32 m0, s26
	s_nop 0
	global_load_lds_dwordx4 v[210:211], off
	v_lshl_add_u64 v[210:211], s[24:25], 0, v[146:147]
	s_add_i32 m0, s26, 0x2000
	s_nop 0
	global_load_lds_dwordx4 v[210:211], off
	v_lshl_add_u64 v[210:211], v[220:221], 0, s[6:7]
	s_mov_b32 m0, s55
	s_nop 0
	global_load_lds_dwordx4 v[210:211], off
	v_lshl_add_u64 v[210:211], v[222:223], 0, s[6:7]
	s_mov_b32 m0, s56
	s_nop 0
	global_load_lds_dwordx4 v[210:211], off
	s_waitcnt vmcnt(8)
	s_waitcnt lgkmcnt(0)
	s_barrier
	s_setprio 1
	s_waitcnt lgkmcnt(0)
	v_mfma_f32_16x16x32_bf16 v[92:95], v[128:131], v[178:181], v[92:95]
	v_mfma_f32_16x16x32_bf16 v[88:91], v[136:139], v[178:181], v[88:91]
	v_mfma_f32_16x16x32_bf16 v[84:87], v[128:131], v[186:189], v[84:87]
	v_mfma_f32_16x16x32_bf16 v[80:83], v[136:139], v[186:189], v[80:83]
	v_mfma_f32_16x16x32_bf16 v[76:79], v[128:131], v[194:197], v[76:79]
	v_mfma_f32_16x16x32_bf16 v[72:75], v[136:139], v[194:197], v[72:75]
	v_mfma_f32_16x16x32_bf16 v[68:71], v[128:131], v[202:205], v[68:71]
	v_mfma_f32_16x16x32_bf16 v[64:67], v[136:139], v[202:205], v[64:67]
	v_mfma_f32_16x16x32_bf16 v[92:95], v[132:135], v[182:185], v[92:95]
	v_mfma_f32_16x16x32_bf16 v[88:91], v[158:161], v[182:185], v[88:91]
	v_mfma_f32_16x16x32_bf16 v[84:87], v[132:135], v[190:193], v[84:87]
	v_mfma_f32_16x16x32_bf16 v[80:83], v[158:161], v[190:193], v[80:83]
	v_mfma_f32_16x16x32_bf16 v[76:79], v[132:135], v[198:201], v[76:79]
	v_mfma_f32_16x16x32_bf16 v[72:75], v[158:161], v[198:201], v[72:75]
	v_mfma_f32_16x16x32_bf16 v[68:71], v[132:135], v[206:209], v[68:71]
	v_mfma_f32_16x16x32_bf16 v[64:67], v[158:161], v[206:209], v[64:67]
	s_setprio 0
	s_setprio 1
	v_mfma_f32_16x16x32_bf16 v[28:31], v[162:165], v[178:181], v[28:31]
	v_mfma_f32_16x16x32_bf16 v[24:27], v[170:173], v[178:181], v[24:27]
	v_mfma_f32_16x16x32_bf16 v[20:23], v[162:165], v[186:189], v[20:23]
	v_mfma_f32_16x16x32_bf16 v[16:19], v[170:173], v[186:189], v[16:19]
	v_mfma_f32_16x16x32_bf16 v[12:15], v[162:165], v[194:197], v[12:15]
	v_mfma_f32_16x16x32_bf16 v[8:11], v[170:173], v[194:197], v[8:11]
	v_mfma_f32_16x16x32_bf16 v[4:7], v[162:165], v[202:205], v[4:7]
	v_mfma_f32_16x16x32_bf16 v[0:3], v[170:173], v[202:205], v[0:3]
	v_mfma_f32_16x16x32_bf16 v[28:31], v[166:169], v[182:185], v[28:31]
	v_mfma_f32_16x16x32_bf16 v[24:27], v[174:177], v[182:185], v[24:27]
	v_mfma_f32_16x16x32_bf16 v[20:23], v[166:169], v[190:193], v[20:23]
	v_mfma_f32_16x16x32_bf16 v[16:19], v[174:177], v[190:193], v[16:19]
	v_mfma_f32_16x16x32_bf16 v[12:15], v[166:169], v[198:201], v[12:15]
	v_mfma_f32_16x16x32_bf16 v[8:11], v[174:177], v[198:201], v[8:11]
	s_barrier
	s_setprio 2
	v_mfma_f32_16x16x32_bf16 v[4:7], v[166:169], v[206:209], v[4:7]
	v_mfma_f32_16x16x32_bf16 v[0:3], v[174:177], v[206:209], v[0:3]
	s_setprio 0
	s_add_i32 s30, s30, 2
	s_add_u32 s28, s28, 0x100
	s_addc_u32 s29, s29, 0
	s_add_u32 s22, s22, 0x100
	s_addc_u32 s23, s23, 0
	s_cmp_gt_u32 s30, 29
	s_cbranch_scc0 .LBB0_1192
	s_and_b64 vcc, exec, s[8:9]
	s_cbranch_vccz .LBB0_1195
	s_barrier

.LBB0_1304:
	ds_read_b128 v[124:127], v163
	ds_read_b128 v[156:159], v163 offset:1024
	ds_read_b128 v[170:173], v163 offset:2048
	ds_read_b128 v[174:177], v163 offset:3072
	ds_read_b128 v[178:181], v165
	ds_read_b128 v[182:185], v165 offset:1024
	ds_read_b128 v[186:189], v165 offset:2048
	ds_read_b128 v[190:193], v165 offset:3072
	s_add_u32 s26, s24, 0xfff80080
	s_addc_u32 s27, s25, -1
	s_cmp_eq_u32 s55, 28
	s_cselect_b32 s29, s17, s27
	s_cselect_b32 s28, s51, s26
	s_cselect_b32 s27, s15, s54
	s_cselect_b32 s26, s52, s53
	v_lshl_add_u64 v[114:115], s[24:25], 0, v[148:149]
	s_add_i32 m0, s23, 0xc000
	ds_read_b128 v[194:197], v167
	ds_read_b128 v[198:201], v167 offset:1024
	ds_read_b128 v[202:205], v167 offset:2048
	ds_read_b128 v[206:209], v167 offset:3072
	ds_read_b128 v[210:213], v167 offset:4096
	ds_read_b128 v[214:217], v167 offset:5120
	ds_read_b128 v[218:221], v167 offset:6144
	ds_read_b128 v[222:225], v167 offset:7168
	global_load_lds_dwordx4 v[114:115], off
	v_lshl_add_u64 v[114:115], s[24:25], 0, v[146:147]
	s_add_i32 m0, s23, 0xe000
	s_nop 0
	global_load_lds_dwordx4 v[114:115], off
	s_waitcnt vmcnt(8)
	s_waitcnt lgkmcnt(0)
	s_barrier
	s_setprio 1
	s_waitcnt lgkmcnt(0)
	v_mfma_f32_16x16x32_bf16 v[132:135], v[124:127], v[194:197], v[132:135]
	v_mfma_f32_16x16x32_bf16 v[120:123], v[170:173], v[194:197], v[120:123]
	v_mfma_f32_16x16x32_bf16 v[108:111], v[124:127], v[202:205], v[108:111]
	v_mfma_f32_16x16x32_bf16 v[100:103], v[170:173], v[202:205], v[100:103]
	v_mfma_f32_16x16x32_bf16 v[92:95], v[124:127], v[210:213], v[92:95]
	v_mfma_f32_16x16x32_bf16 v[84:87], v[170:173], v[210:213], v[84:87]
	v_mfma_f32_16x16x32_bf16 v[76:79], v[124:127], v[218:221], v[76:79]
	v_mfma_f32_16x16x32_bf16 v[68:71], v[170:173], v[218:221], v[68:71]
	v_mfma_f32_16x16x32_bf16 v[132:135], v[156:159], v[198:201], v[132:135]
	v_mfma_f32_16x16x32_bf16 v[120:123], v[174:177], v[198:201], v[120:123]
	v_mfma_f32_16x16x32_bf16 v[108:111], v[156:159], v[206:209], v[108:111]
	v_mfma_f32_16x16x32_bf16 v[100:103], v[174:177], v[206:209], v[100:103]
	v_mfma_f32_16x16x32_bf16 v[92:95], v[156:159], v[214:217], v[92:95]
	v_mfma_f32_16x16x32_bf16 v[84:87], v[174:177], v[214:217], v[84:87]
	v_mfma_f32_16x16x32_bf16 v[76:79], v[156:159], v[222:225], v[76:79]
	v_mfma_f32_16x16x32_bf16 v[68:71], v[174:177], v[222:225], v[68:71]
	s_setprio 0
	s_setprio 1
	v_mfma_f32_16x16x32_bf16 v[128:131], v[178:181], v[194:197], v[128:131]
	v_mfma_f32_16x16x32_bf16 v[114:117], v[186:189], v[194:197], v[116:119]
	v_mfma_f32_16x16x32_bf16 v[104:107], v[178:181], v[202:205], v[104:107]
	v_mfma_f32_16x16x32_bf16 v[96:99], v[186:189], v[202:205], v[96:99]
	v_mfma_f32_16x16x32_bf16 v[88:91], v[178:181], v[210:213], v[88:91]
	v_mfma_f32_16x16x32_bf16 v[80:83], v[186:189], v[210:213], v[80:83]
	v_mfma_f32_16x16x32_bf16 v[72:75], v[178:181], v[218:221], v[72:75]
	v_mfma_f32_16x16x32_bf16 v[64:67], v[186:189], v[218:221], v[64:67]
	v_mfma_f32_16x16x32_bf16 v[128:131], v[182:185], v[198:201], v[128:131]
	v_mfma_f32_16x16x32_bf16 v[114:117], v[190:193], v[198:201], v[114:117]
	v_mfma_f32_16x16x32_bf16 v[104:107], v[182:185], v[206:209], v[104:107]
	v_mfma_f32_16x16x32_bf16 v[96:99], v[190:193], v[206:209], v[96:99]
	v_mfma_f32_16x16x32_bf16 v[88:91], v[182:185], v[214:217], v[88:91]
	v_mfma_f32_16x16x32_bf16 v[80:83], v[190:193], v[214:217], v[80:83]
	s_barrier
	s_setprio 2
	v_mfma_f32_16x16x32_bf16 v[72:75], v[182:185], v[222:225], v[72:75]
	v_mfma_f32_16x16x32_bf16 v[64:67], v[190:193], v[222:225], v[64:67]
	s_setprio 0
	s_add_i32 s56, s47, s67
	v_lshl_add_u64 v[226:227], s[26:27], 0, v[138:139]
	s_mov_b32 m0, s56
	ds_read_b128 v[194:197], v167 offset:16384
	ds_read_b128 v[198:201], v167 offset:17408
	ds_read_b128 v[202:205], v167 offset:18432
	ds_read_b128 v[206:209], v167 offset:19456
	ds_read_b128 v[210:213], v167 offset:20480
	ds_read_b128 v[214:217], v167 offset:21504
	ds_read_b128 v[218:221], v167 offset:22528
	ds_read_b128 v[222:225], v167 offset:23552
	global_load_lds_dwordx4 v[226:227], off
	s_add_i32 m0, s56, 0x2000
	s_add_u32 s56, s26, 0x80000
	v_lshl_add_u64 v[228:229], s[26:27], 0, v[142:143]
	s_addc_u32 s57, s27, 0
	s_add_i32 s58, s48, s67
	global_load_lds_dwordx4 v[228:229], off
	v_lshl_add_u64 v[118:119], s[56:57], 0, v[138:139]
	s_mov_b32 m0, s58
	v_lshl_add_u64 v[230:231], s[28:29], 0, v[136:137]
	global_load_lds_dwordx4 v[118:119], off
	v_lshl_add_u64 v[118:119], s[56:57], 0, v[142:143]
	s_add_i32 m0, s58, 0x2000
	v_lshl_add_u64 v[232:233], s[28:29], 0, v[140:141]
	global_load_lds_dwordx4 v[118:119], off
	s_mov_b32 m0, s23
	s_nop 0
	global_load_lds_dwordx4 v[230:231], off
	s_mov_b32 m0, s37
	s_nop 0
	global_load_lds_dwordx4 v[232:233], off
	s_waitcnt vmcnt(8)
	s_waitcnt lgkmcnt(0)
	s_barrier
	s_setprio 1
	s_waitcnt lgkmcnt(0)
	v_mfma_f32_16x16x32_bf16 v[60:63], v[124:127], v[194:197], v[60:63]
	v_mfma_f32_16x16x32_bf16 v[52:55], v[170:173], v[194:197], v[52:55]
	v_mfma_f32_16x16x32_bf16 v[44:47], v[124:127], v[202:205], v[44:47]
	v_mfma_f32_16x16x32_bf16 v[36:39], v[170:173], v[202:205], v[36:39]
	v_mfma_f32_16x16x32_bf16 v[28:31], v[124:127], v[210:213], v[28:31]
	v_mfma_f32_16x16x32_bf16 v[20:23], v[170:173], v[210:213], v[20:23]
	v_mfma_f32_16x16x32_bf16 v[12:15], v[124:127], v[218:221], v[12:15]
	v_mfma_f32_16x16x32_bf16 v[4:7], v[170:173], v[218:221], v[4:7]
	v_mfma_f32_16x16x32_bf16 v[60:63], v[156:159], v[198:201], v[60:63]
	v_mfma_f32_16x16x32_bf16 v[52:55], v[174:177], v[198:201], v[52:55]
	v_mfma_f32_16x16x32_bf16 v[44:47], v[156:159], v[206:209], v[44:47]
	v_mfma_f32_16x16x32_bf16 v[36:39], v[174:177], v[206:209], v[36:39]
	v_mfma_f32_16x16x32_bf16 v[28:31], v[156:159], v[214:217], v[28:31]
	v_mfma_f32_16x16x32_bf16 v[20:23], v[174:177], v[214:217], v[20:23]
	v_mfma_f32_16x16x32_bf16 v[12:15], v[156:159], v[222:225], v[12:15]
	v_mfma_f32_16x16x32_bf16 v[4:7], v[174:177], v[222:225], v[4:7]
	s_setprio 0
	s_setprio 1
	v_mfma_f32_16x16x32_bf16 v[56:59], v[178:181], v[194:197], v[56:59]
	v_mfma_f32_16x16x32_bf16 v[48:51], v[186:189], v[194:197], v[48:51]
	v_mfma_f32_16x16x32_bf16 v[40:43], v[178:181], v[202:205], v[40:43]
	v_mfma_f32_16x16x32_bf16 v[32:35], v[186:189], v[202:205], v[32:35]
	v_mfma_f32_16x16x32_bf16 v[24:27], v[178:181], v[210:213], v[24:27]
	v_mfma_f32_16x16x32_bf16 v[16:19], v[186:189], v[210:213], v[16:19]
	v_mfma_f32_16x16x32_bf16 v[8:11], v[178:181], v[218:221], v[8:11]
	v_mfma_f32_16x16x32_bf16 v[0:3], v[186:189], v[218:221], v[0:3]
	v_mfma_f32_16x16x32_bf16 v[56:59], v[182:185], v[198:201], v[56:59]
	v_mfma_f32_16x16x32_bf16 v[48:51], v[190:193], v[198:201], v[48:51]
	v_mfma_f32_16x16x32_bf16 v[40:43], v[182:185], v[206:209], v[40:43]
	v_mfma_f32_16x16x32_bf16 v[32:35], v[190:193], v[206:209], v[32:35]
	v_mfma_f32_16x16x32_bf16 v[24:27], v[182:185], v[214:217], v[24:27]
	v_mfma_f32_16x16x32_bf16 v[16:19], v[190:193], v[214:217], v[16:19]
	s_barrier
	s_setprio 2
	v_mfma_f32_16x16x32_bf16 v[8:11], v[182:185], v[222:225], v[8:11]
	v_mfma_f32_16x16x32_bf16 v[0:3], v[190:193], v[222:225], v[0:3]
	s_setprio 0
	s_add_i32 s56, 0, 0x18000
	v_add_u32_e32 v113, s56, v155
	s_add_i32 s57, 0, 0x1c000
	ds_read_b128 v[124:127], v113
	ds_read_b128 v[156:159], v113 offset:1024
	ds_read_b128 v[170:173], v113 offset:2048
	ds_read_b128 v[174:177], v113 offset:3072
	v_add_u32_e32 v113, s57, v155
	ds_read_b128 v[178:181], v113
	ds_read_b128 v[182:185], v113 offset:1024
	ds_read_b128 v[186:189], v113 offset:2048
	ds_read_b128 v[190:193], v113 offset:3072
	s_add_u32 s28, s28, 0x80000
	s_addc_u32 s29, s29, 0
	s_mov_b32 m0, s38
	v_lshl_add_u64 v[118:119], s[28:29], 0, v[136:137]
	ds_read_b128 v[194:197], v167 offset:32768
	ds_read_b128 v[198:201], v167 offset:33792
	ds_read_b128 v[202:205], v167 offset:34816
	ds_read_b128 v[206:209], v167 offset:35840
	ds_read_b128 v[210:213], v167 offset:36864
	ds_read_b128 v[214:217], v167 offset:37888
	ds_read_b128 v[218:221], v167 offset:38912
	ds_read_b128 v[222:225], v167 offset:39936
	global_load_lds_dwordx4 v[118:119], off
	v_lshl_add_u64 v[118:119], s[28:29], 0, v[140:141]
	s_mov_b32 m0, s39
	s_nop 0
	global_load_lds_dwordx4 v[118:119], off
	s_waitcnt vmcnt(8)
	s_waitcnt lgkmcnt(0)
	s_barrier
	s_setprio 1
	s_waitcnt lgkmcnt(0)
	v_mfma_f32_16x16x32_bf16 v[132:135], v[124:127], v[194:197], v[132:135]
	v_mfma_f32_16x16x32_bf16 v[118:121], v[170:173], v[194:197], v[120:123]
	v_mfma_f32_16x16x32_bf16 v[108:111], v[124:127], v[202:205], v[108:111]
	v_mfma_f32_16x16x32_bf16 v[100:103], v[170:173], v[202:205], v[100:103]
	v_mfma_f32_16x16x32_bf16 v[92:95], v[124:127], v[210:213], v[92:95]
	v_mfma_f32_16x16x32_bf16 v[84:87], v[170:173], v[210:213], v[84:87]
	v_mfma_f32_16x16x32_bf16 v[76:79], v[124:127], v[218:221], v[76:79]
	v_mfma_f32_16x16x32_bf16 v[68:71], v[170:173], v[218:221], v[68:71]
	v_mfma_f32_16x16x32_bf16 v[132:135], v[156:159], v[198:201], v[132:135]
	v_mfma_f32_16x16x32_bf16 v[120:123], v[174:177], v[198:201], v[118:121]
	v_mfma_f32_16x16x32_bf16 v[108:111], v[156:159], v[206:209], v[108:111]
	v_mfma_f32_16x16x32_bf16 v[100:103], v[174:177], v[206:209], v[100:103]
	v_mfma_f32_16x16x32_bf16 v[92:95], v[156:159], v[214:217], v[92:95]
	v_mfma_f32_16x16x32_bf16 v[84:87], v[174:177], v[214:217], v[84:87]
	v_mfma_f32_16x16x32_bf16 v[76:79], v[156:159], v[222:225], v[76:79]
	v_mfma_f32_16x16x32_bf16 v[68:71], v[174:177], v[222:225], v[68:71]
	s_setprio 0
	s_setprio 1
	v_mfma_f32_16x16x32_bf16 v[128:131], v[178:181], v[194:197], v[128:131]
	v_mfma_f32_16x16x32_bf16 v[114:117], v[186:189], v[194:197], v[114:117]
	v_mfma_f32_16x16x32_bf16 v[104:107], v[178:181], v[202:205], v[104:107]
	v_mfma_f32_16x16x32_bf16 v[96:99], v[186:189], v[202:205], v[96:99]
	v_mfma_f32_16x16x32_bf16 v[88:91], v[178:181], v[210:213], v[88:91]
	v_mfma_f32_16x16x32_bf16 v[80:83], v[186:189], v[210:213], v[80:83]
	v_mfma_f32_16x16x32_bf16 v[72:75], v[178:181], v[218:221], v[72:75]
	v_mfma_f32_16x16x32_bf16 v[64:67], v[186:189], v[218:221], v[64:67]
	v_mfma_f32_16x16x32_bf16 v[128:131], v[182:185], v[198:201], v[128:131]
	v_mfma_f32_16x16x32_bf16 v[116:119], v[190:193], v[198:201], v[114:117]
	v_mfma_f32_16x16x32_bf16 v[104:107], v[182:185], v[206:209], v[104:107]
	v_mfma_f32_16x16x32_bf16 v[96:99], v[190:193], v[206:209], v[96:99]
	v_mfma_f32_16x16x32_bf16 v[88:91], v[182:185], v[214:217], v[88:91]
	v_mfma_f32_16x16x32_bf16 v[80:83], v[190:193], v[214:217], v[80:83]
	s_barrier
	s_setprio 2
	v_mfma_f32_16x16x32_bf16 v[72:75], v[182:185], v[222:225], v[72:75]
	v_mfma_f32_16x16x32_bf16 v[64:67], v[190:193], v[222:225], v[64:67]
	s_setprio 0
	s_add_i32 s28, s56, s67
	v_lshl_add_u64 v[114:115], v[226:227], 0, s[10:11]
	s_mov_b32 m0, s28
	ds_read_b128 v[194:197], v167 offset:49152
	ds_read_b128 v[198:201], v167 offset:50176
	ds_read_b128 v[202:205], v167 offset:51200
	ds_read_b128 v[206:209], v167 offset:52224
	ds_read_b128 v[210:213], v167 offset:53248
	ds_read_b128 v[214:217], v167 offset:54272
	ds_read_b128 v[218:221], v167 offset:55296
	ds_read_b128 v[222:225], v167 offset:56320
	global_load_lds_dwordx4 v[114:115], off
	s_add_i32 m0, s28, 0x2000
	s_add_u32 s26, s26, 0x80080
	v_lshl_add_u64 v[114:115], v[228:229], 0, s[10:11]
	s_addc_u32 s27, s27, 0
	s_add_i32 s28, s57, s67
	global_load_lds_dwordx4 v[114:115], off
	v_lshl_add_u64 v[114:115], s[26:27], 0, v[138:139]
	s_mov_b32 m0, s28
	s_nop 0
	global_load_lds_dwordx4 v[114:115], off
	v_lshl_add_u64 v[114:115], s[26:27], 0, v[142:143]
	s_add_i32 m0, s28, 0x2000
	s_nop 0
	global_load_lds_dwordx4 v[114:115], off
	v_lshl_add_u64 v[114:115], v[230:231], 0, s[10:11]
	s_mov_b32 m0, s41
	s_nop 0
	global_load_lds_dwordx4 v[114:115], off
	v_lshl_add_u64 v[114:115], v[232:233], 0, s[10:11]
	s_mov_b32 m0, s42
	s_nop 0
	global_load_lds_dwordx4 v[114:115], off
	s_waitcnt vmcnt(8)
	s_waitcnt lgkmcnt(0)
	s_barrier
	s_setprio 1
	s_waitcnt lgkmcnt(0)
	v_mfma_f32_16x16x32_bf16 v[60:63], v[124:127], v[194:197], v[60:63]
	v_mfma_f32_16x16x32_bf16 v[52:55], v[170:173], v[194:197], v[52:55]
	v_mfma_f32_16x16x32_bf16 v[44:47], v[124:127], v[202:205], v[44:47]
	v_mfma_f32_16x16x32_bf16 v[36:39], v[170:173], v[202:205], v[36:39]
	v_mfma_f32_16x16x32_bf16 v[28:31], v[124:127], v[210:213], v[28:31]
	v_mfma_f32_16x16x32_bf16 v[20:23], v[170:173], v[210:213], v[20:23]
	v_mfma_f32_16x16x32_bf16 v[12:15], v[124:127], v[218:221], v[12:15]
	v_mfma_f32_16x16x32_bf16 v[4:7], v[170:173], v[218:221], v[4:7]
	v_mfma_f32_16x16x32_bf16 v[60:63], v[156:159], v[198:201], v[60:63]
	v_mfma_f32_16x16x32_bf16 v[52:55], v[174:177], v[198:201], v[52:55]
	v_mfma_f32_16x16x32_bf16 v[44:47], v[156:159], v[206:209], v[44:47]
	v_mfma_f32_16x16x32_bf16 v[36:39], v[174:177], v[206:209], v[36:39]
	v_mfma_f32_16x16x32_bf16 v[28:31], v[156:159], v[214:217], v[28:31]
	v_mfma_f32_16x16x32_bf16 v[20:23], v[174:177], v[214:217], v[20:23]
	v_mfma_f32_16x16x32_bf16 v[12:15], v[156:159], v[222:225], v[12:15]
	v_mfma_f32_16x16x32_bf16 v[4:7], v[174:177], v[222:225], v[4:7]
	s_setprio 0
	s_setprio 1
	v_mfma_f32_16x16x32_bf16 v[56:59], v[178:181], v[194:197], v[56:59]
	v_mfma_f32_16x16x32_bf16 v[48:51], v[186:189], v[194:197], v[48:51]
	v_mfma_f32_16x16x32_bf16 v[40:43], v[178:181], v[202:205], v[40:43]
	v_mfma_f32_16x16x32_bf16 v[32:35], v[186:189], v[202:205], v[32:35]
	v_mfma_f32_16x16x32_bf16 v[24:27], v[178:181], v[210:213], v[24:27]
	v_mfma_f32_16x16x32_bf16 v[16:19], v[186:189], v[210:213], v[16:19]
	v_mfma_f32_16x16x32_bf16 v[8:11], v[178:181], v[218:221], v[8:11]
	v_mfma_f32_16x16x32_bf16 v[0:3], v[186:189], v[218:221], v[0:3]
	v_mfma_f32_16x16x32_bf16 v[56:59], v[182:185], v[198:201], v[56:59]
	v_mfma_f32_16x16x32_bf16 v[48:51], v[190:193], v[198:201], v[48:51]
	v_mfma_f32_16x16x32_bf16 v[40:43], v[182:185], v[206:209], v[40:43]
	v_mfma_f32_16x16x32_bf16 v[32:35], v[190:193], v[206:209], v[32:35]
	v_mfma_f32_16x16x32_bf16 v[24:27], v[182:185], v[214:217], v[24:27]
	v_mfma_f32_16x16x32_bf16 v[16:19], v[190:193], v[214:217], v[16:19]
	s_barrier
	s_setprio 2
	v_mfma_f32_16x16x32_bf16 v[8:11], v[182:185], v[222:225], v[8:11]
	v_mfma_f32_16x16x32_bf16 v[0:3], v[190:193], v[222:225], v[0:3]
	s_setprio 0
	s_add_i32 s55, s55, 2
	s_add_u32 s53, s53, 0x100
	s_addc_u32 s54, s54, 0
	s_add_u32 s24, s24, 0x100
	s_addc_u32 s25, s25, 0
	s_cmp_gt_u32 s55, 29
	s_cbranch_scc0 .LBB0_1304
	s_and_b64 vcc, exec, s[12:13]
	s_cbranch_vccz .LBB0_1307
	s_barrier

.LBB0_1412:
	ds_read_b128 v[128:131], v215
	ds_read_b128 v[132:135], v215 offset:1024
	ds_read_b128 v[136:139], v215 offset:2048
	ds_read_b128 v[158:161], v215 offset:3072
	ds_read_b128 v[162:165], v216
	ds_read_b128 v[166:169], v216 offset:1024
	ds_read_b128 v[170:173], v216 offset:2048
	ds_read_b128 v[174:177], v216 offset:3072
	s_add_u32 s18, s16, 0x100
	s_addc_u32 s19, s17, 0
	s_cmpk_eq_i32 s26, 0x54
	s_cselect_b32 s23, s3, s19
	s_cselect_b32 s22, s2, s18
	s_cselect_b32 s21, s15, s25
	s_cselect_b32 s20, s14, s24
	v_lshl_add_u64 v[210:211], s[16:17], 0, v[152:153]
	s_add_i32 m0, s34, 0xc000
	ds_read_b128 v[178:181], v217
	ds_read_b128 v[182:185], v217 offset:1024
	ds_read_b128 v[186:189], v217 offset:2048
	ds_read_b128 v[190:193], v217 offset:3072
	ds_read_b128 v[194:197], v217 offset:4096
	ds_read_b128 v[198:201], v217 offset:5120
	ds_read_b128 v[202:205], v217 offset:6144
	ds_read_b128 v[206:209], v217 offset:7168
	global_load_lds_dwordx4 v[210:211], off
	v_lshl_add_u64 v[210:211], s[16:17], 0, v[150:151]
	s_add_i32 m0, s34, 0xe000
	s_nop 0
	global_load_lds_dwordx4 v[210:211], off
	s_waitcnt vmcnt(8)
	s_waitcnt lgkmcnt(0)
	s_barrier
	s_setprio 1
	s_waitcnt lgkmcnt(0)
	v_mfma_f32_16x16x32_bf16 v[124:127], v[128:131], v[178:181], v[124:127]
	v_mfma_f32_16x16x32_bf16 v[120:123], v[136:139], v[178:181], v[120:123]
	v_mfma_f32_16x16x32_bf16 v[116:119], v[128:131], v[186:189], v[116:119]
	v_mfma_f32_16x16x32_bf16 v[112:115], v[136:139], v[186:189], v[112:115]
	v_mfma_f32_16x16x32_bf16 v[108:111], v[128:131], v[194:197], v[108:111]
	v_mfma_f32_16x16x32_bf16 v[104:107], v[136:139], v[194:197], v[104:107]
	v_mfma_f32_16x16x32_bf16 v[100:103], v[128:131], v[202:205], v[100:103]
	v_mfma_f32_16x16x32_bf16 v[96:99], v[136:139], v[202:205], v[96:99]
	v_mfma_f32_16x16x32_bf16 v[124:127], v[132:135], v[182:185], v[124:127]
	v_mfma_f32_16x16x32_bf16 v[120:123], v[158:161], v[182:185], v[120:123]
	v_mfma_f32_16x16x32_bf16 v[116:119], v[132:135], v[190:193], v[116:119]
	v_mfma_f32_16x16x32_bf16 v[112:115], v[158:161], v[190:193], v[112:115]
	v_mfma_f32_16x16x32_bf16 v[108:111], v[132:135], v[198:201], v[108:111]
	v_mfma_f32_16x16x32_bf16 v[104:107], v[158:161], v[198:201], v[104:107]
	v_mfma_f32_16x16x32_bf16 v[100:103], v[132:135], v[206:209], v[100:103]
	v_mfma_f32_16x16x32_bf16 v[96:99], v[158:161], v[206:209], v[96:99]
	s_setprio 0
	s_setprio 1
	v_mfma_f32_16x16x32_bf16 v[60:63], v[162:165], v[178:181], v[60:63]
	v_mfma_f32_16x16x32_bf16 v[56:59], v[170:173], v[178:181], v[56:59]
	v_mfma_f32_16x16x32_bf16 v[52:55], v[162:165], v[186:189], v[52:55]
	v_mfma_f32_16x16x32_bf16 v[48:51], v[170:173], v[186:189], v[48:51]
	v_mfma_f32_16x16x32_bf16 v[44:47], v[162:165], v[194:197], v[44:47]
	v_mfma_f32_16x16x32_bf16 v[40:43], v[170:173], v[194:197], v[40:43]
	v_mfma_f32_16x16x32_bf16 v[36:39], v[162:165], v[202:205], v[36:39]
	v_mfma_f32_16x16x32_bf16 v[32:35], v[170:173], v[202:205], v[32:35]
	v_mfma_f32_16x16x32_bf16 v[60:63], v[166:169], v[182:185], v[60:63]
	v_mfma_f32_16x16x32_bf16 v[56:59], v[174:177], v[182:185], v[56:59]
	v_mfma_f32_16x16x32_bf16 v[52:55], v[166:169], v[190:193], v[52:55]
	v_mfma_f32_16x16x32_bf16 v[48:51], v[174:177], v[190:193], v[48:51]
	v_mfma_f32_16x16x32_bf16 v[44:47], v[166:169], v[198:201], v[44:47]
	v_mfma_f32_16x16x32_bf16 v[40:43], v[174:177], v[198:201], v[40:43]
	s_barrier
	s_setprio 2
	v_mfma_f32_16x16x32_bf16 v[36:39], v[166:169], v[206:209], v[36:39]
	v_mfma_f32_16x16x32_bf16 v[32:35], v[174:177], v[206:209], v[32:35]
	s_setprio 0
	s_add_i32 s16, s56, s67
	v_lshl_add_u64 v[210:211], s[20:21], 0, v[142:143]
	s_mov_b32 m0, s16
	ds_read_b128 v[178:181], v217 offset:16384
	ds_read_b128 v[182:185], v217 offset:17408
	ds_read_b128 v[186:189], v217 offset:18432
	ds_read_b128 v[190:193], v217 offset:19456
	ds_read_b128 v[194:197], v217 offset:20480
	ds_read_b128 v[198:201], v217 offset:21504
	ds_read_b128 v[202:205], v217 offset:22528
	ds_read_b128 v[206:209], v217 offset:23552
	global_load_lds_dwordx4 v[210:211], off
	s_add_i32 m0, s16, 0x2000
	s_add_u32 s16, s20, 0x160000
	v_lshl_add_u64 v[212:213], s[20:21], 0, v[146:147]
	s_addc_u32 s17, s21, 0
	s_add_i32 s27, s57, s67
	global_load_lds_dwordx4 v[212:213], off
	v_lshl_add_u64 v[220:221], s[16:17], 0, v[142:143]
	s_mov_b32 m0, s27
	v_lshl_add_u64 v[222:223], s[22:23], 0, v[144:145]
	global_load_lds_dwordx4 v[220:221], off
	v_lshl_add_u64 v[220:221], s[16:17], 0, v[146:147]
	s_add_i32 m0, s27, 0x2000
	s_nop 0
	global_load_lds_dwordx4 v[220:221], off
	v_lshl_add_u64 v[220:221], s[22:23], 0, v[140:141]
	s_mov_b32 m0, s34
	s_nop 0
	global_load_lds_dwordx4 v[220:221], off
	s_mov_b32 m0, s35
	s_nop 0
	global_load_lds_dwordx4 v[222:223], off
	s_waitcnt vmcnt(8)
	s_waitcnt lgkmcnt(0)
	s_barrier
	s_setprio 1
	s_waitcnt lgkmcnt(0)
	v_mfma_f32_16x16x32_bf16 v[92:95], v[128:131], v[178:181], v[92:95]
	v_mfma_f32_16x16x32_bf16 v[88:91], v[136:139], v[178:181], v[88:91]
	v_mfma_f32_16x16x32_bf16 v[84:87], v[128:131], v[186:189], v[84:87]
	v_mfma_f32_16x16x32_bf16 v[80:83], v[136:139], v[186:189], v[80:83]
	v_mfma_f32_16x16x32_bf16 v[76:79], v[128:131], v[194:197], v[76:79]
	v_mfma_f32_16x16x32_bf16 v[72:75], v[136:139], v[194:197], v[72:75]
	v_mfma_f32_16x16x32_bf16 v[68:71], v[128:131], v[202:205], v[68:71]
	v_mfma_f32_16x16x32_bf16 v[64:67], v[136:139], v[202:205], v[64:67]
	v_mfma_f32_16x16x32_bf16 v[92:95], v[132:135], v[182:185], v[92:95]
	v_mfma_f32_16x16x32_bf16 v[88:91], v[158:161], v[182:185], v[88:91]
	v_mfma_f32_16x16x32_bf16 v[84:87], v[132:135], v[190:193], v[84:87]
	v_mfma_f32_16x16x32_bf16 v[80:83], v[158:161], v[190:193], v[80:83]
	v_mfma_f32_16x16x32_bf16 v[76:79], v[132:135], v[198:201], v[76:79]
	v_mfma_f32_16x16x32_bf16 v[72:75], v[158:161], v[198:201], v[72:75]
	v_mfma_f32_16x16x32_bf16 v[68:71], v[132:135], v[206:209], v[68:71]
	v_mfma_f32_16x16x32_bf16 v[64:67], v[158:161], v[206:209], v[64:67]
	s_setprio 0
	s_setprio 1
	v_mfma_f32_16x16x32_bf16 v[28:31], v[162:165], v[178:181], v[28:31]
	v_mfma_f32_16x16x32_bf16 v[24:27], v[170:173], v[178:181], v[24:27]
	v_mfma_f32_16x16x32_bf16 v[20:23], v[162:165], v[186:189], v[20:23]
	v_mfma_f32_16x16x32_bf16 v[16:19], v[170:173], v[186:189], v[16:19]
	v_mfma_f32_16x16x32_bf16 v[12:15], v[162:165], v[194:197], v[12:15]
	v_mfma_f32_16x16x32_bf16 v[8:11], v[170:173], v[194:197], v[8:11]
	v_mfma_f32_16x16x32_bf16 v[4:7], v[162:165], v[202:205], v[4:7]
	v_mfma_f32_16x16x32_bf16 v[0:3], v[170:173], v[202:205], v[0:3]
	v_mfma_f32_16x16x32_bf16 v[28:31], v[166:169], v[182:185], v[28:31]
	v_mfma_f32_16x16x32_bf16 v[24:27], v[174:177], v[182:185], v[24:27]
	v_mfma_f32_16x16x32_bf16 v[20:23], v[166:169], v[190:193], v[20:23]
	v_mfma_f32_16x16x32_bf16 v[16:19], v[174:177], v[190:193], v[16:19]
	v_mfma_f32_16x16x32_bf16 v[12:15], v[166:169], v[198:201], v[12:15]
	v_mfma_f32_16x16x32_bf16 v[8:11], v[174:177], v[198:201], v[8:11]
	s_barrier
	s_setprio 2
	v_mfma_f32_16x16x32_bf16 v[4:7], v[166:169], v[206:209], v[4:7]
	v_mfma_f32_16x16x32_bf16 v[0:3], v[174:177], v[206:209], v[0:3]
	s_setprio 0
	s_add_i32 s27, 0, 0x18000
	v_add_u32_e32 v148, s27, v214
	s_add_i32 s72, 0, 0x1c000
	ds_read_b128 v[128:131], v148
	ds_read_b128 v[132:135], v148 offset:1024
	ds_read_b128 v[136:139], v148 offset:2048
	ds_read_b128 v[158:161], v148 offset:3072
	v_add_u32_e32 v148, s72, v214
	ds_read_b128 v[162:165], v148
	ds_read_b128 v[166:169], v148 offset:1024
	ds_read_b128 v[170:173], v148 offset:2048
	ds_read_b128 v[174:177], v148 offset:3072
	s_add_u32 s16, s22, 0x160000
	s_addc_u32 s17, s23, 0
	s_mov_b32 m0, s36
	v_lshl_add_u64 v[224:225], s[16:17], 0, v[140:141]
	ds_read_b128 v[178:181], v217 offset:32768
	ds_read_b128 v[182:185], v217 offset:33792
	ds_read_b128 v[186:189], v217 offset:34816
	ds_read_b128 v[190:193], v217 offset:35840
	ds_read_b128 v[194:197], v217 offset:36864
	ds_read_b128 v[198:201], v217 offset:37888
	ds_read_b128 v[202:205], v217 offset:38912
	ds_read_b128 v[206:209], v217 offset:39936
	global_load_lds_dwordx4 v[224:225], off
	v_lshl_add_u64 v[224:225], s[16:17], 0, v[144:145]
	s_mov_b32 m0, s37
	s_nop 0
	global_load_lds_dwordx4 v[224:225], off
	s_waitcnt vmcnt(8)
	s_waitcnt lgkmcnt(0)
	s_barrier
	s_setprio 1
	s_waitcnt lgkmcnt(0)
	v_mfma_f32_16x16x32_bf16 v[124:127], v[128:131], v[178:181], v[124:127]
	v_mfma_f32_16x16x32_bf16 v[120:123], v[136:139], v[178:181], v[120:123]
	v_mfma_f32_16x16x32_bf16 v[116:119], v[128:131], v[186:189], v[116:119]
	v_mfma_f32_16x16x32_bf16 v[112:115], v[136:139], v[186:189], v[112:115]
	v_mfma_f32_16x16x32_bf16 v[108:111], v[128:131], v[194:197], v[108:111]
	v_mfma_f32_16x16x32_bf16 v[104:107], v[136:139], v[194:197], v[104:107]
	v_mfma_f32_16x16x32_bf16 v[100:103], v[128:131], v[202:205], v[100:103]
	v_mfma_f32_16x16x32_bf16 v[96:99], v[136:139], v[202:205], v[96:99]
	v_mfma_f32_16x16x32_bf16 v[124:127], v[132:135], v[182:185], v[124:127]
	v_mfma_f32_16x16x32_bf16 v[120:123], v[158:161], v[182:185], v[120:123]
	v_mfma_f32_16x16x32_bf16 v[116:119], v[132:135], v[190:193], v[116:119]
	v_mfma_f32_16x16x32_bf16 v[112:115], v[158:161], v[190:193], v[112:115]
	v_mfma_f32_16x16x32_bf16 v[108:111], v[132:135], v[198:201], v[108:111]
	v_mfma_f32_16x16x32_bf16 v[104:107], v[158:161], v[198:201], v[104:107]
	v_mfma_f32_16x16x32_bf16 v[100:103], v[132:135], v[206:209], v[100:103]
	v_mfma_f32_16x16x32_bf16 v[96:99], v[158:161], v[206:209], v[96:99]
	s_setprio 0
	s_setprio 1
	v_mfma_f32_16x16x32_bf16 v[60:63], v[162:165], v[178:181], v[60:63]
	v_mfma_f32_16x16x32_bf16 v[56:59], v[170:173], v[178:181], v[56:59]
	v_mfma_f32_16x16x32_bf16 v[52:55], v[162:165], v[186:189], v[52:55]
	v_mfma_f32_16x16x32_bf16 v[48:51], v[170:173], v[186:189], v[48:51]
	v_mfma_f32_16x16x32_bf16 v[44:47], v[162:165], v[194:197], v[44:47]
	v_mfma_f32_16x16x32_bf16 v[40:43], v[170:173], v[194:197], v[40:43]
	v_mfma_f32_16x16x32_bf16 v[36:39], v[162:165], v[202:205], v[36:39]
	v_mfma_f32_16x16x32_bf16 v[32:35], v[170:173], v[202:205], v[32:35]
	v_mfma_f32_16x16x32_bf16 v[60:63], v[166:169], v[182:185], v[60:63]
	v_mfma_f32_16x16x32_bf16 v[56:59], v[174:177], v[182:185], v[56:59]
	v_mfma_f32_16x16x32_bf16 v[52:55], v[166:169], v[190:193], v[52:55]
	v_mfma_f32_16x16x32_bf16 v[48:51], v[174:177], v[190:193], v[48:51]
	v_mfma_f32_16x16x32_bf16 v[44:47], v[166:169], v[198:201], v[44:47]
	v_mfma_f32_16x16x32_bf16 v[40:43], v[174:177], v[198:201], v[40:43]
	s_barrier
	s_setprio 2
	v_mfma_f32_16x16x32_bf16 v[36:39], v[166:169], v[206:209], v[36:39]
	v_mfma_f32_16x16x32_bf16 v[32:35], v[174:177], v[206:209], v[32:35]
	s_setprio 0
	s_add_i32 s16, s27, s67
	v_lshl_add_u64 v[210:211], v[210:211], 0, s[8:9]
	s_mov_b32 m0, s16
	ds_read_b128 v[178:181], v217 offset:49152
	ds_read_b128 v[182:185], v217 offset:50176
	ds_read_b128 v[186:189], v217 offset:51200
	ds_read_b128 v[190:193], v217 offset:52224
	ds_read_b128 v[194:197], v217 offset:53248
	ds_read_b128 v[198:201], v217 offset:54272
	ds_read_b128 v[202:205], v217 offset:55296
	ds_read_b128 v[206:209], v217 offset:56320
	global_load_lds_dwordx4 v[210:211], off
	s_add_i32 m0, s16, 0x2000
	s_add_u32 s16, s20, 0x160080
	v_lshl_add_u64 v[210:211], v[212:213], 0, s[8:9]
	s_addc_u32 s17, s21, 0
	s_add_i32 s20, s72, s67
	global_load_lds_dwordx4 v[210:211], off
	v_lshl_add_u64 v[210:211], s[16:17], 0, v[142:143]
	s_mov_b32 m0, s20
	s_nop 0
	global_load_lds_dwordx4 v[210:211], off
	v_lshl_add_u64 v[210:211], s[16:17], 0, v[146:147]
	s_add_i32 m0, s20, 0x2000
	s_nop 0
	global_load_lds_dwordx4 v[210:211], off
	v_lshl_add_u64 v[210:211], v[220:221], 0, s[8:9]
	s_mov_b32 m0, s51
	s_nop 0
	global_load_lds_dwordx4 v[210:211], off
	v_lshl_add_u64 v[210:211], v[222:223], 0, s[8:9]
	s_mov_b32 m0, s52
	s_nop 0
	global_load_lds_dwordx4 v[210:211], off
	s_waitcnt vmcnt(8)
	s_waitcnt lgkmcnt(0)
	s_barrier
	s_setprio 1
	s_waitcnt lgkmcnt(0)
	v_mfma_f32_16x16x32_bf16 v[92:95], v[128:131], v[178:181], v[92:95]
	v_mfma_f32_16x16x32_bf16 v[88:91], v[136:139], v[178:181], v[88:91]
	v_mfma_f32_16x16x32_bf16 v[84:87], v[128:131], v[186:189], v[84:87]
	v_mfma_f32_16x16x32_bf16 v[80:83], v[136:139], v[186:189], v[80:83]
	v_mfma_f32_16x16x32_bf16 v[76:79], v[128:131], v[194:197], v[76:79]
	v_mfma_f32_16x16x32_bf16 v[72:75], v[136:139], v[194:197], v[72:75]
	v_mfma_f32_16x16x32_bf16 v[68:71], v[128:131], v[202:205], v[68:71]
	v_mfma_f32_16x16x32_bf16 v[64:67], v[136:139], v[202:205], v[64:67]
	v_mfma_f32_16x16x32_bf16 v[92:95], v[132:135], v[182:185], v[92:95]
	v_mfma_f32_16x16x32_bf16 v[88:91], v[158:161], v[182:185], v[88:91]
	v_mfma_f32_16x16x32_bf16 v[84:87], v[132:135], v[190:193], v[84:87]
	v_mfma_f32_16x16x32_bf16 v[80:83], v[158:161], v[190:193], v[80:83]
	v_mfma_f32_16x16x32_bf16 v[76:79], v[132:135], v[198:201], v[76:79]
	v_mfma_f32_16x16x32_bf16 v[72:75], v[158:161], v[198:201], v[72:75]
	v_mfma_f32_16x16x32_bf16 v[68:71], v[132:135], v[206:209], v[68:71]
	v_mfma_f32_16x16x32_bf16 v[64:67], v[158:161], v[206:209], v[64:67]
	s_setprio 0
	s_setprio 1
	v_mfma_f32_16x16x32_bf16 v[28:31], v[162:165], v[178:181], v[28:31]
	v_mfma_f32_16x16x32_bf16 v[24:27], v[170:173], v[178:181], v[24:27]
	v_mfma_f32_16x16x32_bf16 v[20:23], v[162:165], v[186:189], v[20:23]
	v_mfma_f32_16x16x32_bf16 v[16:19], v[170:173], v[186:189], v[16:19]
	v_mfma_f32_16x16x32_bf16 v[12:15], v[162:165], v[194:197], v[12:15]
	v_mfma_f32_16x16x32_bf16 v[8:11], v[170:173], v[194:197], v[8:11]
	v_mfma_f32_16x16x32_bf16 v[4:7], v[162:165], v[202:205], v[4:7]
	v_mfma_f32_16x16x32_bf16 v[0:3], v[170:173], v[202:205], v[0:3]
	v_mfma_f32_16x16x32_bf16 v[28:31], v[166:169], v[182:185], v[28:31]
	v_mfma_f32_16x16x32_bf16 v[24:27], v[174:177], v[182:185], v[24:27]
	v_mfma_f32_16x16x32_bf16 v[20:23], v[166:169], v[190:193], v[20:23]
	v_mfma_f32_16x16x32_bf16 v[16:19], v[174:177], v[190:193], v[16:19]
	v_mfma_f32_16x16x32_bf16 v[12:15], v[166:169], v[198:201], v[12:15]
	v_mfma_f32_16x16x32_bf16 v[8:11], v[174:177], v[198:201], v[8:11]
	s_barrier
	s_setprio 2
	v_mfma_f32_16x16x32_bf16 v[4:7], v[166:169], v[206:209], v[4:7]
	v_mfma_f32_16x16x32_bf16 v[0:3], v[174:177], v[206:209], v[0:3]
	s_setprio 0
	s_add_i32 s26, s26, 2
	s_add_u32 s24, s24, 0x100
	s_addc_u32 s25, s25, 0
	s_cmpk_gt_u32 s26, 0x55
	s_mov_b64 s[16:17], s[18:19]
	s_cbranch_scc0 .LBB0_1412
	s_and_b64 vcc, exec, s[10:11]
	s_cbranch_vccz .LBB0_1415
	s_barrier

.LBB0_1502:
	ds_read_b128 v[130:133], v177
	ds_read_b128 v[134:137], v177 offset:1024
	ds_read_b128 v[138:141], v177 offset:2048
	ds_read_b128 v[142:145], v177 offset:3072
	ds_read_b128 v[146:149], v179
	ds_read_b128 v[184:187], v179 offset:1024
	ds_read_b128 v[188:191], v179 offset:2048
	ds_read_b128 v[192:195], v179 offset:3072
	s_add_u32 s30, s28, 0xfff80080
	s_addc_u32 s31, s29, -1
	s_cmp_eq_u32 s60, 28
	s_cselect_b32 s35, s6, s31
	s_cselect_b32 s34, s21, s30
	s_cselect_b32 s31, s19, s59
	s_cselect_b32 s30, s27, s58
	v_lshl_add_u64 v[150:151], s[28:29], 0, v[166:167]
	s_add_i32 m0, s41, 0xc000
	ds_read_b128 v[196:199], v181
	ds_read_b128 v[200:203], v181 offset:1024
	ds_read_b128 v[204:207], v181 offset:2048
	ds_read_b128 v[208:211], v181 offset:3072
	ds_read_b128 v[212:215], v181 offset:4096
	ds_read_b128 v[216:219], v181 offset:5120
	ds_read_b128 v[220:223], v181 offset:6144
	ds_read_b128 v[224:227], v181 offset:7168
	global_load_lds_dwordx4 v[150:151], off
	v_lshl_add_u64 v[150:151], s[28:29], 0, v[164:165]
	s_add_i32 m0, s41, 0xe000
	s_nop 0
	global_load_lds_dwordx4 v[150:151], off
	s_waitcnt vmcnt(8)
	s_waitcnt lgkmcnt(0)
	s_barrier
	s_setprio 1
	s_waitcnt lgkmcnt(0)
	v_mfma_f32_16x16x32_bf16 v[124:127], v[130:133], v[196:199], v[124:127]
	v_mfma_f32_16x16x32_bf16 v[120:123], v[138:141], v[196:199], v[120:123]
	v_mfma_f32_16x16x32_bf16 v[108:111], v[130:133], v[204:207], v[108:111]
	v_mfma_f32_16x16x32_bf16 v[100:103], v[138:141], v[204:207], v[100:103]
	v_mfma_f32_16x16x32_bf16 v[92:95], v[130:133], v[212:215], v[92:95]
	v_mfma_f32_16x16x32_bf16 v[84:87], v[138:141], v[212:215], v[84:87]
	v_mfma_f32_16x16x32_bf16 v[76:79], v[130:133], v[220:223], v[76:79]
	v_mfma_f32_16x16x32_bf16 v[68:71], v[138:141], v[220:223], v[68:71]
	v_mfma_f32_16x16x32_bf16 v[124:127], v[134:137], v[200:203], v[124:127]
	v_mfma_f32_16x16x32_bf16 v[120:123], v[142:145], v[200:203], v[120:123]
	v_mfma_f32_16x16x32_bf16 v[108:111], v[134:137], v[208:211], v[108:111]
	v_mfma_f32_16x16x32_bf16 v[100:103], v[142:145], v[208:211], v[100:103]
	v_mfma_f32_16x16x32_bf16 v[92:95], v[134:137], v[216:219], v[92:95]
	v_mfma_f32_16x16x32_bf16 v[84:87], v[142:145], v[216:219], v[84:87]
	v_mfma_f32_16x16x32_bf16 v[76:79], v[134:137], v[224:227], v[76:79]
	v_mfma_f32_16x16x32_bf16 v[68:71], v[142:145], v[224:227], v[68:71]
	s_setprio 0
	s_setprio 1
	v_mfma_f32_16x16x32_bf16 v[116:119], v[146:149], v[196:199], v[116:119]
	v_mfma_f32_16x16x32_bf16 v[112:115], v[188:191], v[196:199], v[112:115]
	v_mfma_f32_16x16x32_bf16 v[104:107], v[146:149], v[204:207], v[104:107]
	v_mfma_f32_16x16x32_bf16 v[96:99], v[188:191], v[204:207], v[96:99]
	v_mfma_f32_16x16x32_bf16 v[88:91], v[146:149], v[212:215], v[88:91]
	v_mfma_f32_16x16x32_bf16 v[80:83], v[188:191], v[212:215], v[80:83]
	v_mfma_f32_16x16x32_bf16 v[72:75], v[146:149], v[220:223], v[72:75]
	v_mfma_f32_16x16x32_bf16 v[64:67], v[188:191], v[220:223], v[64:67]
	v_mfma_f32_16x16x32_bf16 v[116:119], v[184:187], v[200:203], v[116:119]
	v_mfma_f32_16x16x32_bf16 v[112:115], v[192:195], v[200:203], v[112:115]
	v_mfma_f32_16x16x32_bf16 v[104:107], v[184:187], v[208:211], v[104:107]
	v_mfma_f32_16x16x32_bf16 v[96:99], v[192:195], v[208:211], v[96:99]
	v_mfma_f32_16x16x32_bf16 v[88:91], v[184:187], v[216:219], v[88:91]
	v_mfma_f32_16x16x32_bf16 v[80:83], v[192:195], v[216:219], v[80:83]
	s_barrier
	s_setprio 2
	v_mfma_f32_16x16x32_bf16 v[72:75], v[184:187], v[224:227], v[72:75]
	v_mfma_f32_16x16x32_bf16 v[64:67], v[192:195], v[224:227], v[64:67]
	s_setprio 0
	s_add_i32 s61, s53, s67
	v_lshl_add_u64 v[150:151], s[30:31], 0, v[154:155]
	s_mov_b32 m0, s61
	ds_read_b128 v[196:199], v181 offset:16384
	ds_read_b128 v[200:203], v181 offset:17408
	ds_read_b128 v[204:207], v181 offset:18432
	ds_read_b128 v[208:211], v181 offset:19456
	ds_read_b128 v[212:215], v181 offset:20480
	ds_read_b128 v[216:219], v181 offset:21504
	ds_read_b128 v[220:223], v181 offset:22528
	ds_read_b128 v[224:227], v181 offset:23552
	global_load_lds_dwordx4 v[150:151], off
	s_add_i32 m0, s61, 0x2000
	s_add_u32 s62, s30, 0x80000
	v_lshl_add_u64 v[228:229], s[30:31], 0, v[158:159]
	s_addc_u32 s63, s31, 0
	s_add_i32 s61, s54, s67
	global_load_lds_dwordx4 v[228:229], off
	v_lshl_add_u64 v[230:231], s[62:63], 0, v[154:155]
	s_mov_b32 m0, s61
	v_lshl_add_u64 v[232:233], s[34:35], 0, v[156:157]
	global_load_lds_dwordx4 v[230:231], off
	v_lshl_add_u64 v[230:231], s[62:63], 0, v[158:159]
	s_add_i32 m0, s61, 0x2000
	s_nop 0
	global_load_lds_dwordx4 v[230:231], off
	v_lshl_add_u64 v[230:231], s[34:35], 0, v[152:153]
	s_mov_b32 m0, s41
	s_nop 0
	global_load_lds_dwordx4 v[230:231], off
	s_mov_b32 m0, s42
	s_nop 0
	global_load_lds_dwordx4 v[232:233], off
	s_waitcnt vmcnt(8)
	s_waitcnt lgkmcnt(0)
	s_barrier
	s_setprio 1
	s_waitcnt lgkmcnt(0)
	v_mfma_f32_16x16x32_bf16 v[60:63], v[130:133], v[196:199], v[60:63]
	v_mfma_f32_16x16x32_bf16 v[52:55], v[138:141], v[196:199], v[52:55]
	v_mfma_f32_16x16x32_bf16 v[44:47], v[130:133], v[204:207], v[44:47]
	v_mfma_f32_16x16x32_bf16 v[36:39], v[138:141], v[204:207], v[36:39]
	v_mfma_f32_16x16x32_bf16 v[28:31], v[130:133], v[212:215], v[28:31]
	v_mfma_f32_16x16x32_bf16 v[20:23], v[138:141], v[212:215], v[20:23]
	v_mfma_f32_16x16x32_bf16 v[12:15], v[130:133], v[220:223], v[12:15]
	v_mfma_f32_16x16x32_bf16 v[4:7], v[138:141], v[220:223], v[4:7]
	v_mfma_f32_16x16x32_bf16 v[60:63], v[134:137], v[200:203], v[60:63]
	v_mfma_f32_16x16x32_bf16 v[52:55], v[142:145], v[200:203], v[52:55]
	v_mfma_f32_16x16x32_bf16 v[44:47], v[134:137], v[208:211], v[44:47]
	v_mfma_f32_16x16x32_bf16 v[36:39], v[142:145], v[208:211], v[36:39]
	v_mfma_f32_16x16x32_bf16 v[28:31], v[134:137], v[216:219], v[28:31]
	v_mfma_f32_16x16x32_bf16 v[20:23], v[142:145], v[216:219], v[20:23]
	v_mfma_f32_16x16x32_bf16 v[12:15], v[134:137], v[224:227], v[12:15]
	v_mfma_f32_16x16x32_bf16 v[4:7], v[142:145], v[224:227], v[4:7]
	s_setprio 0
	s_setprio 1
	v_mfma_f32_16x16x32_bf16 v[56:59], v[146:149], v[196:199], v[56:59]
	v_mfma_f32_16x16x32_bf16 v[48:51], v[188:191], v[196:199], v[48:51]
	v_mfma_f32_16x16x32_bf16 v[40:43], v[146:149], v[204:207], v[40:43]
	v_mfma_f32_16x16x32_bf16 v[32:35], v[188:191], v[204:207], v[32:35]
	v_mfma_f32_16x16x32_bf16 v[24:27], v[146:149], v[212:215], v[24:27]
	v_mfma_f32_16x16x32_bf16 v[16:19], v[188:191], v[212:215], v[16:19]
	v_mfma_f32_16x16x32_bf16 v[8:11], v[146:149], v[220:223], v[8:11]
	v_mfma_f32_16x16x32_bf16 v[0:3], v[188:191], v[220:223], v[0:3]
	v_mfma_f32_16x16x32_bf16 v[56:59], v[184:187], v[200:203], v[56:59]
	v_mfma_f32_16x16x32_bf16 v[48:51], v[192:195], v[200:203], v[48:51]
	v_mfma_f32_16x16x32_bf16 v[40:43], v[184:187], v[208:211], v[40:43]
	v_mfma_f32_16x16x32_bf16 v[32:35], v[192:195], v[208:211], v[32:35]
	v_mfma_f32_16x16x32_bf16 v[24:27], v[184:187], v[216:219], v[24:27]
	v_mfma_f32_16x16x32_bf16 v[16:19], v[192:195], v[216:219], v[16:19]
	s_barrier
	s_setprio 2
	v_mfma_f32_16x16x32_bf16 v[8:11], v[184:187], v[224:227], v[8:11]
	v_mfma_f32_16x16x32_bf16 v[0:3], v[192:195], v[224:227], v[0:3]
	s_setprio 0
	s_add_i32 s61, 0, 0x18000
	v_add_u32_e32 v129, s61, v173
	s_add_i32 s62, 0, 0x1c000
	ds_read_b128 v[130:133], v129
	ds_read_b128 v[134:137], v129 offset:1024
	ds_read_b128 v[138:141], v129 offset:2048
	ds_read_b128 v[142:145], v129 offset:3072
	v_add_u32_e32 v129, s62, v173
	ds_read_b128 v[146:149], v129
	ds_read_b128 v[184:187], v129 offset:1024
	ds_read_b128 v[188:191], v129 offset:2048
	ds_read_b128 v[192:195], v129 offset:3072
	s_add_u32 s34, s34, 0x80000
	s_addc_u32 s35, s35, 0
	s_mov_b32 m0, s43
	v_lshl_add_u64 v[234:235], s[34:35], 0, v[152:153]
	ds_read_b128 v[196:199], v181 offset:32768
	ds_read_b128 v[200:203], v181 offset:33792
	ds_read_b128 v[204:207], v181 offset:34816
	ds_read_b128 v[208:211], v181 offset:35840
	ds_read_b128 v[212:215], v181 offset:36864
	ds_read_b128 v[216:219], v181 offset:37888
	ds_read_b128 v[220:223], v181 offset:38912
	ds_read_b128 v[224:227], v181 offset:39936
	global_load_lds_dwordx4 v[234:235], off
	v_lshl_add_u64 v[234:235], s[34:35], 0, v[156:157]
	s_mov_b32 m0, s44
	s_nop 0
	global_load_lds_dwordx4 v[234:235], off
	s_waitcnt vmcnt(8)
	s_waitcnt lgkmcnt(0)
	s_barrier
	s_setprio 1
	s_waitcnt lgkmcnt(0)
	v_mfma_f32_16x16x32_bf16 v[124:127], v[130:133], v[196:199], v[124:127]
	v_mfma_f32_16x16x32_bf16 v[120:123], v[138:141], v[196:199], v[120:123]
	v_mfma_f32_16x16x32_bf16 v[108:111], v[130:133], v[204:207], v[108:111]
	v_mfma_f32_16x16x32_bf16 v[100:103], v[138:141], v[204:207], v[100:103]
	v_mfma_f32_16x16x32_bf16 v[92:95], v[130:133], v[212:215], v[92:95]
	v_mfma_f32_16x16x32_bf16 v[84:87], v[138:141], v[212:215], v[84:87]
	v_mfma_f32_16x16x32_bf16 v[76:79], v[130:133], v[220:223], v[76:79]
	v_mfma_f32_16x16x32_bf16 v[68:71], v[138:141], v[220:223], v[68:71]
	v_mfma_f32_16x16x32_bf16 v[124:127], v[134:137], v[200:203], v[124:127]
	v_mfma_f32_16x16x32_bf16 v[120:123], v[142:145], v[200:203], v[120:123]
	v_mfma_f32_16x16x32_bf16 v[108:111], v[134:137], v[208:211], v[108:111]
	v_mfma_f32_16x16x32_bf16 v[100:103], v[142:145], v[208:211], v[100:103]
	v_mfma_f32_16x16x32_bf16 v[92:95], v[134:137], v[216:219], v[92:95]
	v_mfma_f32_16x16x32_bf16 v[84:87], v[142:145], v[216:219], v[84:87]
	v_mfma_f32_16x16x32_bf16 v[76:79], v[134:137], v[224:227], v[76:79]
	v_mfma_f32_16x16x32_bf16 v[68:71], v[142:145], v[224:227], v[68:71]
	s_setprio 0
	s_setprio 1
	v_mfma_f32_16x16x32_bf16 v[116:119], v[146:149], v[196:199], v[116:119]
	v_mfma_f32_16x16x32_bf16 v[112:115], v[188:191], v[196:199], v[112:115]
	v_mfma_f32_16x16x32_bf16 v[104:107], v[146:149], v[204:207], v[104:107]
	v_mfma_f32_16x16x32_bf16 v[96:99], v[188:191], v[204:207], v[96:99]
	v_mfma_f32_16x16x32_bf16 v[88:91], v[146:149], v[212:215], v[88:91]
	v_mfma_f32_16x16x32_bf16 v[80:83], v[188:191], v[212:215], v[80:83]
	v_mfma_f32_16x16x32_bf16 v[72:75], v[146:149], v[220:223], v[72:75]
	v_mfma_f32_16x16x32_bf16 v[64:67], v[188:191], v[220:223], v[64:67]
	v_mfma_f32_16x16x32_bf16 v[116:119], v[184:187], v[200:203], v[116:119]
	v_mfma_f32_16x16x32_bf16 v[112:115], v[192:195], v[200:203], v[112:115]
	v_mfma_f32_16x16x32_bf16 v[104:107], v[184:187], v[208:211], v[104:107]
	v_mfma_f32_16x16x32_bf16 v[96:99], v[192:195], v[208:211], v[96:99]
	v_mfma_f32_16x16x32_bf16 v[88:91], v[184:187], v[216:219], v[88:91]
	v_mfma_f32_16x16x32_bf16 v[80:83], v[192:195], v[216:219], v[80:83]
	s_barrier
	s_setprio 2
	v_mfma_f32_16x16x32_bf16 v[72:75], v[184:187], v[224:227], v[72:75]
	v_mfma_f32_16x16x32_bf16 v[64:67], v[192:195], v[224:227], v[64:67]
	s_setprio 0
	s_add_i32 s34, s61, s67
	v_lshl_add_u64 v[150:151], v[150:151], 0, s[12:13]
	s_mov_b32 m0, s34
	ds_read_b128 v[196:199], v181 offset:49152
	ds_read_b128 v[200:203], v181 offset:50176
	ds_read_b128 v[204:207], v181 offset:51200
	ds_read_b128 v[208:211], v181 offset:52224
	ds_read_b128 v[212:215], v181 offset:53248
	ds_read_b128 v[216:219], v181 offset:54272
	ds_read_b128 v[220:223], v181 offset:55296
	ds_read_b128 v[224:227], v181 offset:56320
	global_load_lds_dwordx4 v[150:151], off
	s_add_i32 m0, s34, 0x2000
	s_add_u32 s30, s30, 0x80080
	v_lshl_add_u64 v[150:151], v[228:229], 0, s[12:13]
	s_addc_u32 s31, s31, 0
	s_add_i32 s34, s62, s67
	global_load_lds_dwordx4 v[150:151], off
	v_lshl_add_u64 v[150:151], s[30:31], 0, v[154:155]
	s_mov_b32 m0, s34
	s_nop 0
	global_load_lds_dwordx4 v[150:151], off
	v_lshl_add_u64 v[150:151], s[30:31], 0, v[158:159]
	s_add_i32 m0, s34, 0x2000
	s_nop 0
	global_load_lds_dwordx4 v[150:151], off
	v_lshl_add_u64 v[150:151], v[230:231], 0, s[12:13]
	s_mov_b32 m0, s47
	s_nop 0
	global_load_lds_dwordx4 v[150:151], off
	v_lshl_add_u64 v[150:151], v[232:233], 0, s[12:13]
	s_mov_b32 m0, s48
	s_nop 0
	global_load_lds_dwordx4 v[150:151], off
	s_waitcnt vmcnt(8)
	s_waitcnt lgkmcnt(0)
	s_barrier
	s_setprio 1
	s_waitcnt lgkmcnt(0)
	v_mfma_f32_16x16x32_bf16 v[60:63], v[130:133], v[196:199], v[60:63]
	v_mfma_f32_16x16x32_bf16 v[52:55], v[138:141], v[196:199], v[52:55]
	v_mfma_f32_16x16x32_bf16 v[44:47], v[130:133], v[204:207], v[44:47]
	v_mfma_f32_16x16x32_bf16 v[36:39], v[138:141], v[204:207], v[36:39]
	v_mfma_f32_16x16x32_bf16 v[28:31], v[130:133], v[212:215], v[28:31]
	v_mfma_f32_16x16x32_bf16 v[20:23], v[138:141], v[212:215], v[20:23]
	v_mfma_f32_16x16x32_bf16 v[12:15], v[130:133], v[220:223], v[12:15]
	v_mfma_f32_16x16x32_bf16 v[4:7], v[138:141], v[220:223], v[4:7]
	v_mfma_f32_16x16x32_bf16 v[60:63], v[134:137], v[200:203], v[60:63]
	v_mfma_f32_16x16x32_bf16 v[52:55], v[142:145], v[200:203], v[52:55]
	v_mfma_f32_16x16x32_bf16 v[44:47], v[134:137], v[208:211], v[44:47]
	v_mfma_f32_16x16x32_bf16 v[36:39], v[142:145], v[208:211], v[36:39]
	v_mfma_f32_16x16x32_bf16 v[28:31], v[134:137], v[216:219], v[28:31]
	v_mfma_f32_16x16x32_bf16 v[20:23], v[142:145], v[216:219], v[20:23]
	v_mfma_f32_16x16x32_bf16 v[12:15], v[134:137], v[224:227], v[12:15]
	v_mfma_f32_16x16x32_bf16 v[4:7], v[142:145], v[224:227], v[4:7]
	s_setprio 0
	s_setprio 1
	v_mfma_f32_16x16x32_bf16 v[56:59], v[146:149], v[196:199], v[56:59]
	v_mfma_f32_16x16x32_bf16 v[48:51], v[188:191], v[196:199], v[48:51]
	v_mfma_f32_16x16x32_bf16 v[40:43], v[146:149], v[204:207], v[40:43]
	v_mfma_f32_16x16x32_bf16 v[32:35], v[188:191], v[204:207], v[32:35]
	v_mfma_f32_16x16x32_bf16 v[24:27], v[146:149], v[212:215], v[24:27]
	v_mfma_f32_16x16x32_bf16 v[16:19], v[188:191], v[212:215], v[16:19]
	v_mfma_f32_16x16x32_bf16 v[8:11], v[146:149], v[220:223], v[8:11]
	v_mfma_f32_16x16x32_bf16 v[0:3], v[188:191], v[220:223], v[0:3]
	v_mfma_f32_16x16x32_bf16 v[56:59], v[184:187], v[200:203], v[56:59]
	v_mfma_f32_16x16x32_bf16 v[48:51], v[192:195], v[200:203], v[48:51]
	v_mfma_f32_16x16x32_bf16 v[40:43], v[184:187], v[208:211], v[40:43]
	v_mfma_f32_16x16x32_bf16 v[32:35], v[192:195], v[208:211], v[32:35]
	v_mfma_f32_16x16x32_bf16 v[24:27], v[184:187], v[216:219], v[24:27]
	v_mfma_f32_16x16x32_bf16 v[16:19], v[192:195], v[216:219], v[16:19]
	s_barrier
	s_setprio 2
	v_mfma_f32_16x16x32_bf16 v[8:11], v[184:187], v[224:227], v[8:11]
	v_mfma_f32_16x16x32_bf16 v[0:3], v[192:195], v[224:227], v[0:3]
	s_setprio 0
	s_add_i32 s60, s60, 2
	s_add_u32 s58, s58, 0x100
	s_addc_u32 s59, s59, 0
	s_add_u32 s28, s28, 0x100
	s_addc_u32 s29, s29, 0
	s_cmp_gt_u32 s60, 29
	s_cbranch_scc0 .LBB0_1502
	s_and_b64 vcc, exec, s[14:15]
	s_cbranch_vccz .LBB0_1505
	s_barrier

.LBB0_1661:
	ds_read_b128 v[128:131], v243
	ds_read_b128 v[132:135], v243 offset:1024
	ds_read_b128 v[136:139], v243 offset:2048
	ds_read_b128 v[140:143], v243 offset:3072
	ds_read_b128 v[144:147], v244
	ds_read_b128 v[148:151], v244 offset:1024
	ds_read_b128 v[152:155], v244 offset:2048
	ds_read_b128 v[156:159], v244 offset:3072
	s_add_u32 s26, s24, 0xfff80080
	s_addc_u32 s27, s25, -1
	s_cmp_eq_u32 s75, 28
	s_cselect_b32 s29, s3, s27
	s_cselect_b32 s28, s5, s26
	s_cselect_b32 s27, s17, s31
	s_cselect_b32 s26, s19, s30
	v_lshl_add_u64 v[210:211], s[24:25], 0, v[180:181]
	s_add_i32 m0, s38, 0xc000
	ds_read_b128 v[160:163], v245
	ds_read_b128 v[164:167], v245 offset:1024
	ds_read_b128 v[186:189], v245 offset:2048
	ds_read_b128 v[190:193], v245 offset:3072
	ds_read_b128 v[194:197], v245 offset:4096
	ds_read_b128 v[198:201], v245 offset:5120
	ds_read_b128 v[202:205], v245 offset:6144
	ds_read_b128 v[206:209], v245 offset:7168
	global_load_lds_dwordx4 v[210:211], off
	v_lshl_add_u64 v[210:211], s[24:25], 0, v[178:179]
	s_add_i32 m0, s38, 0xe000
	s_nop 0
	global_load_lds_dwordx4 v[210:211], off
	s_waitcnt vmcnt(8)
	s_waitcnt lgkmcnt(0)
	s_barrier
	s_setprio 1
	s_waitcnt lgkmcnt(0)
	v_mfma_f32_16x16x32_bf16 v[124:127], v[128:131], v[160:163], v[124:127]
	v_mfma_f32_16x16x32_bf16 v[120:123], v[136:139], v[160:163], v[120:123]
	v_mfma_f32_16x16x32_bf16 v[116:119], v[128:131], v[186:189], v[116:119]
	v_mfma_f32_16x16x32_bf16 v[112:115], v[136:139], v[186:189], v[112:115]
	v_mfma_f32_16x16x32_bf16 v[108:111], v[128:131], v[194:197], v[108:111]
	v_mfma_f32_16x16x32_bf16 v[104:107], v[136:139], v[194:197], v[104:107]
	v_mfma_f32_16x16x32_bf16 v[100:103], v[128:131], v[202:205], v[100:103]
	v_mfma_f32_16x16x32_bf16 v[96:99], v[136:139], v[202:205], v[96:99]
	v_mfma_f32_16x16x32_bf16 v[124:127], v[132:135], v[164:167], v[124:127]
	v_mfma_f32_16x16x32_bf16 v[120:123], v[140:143], v[164:167], v[120:123]
	v_mfma_f32_16x16x32_bf16 v[116:119], v[132:135], v[190:193], v[116:119]
	v_mfma_f32_16x16x32_bf16 v[112:115], v[140:143], v[190:193], v[112:115]
	v_mfma_f32_16x16x32_bf16 v[108:111], v[132:135], v[198:201], v[108:111]
	v_mfma_f32_16x16x32_bf16 v[104:107], v[140:143], v[198:201], v[104:107]
	v_mfma_f32_16x16x32_bf16 v[100:103], v[132:135], v[206:209], v[100:103]
	v_mfma_f32_16x16x32_bf16 v[96:99], v[140:143], v[206:209], v[96:99]
	s_setprio 0
	s_setprio 1
	v_mfma_f32_16x16x32_bf16 v[60:63], v[144:147], v[160:163], v[60:63]
	v_mfma_f32_16x16x32_bf16 v[56:59], v[152:155], v[160:163], v[56:59]
	v_mfma_f32_16x16x32_bf16 v[52:55], v[144:147], v[186:189], v[52:55]
	v_mfma_f32_16x16x32_bf16 v[48:51], v[152:155], v[186:189], v[48:51]
	v_mfma_f32_16x16x32_bf16 v[44:47], v[144:147], v[194:197], v[44:47]
	v_mfma_f32_16x16x32_bf16 v[40:43], v[152:155], v[194:197], v[40:43]
	v_mfma_f32_16x16x32_bf16 v[36:39], v[144:147], v[202:205], v[36:39]
	v_mfma_f32_16x16x32_bf16 v[32:35], v[152:155], v[202:205], v[32:35]
	v_mfma_f32_16x16x32_bf16 v[60:63], v[148:151], v[164:167], v[60:63]
	v_mfma_f32_16x16x32_bf16 v[56:59], v[156:159], v[164:167], v[56:59]
	v_mfma_f32_16x16x32_bf16 v[52:55], v[148:151], v[190:193], v[52:55]
	v_mfma_f32_16x16x32_bf16 v[48:51], v[156:159], v[190:193], v[48:51]
	v_mfma_f32_16x16x32_bf16 v[44:47], v[148:151], v[198:201], v[44:47]
	v_mfma_f32_16x16x32_bf16 v[40:43], v[156:159], v[198:201], v[40:43]
	s_barrier
	s_setprio 2
	v_mfma_f32_16x16x32_bf16 v[36:39], v[148:151], v[206:209], v[36:39]
	v_mfma_f32_16x16x32_bf16 v[32:35], v[156:159], v[206:209], v[32:35]
	s_setprio 0
	s_add_i32 s76, s62, s67
	v_lshl_add_u64 v[210:211], s[26:27], 0, v[170:171]
	s_mov_b32 m0, s76
	ds_read_b128 v[160:163], v245 offset:16384
	ds_read_b128 v[164:167], v245 offset:17408
	ds_read_b128 v[186:189], v245 offset:18432
	ds_read_b128 v[190:193], v245 offset:19456
	ds_read_b128 v[194:197], v245 offset:20480
	ds_read_b128 v[198:201], v245 offset:21504
	ds_read_b128 v[202:205], v245 offset:22528
	ds_read_b128 v[206:209], v245 offset:23552
	global_load_lds_dwordx4 v[210:211], off
	s_add_i32 m0, s76, 0x2000
	s_add_u32 s76, s26, 0x80000
	v_lshl_add_u64 v[212:213], s[26:27], 0, v[174:175]
	s_addc_u32 s77, s27, 0
	s_add_i32 s78, s63, s67
	global_load_lds_dwordx4 v[212:213], off
	v_lshl_add_u64 v[214:215], s[76:77], 0, v[170:171]
	s_mov_b32 m0, s78
	v_lshl_add_u64 v[216:217], s[28:29], 0, v[172:173]
	global_load_lds_dwordx4 v[214:215], off
	v_lshl_add_u64 v[214:215], s[76:77], 0, v[174:175]
	s_add_i32 m0, s78, 0x2000
	s_nop 0
	global_load_lds_dwordx4 v[214:215], off
	v_lshl_add_u64 v[214:215], s[28:29], 0, v[168:169]
	s_mov_b32 m0, s38
	s_nop 0
	global_load_lds_dwordx4 v[214:215], off
	s_mov_b32 m0, s39
	s_nop 0
	global_load_lds_dwordx4 v[216:217], off
	s_waitcnt vmcnt(8)
	s_waitcnt lgkmcnt(0)
	s_barrier
	s_setprio 1
	s_waitcnt lgkmcnt(0)
	v_mfma_f32_16x16x32_bf16 v[92:95], v[128:131], v[160:163], v[92:95]
	v_mfma_f32_16x16x32_bf16 v[88:91], v[136:139], v[160:163], v[88:91]
	v_mfma_f32_16x16x32_bf16 v[84:87], v[128:131], v[186:189], v[84:87]
	v_mfma_f32_16x16x32_bf16 v[80:83], v[136:139], v[186:189], v[80:83]
	v_mfma_f32_16x16x32_bf16 v[76:79], v[128:131], v[194:197], v[76:79]
	v_mfma_f32_16x16x32_bf16 v[72:75], v[136:139], v[194:197], v[72:75]
	v_mfma_f32_16x16x32_bf16 v[68:71], v[128:131], v[202:205], v[68:71]
	v_mfma_f32_16x16x32_bf16 v[64:67], v[136:139], v[202:205], v[64:67]
	v_mfma_f32_16x16x32_bf16 v[92:95], v[132:135], v[164:167], v[92:95]
	v_mfma_f32_16x16x32_bf16 v[88:91], v[140:143], v[164:167], v[88:91]
	v_mfma_f32_16x16x32_bf16 v[84:87], v[132:135], v[190:193], v[84:87]
	v_mfma_f32_16x16x32_bf16 v[80:83], v[140:143], v[190:193], v[80:83]
	v_mfma_f32_16x16x32_bf16 v[76:79], v[132:135], v[198:201], v[76:79]
	v_mfma_f32_16x16x32_bf16 v[72:75], v[140:143], v[198:201], v[72:75]
	v_mfma_f32_16x16x32_bf16 v[68:71], v[132:135], v[206:209], v[68:71]
	v_mfma_f32_16x16x32_bf16 v[64:67], v[140:143], v[206:209], v[64:67]
	s_setprio 0
	s_setprio 1
	v_mfma_f32_16x16x32_bf16 v[28:31], v[144:147], v[160:163], v[28:31]
	v_mfma_f32_16x16x32_bf16 v[24:27], v[152:155], v[160:163], v[24:27]
	v_mfma_f32_16x16x32_bf16 v[20:23], v[144:147], v[186:189], v[20:23]
	v_mfma_f32_16x16x32_bf16 v[16:19], v[152:155], v[186:189], v[16:19]
	v_mfma_f32_16x16x32_bf16 v[12:15], v[144:147], v[194:197], v[12:15]
	v_mfma_f32_16x16x32_bf16 v[8:11], v[152:155], v[194:197], v[8:11]
	v_mfma_f32_16x16x32_bf16 v[4:7], v[144:147], v[202:205], v[4:7]
	v_mfma_f32_16x16x32_bf16 v[0:3], v[152:155], v[202:205], v[0:3]
	v_mfma_f32_16x16x32_bf16 v[28:31], v[148:151], v[164:167], v[28:31]
	v_mfma_f32_16x16x32_bf16 v[24:27], v[156:159], v[164:167], v[24:27]
	v_mfma_f32_16x16x32_bf16 v[20:23], v[148:151], v[190:193], v[20:23]
	v_mfma_f32_16x16x32_bf16 v[16:19], v[156:159], v[190:193], v[16:19]
	v_mfma_f32_16x16x32_bf16 v[12:15], v[148:151], v[198:201], v[12:15]
	v_mfma_f32_16x16x32_bf16 v[8:11], v[156:159], v[198:201], v[8:11]
	s_barrier
	s_setprio 2
	v_mfma_f32_16x16x32_bf16 v[4:7], v[148:151], v[206:209], v[4:7]
	v_mfma_f32_16x16x32_bf16 v[0:3], v[156:159], v[206:209], v[0:3]
	s_setprio 0
	s_add_i32 s76, 0, 0x18000
	s_add_i32 s77, 0, 0x1c000
	v_add_u32_e32 v140, s76, v242
	v_add_u32_e32 v156, s77, v242
	ds_read_b128 v[128:131], v140
	ds_read_b128 v[132:135], v140 offset:1024
	ds_read_b128 v[136:139], v140 offset:2048
	ds_read_b128 v[140:143], v140 offset:3072
	ds_read_b128 v[144:147], v156
	ds_read_b128 v[148:151], v156 offset:1024
	ds_read_b128 v[152:155], v156 offset:2048
	ds_read_b128 v[156:159], v156 offset:3072
	s_add_u32 s28, s28, 0x80000
	s_addc_u32 s29, s29, 0
	s_mov_b32 m0, s40
	v_lshl_add_u64 v[218:219], s[28:29], 0, v[168:169]
	ds_read_b128 v[160:163], v245 offset:32768
	ds_read_b128 v[164:167], v245 offset:33792
	ds_read_b128 v[186:189], v245 offset:34816
	ds_read_b128 v[190:193], v245 offset:35840
	ds_read_b128 v[194:197], v245 offset:36864
	ds_read_b128 v[198:201], v245 offset:37888
	ds_read_b128 v[202:205], v245 offset:38912
	ds_read_b128 v[206:209], v245 offset:39936
	global_load_lds_dwordx4 v[218:219], off
	v_lshl_add_u64 v[218:219], s[28:29], 0, v[172:173]
	s_mov_b32 m0, s41
	s_nop 0
	global_load_lds_dwordx4 v[218:219], off
	s_waitcnt vmcnt(8)
	s_waitcnt lgkmcnt(0)
	s_barrier
	s_setprio 1
	s_waitcnt lgkmcnt(0)
	v_mfma_f32_16x16x32_bf16 v[124:127], v[128:131], v[160:163], v[124:127]
	v_mfma_f32_16x16x32_bf16 v[120:123], v[136:139], v[160:163], v[120:123]
	v_mfma_f32_16x16x32_bf16 v[116:119], v[128:131], v[186:189], v[116:119]
	v_mfma_f32_16x16x32_bf16 v[112:115], v[136:139], v[186:189], v[112:115]
	v_mfma_f32_16x16x32_bf16 v[108:111], v[128:131], v[194:197], v[108:111]
	v_mfma_f32_16x16x32_bf16 v[104:107], v[136:139], v[194:197], v[104:107]
	v_mfma_f32_16x16x32_bf16 v[100:103], v[128:131], v[202:205], v[100:103]
	v_mfma_f32_16x16x32_bf16 v[96:99], v[136:139], v[202:205], v[96:99]
	v_mfma_f32_16x16x32_bf16 v[124:127], v[132:135], v[164:167], v[124:127]
	v_mfma_f32_16x16x32_bf16 v[120:123], v[140:143], v[164:167], v[120:123]
	v_mfma_f32_16x16x32_bf16 v[116:119], v[132:135], v[190:193], v[116:119]
	v_mfma_f32_16x16x32_bf16 v[112:115], v[140:143], v[190:193], v[112:115]
	v_mfma_f32_16x16x32_bf16 v[108:111], v[132:135], v[198:201], v[108:111]
	v_mfma_f32_16x16x32_bf16 v[104:107], v[140:143], v[198:201], v[104:107]
	v_mfma_f32_16x16x32_bf16 v[100:103], v[132:135], v[206:209], v[100:103]
	v_mfma_f32_16x16x32_bf16 v[96:99], v[140:143], v[206:209], v[96:99]
	s_setprio 0
	s_setprio 1
	v_mfma_f32_16x16x32_bf16 v[60:63], v[144:147], v[160:163], v[60:63]
	v_mfma_f32_16x16x32_bf16 v[56:59], v[152:155], v[160:163], v[56:59]
	v_mfma_f32_16x16x32_bf16 v[52:55], v[144:147], v[186:189], v[52:55]
	v_mfma_f32_16x16x32_bf16 v[48:51], v[152:155], v[186:189], v[48:51]
	v_mfma_f32_16x16x32_bf16 v[44:47], v[144:147], v[194:197], v[44:47]
	v_mfma_f32_16x16x32_bf16 v[40:43], v[152:155], v[194:197], v[40:43]
	v_mfma_f32_16x16x32_bf16 v[36:39], v[144:147], v[202:205], v[36:39]
	v_mfma_f32_16x16x32_bf16 v[32:35], v[152:155], v[202:205], v[32:35]
	v_mfma_f32_16x16x32_bf16 v[60:63], v[148:151], v[164:167], v[60:63]
	v_mfma_f32_16x16x32_bf16 v[56:59], v[156:159], v[164:167], v[56:59]
	v_mfma_f32_16x16x32_bf16 v[52:55], v[148:151], v[190:193], v[52:55]
	v_mfma_f32_16x16x32_bf16 v[48:51], v[156:159], v[190:193], v[48:51]
	v_mfma_f32_16x16x32_bf16 v[44:47], v[148:151], v[198:201], v[44:47]
	v_mfma_f32_16x16x32_bf16 v[40:43], v[156:159], v[198:201], v[40:43]
	s_barrier
	s_setprio 2
	v_mfma_f32_16x16x32_bf16 v[36:39], v[148:151], v[206:209], v[36:39]
	v_mfma_f32_16x16x32_bf16 v[32:35], v[156:159], v[206:209], v[32:35]
	s_setprio 0
	s_add_i32 s28, s76, s67
	v_lshl_add_u64 v[210:211], v[210:211], 0, s[8:9]
	s_mov_b32 m0, s28
	ds_read_b128 v[160:163], v245 offset:49152
	ds_read_b128 v[164:167], v245 offset:50176
	ds_read_b128 v[186:189], v245 offset:51200
	ds_read_b128 v[190:193], v245 offset:52224
	ds_read_b128 v[194:197], v245 offset:53248
	ds_read_b128 v[198:201], v245 offset:54272
	ds_read_b128 v[202:205], v245 offset:55296
	ds_read_b128 v[206:209], v245 offset:56320
	global_load_lds_dwordx4 v[210:211], off
	s_add_i32 m0, s28, 0x2000
	s_add_u32 s26, s26, 0x80080
	v_lshl_add_u64 v[210:211], v[212:213], 0, s[8:9]
	s_addc_u32 s27, s27, 0
	s_add_i32 s28, s77, s67
	global_load_lds_dwordx4 v[210:211], off
	v_lshl_add_u64 v[210:211], s[26:27], 0, v[170:171]
	s_mov_b32 m0, s28
	s_nop 0
	global_load_lds_dwordx4 v[210:211], off
	v_lshl_add_u64 v[210:211], s[26:27], 0, v[174:175]
	s_add_i32 m0, s28, 0x2000
	s_nop 0
	global_load_lds_dwordx4 v[210:211], off
	v_lshl_add_u64 v[210:211], v[214:215], 0, s[8:9]
	s_mov_b32 m0, s55
	s_nop 0
	global_load_lds_dwordx4 v[210:211], off
	v_lshl_add_u64 v[210:211], v[216:217], 0, s[8:9]
	s_mov_b32 m0, s56
	s_nop 0
	global_load_lds_dwordx4 v[210:211], off
	s_waitcnt vmcnt(8)
	s_waitcnt lgkmcnt(0)
	s_barrier
	s_setprio 1
	s_waitcnt lgkmcnt(0)
	v_mfma_f32_16x16x32_bf16 v[92:95], v[128:131], v[160:163], v[92:95]
	v_mfma_f32_16x16x32_bf16 v[88:91], v[136:139], v[160:163], v[88:91]
	v_mfma_f32_16x16x32_bf16 v[84:87], v[128:131], v[186:189], v[84:87]
	v_mfma_f32_16x16x32_bf16 v[80:83], v[136:139], v[186:189], v[80:83]
	v_mfma_f32_16x16x32_bf16 v[76:79], v[128:131], v[194:197], v[76:79]
	v_mfma_f32_16x16x32_bf16 v[72:75], v[136:139], v[194:197], v[72:75]
	v_mfma_f32_16x16x32_bf16 v[68:71], v[128:131], v[202:205], v[68:71]
	v_mfma_f32_16x16x32_bf16 v[64:67], v[136:139], v[202:205], v[64:67]
	v_mfma_f32_16x16x32_bf16 v[92:95], v[132:135], v[164:167], v[92:95]
	v_mfma_f32_16x16x32_bf16 v[88:91], v[140:143], v[164:167], v[88:91]
	v_mfma_f32_16x16x32_bf16 v[84:87], v[132:135], v[190:193], v[84:87]
	v_mfma_f32_16x16x32_bf16 v[80:83], v[140:143], v[190:193], v[80:83]
	v_mfma_f32_16x16x32_bf16 v[76:79], v[132:135], v[198:201], v[76:79]
	v_mfma_f32_16x16x32_bf16 v[72:75], v[140:143], v[198:201], v[72:75]
	v_mfma_f32_16x16x32_bf16 v[68:71], v[132:135], v[206:209], v[68:71]
	v_mfma_f32_16x16x32_bf16 v[64:67], v[140:143], v[206:209], v[64:67]
	s_setprio 0
	s_setprio 1
	v_mfma_f32_16x16x32_bf16 v[28:31], v[144:147], v[160:163], v[28:31]
	v_mfma_f32_16x16x32_bf16 v[24:27], v[152:155], v[160:163], v[24:27]
	v_mfma_f32_16x16x32_bf16 v[20:23], v[144:147], v[186:189], v[20:23]
	v_mfma_f32_16x16x32_bf16 v[16:19], v[152:155], v[186:189], v[16:19]
	v_mfma_f32_16x16x32_bf16 v[12:15], v[144:147], v[194:197], v[12:15]
	v_mfma_f32_16x16x32_bf16 v[8:11], v[152:155], v[194:197], v[8:11]
	v_mfma_f32_16x16x32_bf16 v[4:7], v[144:147], v[202:205], v[4:7]
	v_mfma_f32_16x16x32_bf16 v[0:3], v[152:155], v[202:205], v[0:3]
	v_mfma_f32_16x16x32_bf16 v[28:31], v[148:151], v[164:167], v[28:31]
	v_mfma_f32_16x16x32_bf16 v[24:27], v[156:159], v[164:167], v[24:27]
	v_mfma_f32_16x16x32_bf16 v[20:23], v[148:151], v[190:193], v[20:23]
	v_mfma_f32_16x16x32_bf16 v[16:19], v[156:159], v[190:193], v[16:19]
	v_mfma_f32_16x16x32_bf16 v[12:15], v[148:151], v[198:201], v[12:15]
	v_mfma_f32_16x16x32_bf16 v[8:11], v[156:159], v[198:201], v[8:11]
	s_barrier
	s_setprio 2
	v_mfma_f32_16x16x32_bf16 v[4:7], v[148:151], v[206:209], v[4:7]
	v_mfma_f32_16x16x32_bf16 v[0:3], v[156:159], v[206:209], v[0:3]
	s_setprio 0
	s_add_i32 s75, s75, 2
	s_add_u32 s30, s30, 0x100
	s_addc_u32 s31, s31, 0
	s_add_u32 s24, s24, 0x100
	s_addc_u32 s25, s25, 0
	s_cmp_gt_u32 s75, 29
	s_cbranch_scc0 .LBB0_1661
	s_and_b64 vcc, exec, s[10:11]
	s_cbranch_vccz .LBB0_1664
	s_barrier

.LBB0_1979:
	ds_read_b128 v[130:133], v185
	ds_read_b128 v[134:137], v185 offset:1024
	ds_read_b128 v[138:141], v185 offset:2048
	ds_read_b128 v[142:145], v185 offset:3072
	ds_read_b128 v[146:149], v187
	ds_read_b128 v[150:153], v187 offset:1024
	ds_read_b128 v[154:157], v187 offset:2048
	ds_read_b128 v[192:195], v187 offset:3072
	s_add_u32 s30, s28, 0xfff80080
	s_addc_u32 s31, s29, -1
	s_cmp_eq_u32 s61, 28
	s_cselect_b32 s35, s6, s31
	s_cselect_b32 s34, s21, s30
	s_cselect_b32 s31, s19, s60
	s_cselect_b32 s30, s58, s59
	v_lshl_add_u64 v[158:159], s[28:29], 0, v[174:175]
	s_add_i32 m0, s27, 0xc000
	ds_read_b128 v[196:199], v189
	ds_read_b128 v[200:203], v189 offset:1024
	ds_read_b128 v[204:207], v189 offset:2048
	ds_read_b128 v[208:211], v189 offset:3072
	ds_read_b128 v[212:215], v189 offset:4096
	ds_read_b128 v[216:219], v189 offset:5120
	ds_read_b128 v[220:223], v189 offset:6144
	ds_read_b128 v[224:227], v189 offset:7168
	global_load_lds_dwordx4 v[158:159], off
	v_lshl_add_u64 v[158:159], s[28:29], 0, v[172:173]
	s_add_i32 m0, s27, 0xe000
	s_nop 0
	global_load_lds_dwordx4 v[158:159], off
	s_waitcnt vmcnt(8)
	s_waitcnt lgkmcnt(0)
	s_barrier
	s_setprio 1
	s_waitcnt lgkmcnt(0)
	v_mfma_f32_16x16x32_bf16 v[124:127], v[130:133], v[196:199], v[124:127]
	v_mfma_f32_16x16x32_bf16 v[120:123], v[138:141], v[196:199], v[120:123]
	v_mfma_f32_16x16x32_bf16 v[112:115], v[130:133], v[204:207], v[112:115]
	v_mfma_f32_16x16x32_bf16 v[104:107], v[138:141], v[204:207], v[104:107]
	v_mfma_f32_16x16x32_bf16 v[96:99], v[130:133], v[212:215], v[96:99]
	v_mfma_f32_16x16x32_bf16 v[88:91], v[138:141], v[212:215], v[88:91]
	v_mfma_f32_16x16x32_bf16 v[80:83], v[130:133], v[220:223], v[80:83]
	v_mfma_f32_16x16x32_bf16 v[72:75], v[138:141], v[220:223], v[72:75]
	v_mfma_f32_16x16x32_bf16 v[124:127], v[134:137], v[200:203], v[124:127]
	v_mfma_f32_16x16x32_bf16 v[120:123], v[142:145], v[200:203], v[120:123]
	v_mfma_f32_16x16x32_bf16 v[112:115], v[134:137], v[208:211], v[112:115]
	v_mfma_f32_16x16x32_bf16 v[104:107], v[142:145], v[208:211], v[104:107]
	v_mfma_f32_16x16x32_bf16 v[96:99], v[134:137], v[216:219], v[96:99]
	v_mfma_f32_16x16x32_bf16 v[88:91], v[142:145], v[216:219], v[88:91]
	v_mfma_f32_16x16x32_bf16 v[80:83], v[134:137], v[224:227], v[80:83]
	v_mfma_f32_16x16x32_bf16 v[72:75], v[142:145], v[224:227], v[72:75]
	s_setprio 0
	s_setprio 1
	v_mfma_f32_16x16x32_bf16 v[116:119], v[146:149], v[196:199], v[116:119]
	v_mfma_f32_16x16x32_bf16 v[108:111], v[154:157], v[196:199], v[108:111]
	v_mfma_f32_16x16x32_bf16 v[100:103], v[146:149], v[204:207], v[100:103]
	v_mfma_f32_16x16x32_bf16 v[92:95], v[154:157], v[204:207], v[92:95]
	v_mfma_f32_16x16x32_bf16 v[84:87], v[146:149], v[212:215], v[84:87]
	v_mfma_f32_16x16x32_bf16 v[76:79], v[154:157], v[212:215], v[76:79]
	v_mfma_f32_16x16x32_bf16 v[68:71], v[146:149], v[220:223], v[68:71]
	v_mfma_f32_16x16x32_bf16 v[64:67], v[154:157], v[220:223], v[64:67]
	v_mfma_f32_16x16x32_bf16 v[116:119], v[150:153], v[200:203], v[116:119]
	v_mfma_f32_16x16x32_bf16 v[108:111], v[192:195], v[200:203], v[108:111]
	v_mfma_f32_16x16x32_bf16 v[100:103], v[150:153], v[208:211], v[100:103]
	v_mfma_f32_16x16x32_bf16 v[92:95], v[192:195], v[208:211], v[92:95]
	v_mfma_f32_16x16x32_bf16 v[84:87], v[150:153], v[216:219], v[84:87]
	v_mfma_f32_16x16x32_bf16 v[76:79], v[192:195], v[216:219], v[76:79]
	s_barrier
	s_setprio 2
	v_mfma_f32_16x16x32_bf16 v[68:71], v[150:153], v[224:227], v[68:71]
	v_mfma_f32_16x16x32_bf16 v[64:67], v[192:195], v[224:227], v[64:67]
	s_setprio 0
	s_add_i32 s62, s52, s67
	v_lshl_add_u64 v[158:159], s[30:31], 0, v[162:163]
	s_mov_b32 m0, s62
	ds_read_b128 v[196:199], v189 offset:16384
	ds_read_b128 v[200:203], v189 offset:17408
	ds_read_b128 v[204:207], v189 offset:18432
	ds_read_b128 v[208:211], v189 offset:19456
	ds_read_b128 v[212:215], v189 offset:20480
	ds_read_b128 v[216:219], v189 offset:21504
	ds_read_b128 v[220:223], v189 offset:22528
	ds_read_b128 v[224:227], v189 offset:23552
	global_load_lds_dwordx4 v[158:159], off
	s_add_i32 m0, s62, 0x2000
	s_add_u32 s62, s30, 0x80000
	v_lshl_add_u64 v[228:229], s[30:31], 0, v[166:167]
	s_addc_u32 s63, s31, 0
	s_add_i32 s64, s53, s67
	global_load_lds_dwordx4 v[228:229], off
	v_lshl_add_u64 v[230:231], s[62:63], 0, v[162:163]
	s_mov_b32 m0, s64
	v_lshl_add_u64 v[232:233], s[34:35], 0, v[164:165]
	global_load_lds_dwordx4 v[230:231], off
	v_lshl_add_u64 v[230:231], s[62:63], 0, v[166:167]
	s_add_i32 m0, s64, 0x2000
	s_nop 0
	global_load_lds_dwordx4 v[230:231], off
	v_lshl_add_u64 v[230:231], s[34:35], 0, v[160:161]
	s_mov_b32 m0, s27
	s_nop 0
	global_load_lds_dwordx4 v[230:231], off
	s_mov_b32 m0, s41
	s_nop 0
	global_load_lds_dwordx4 v[232:233], off
	s_waitcnt vmcnt(8)
	s_waitcnt lgkmcnt(0)
	s_barrier
	s_setprio 1
	s_waitcnt lgkmcnt(0)
	v_mfma_f32_16x16x32_bf16 v[60:63], v[130:133], v[196:199], v[60:63]
	v_mfma_f32_16x16x32_bf16 v[56:59], v[138:141], v[196:199], v[56:59]
	v_mfma_f32_16x16x32_bf16 v[48:51], v[130:133], v[204:207], v[48:51]
	v_mfma_f32_16x16x32_bf16 v[40:43], v[138:141], v[204:207], v[40:43]
	v_mfma_f32_16x16x32_bf16 v[32:35], v[130:133], v[212:215], v[32:35]
	v_mfma_f32_16x16x32_bf16 v[24:27], v[138:141], v[212:215], v[24:27]
	v_mfma_f32_16x16x32_bf16 v[16:19], v[130:133], v[220:223], v[16:19]
	v_mfma_f32_16x16x32_bf16 v[8:11], v[138:141], v[220:223], v[8:11]
	v_mfma_f32_16x16x32_bf16 v[60:63], v[134:137], v[200:203], v[60:63]
	v_mfma_f32_16x16x32_bf16 v[56:59], v[142:145], v[200:203], v[56:59]
	v_mfma_f32_16x16x32_bf16 v[48:51], v[134:137], v[208:211], v[48:51]
	v_mfma_f32_16x16x32_bf16 v[40:43], v[142:145], v[208:211], v[40:43]
	v_mfma_f32_16x16x32_bf16 v[32:35], v[134:137], v[216:219], v[32:35]
	v_mfma_f32_16x16x32_bf16 v[24:27], v[142:145], v[216:219], v[24:27]
	v_mfma_f32_16x16x32_bf16 v[16:19], v[134:137], v[224:227], v[16:19]
	v_mfma_f32_16x16x32_bf16 v[8:11], v[142:145], v[224:227], v[8:11]
	s_setprio 0
	s_setprio 1
	v_mfma_f32_16x16x32_bf16 v[52:55], v[146:149], v[196:199], v[52:55]
	v_mfma_f32_16x16x32_bf16 v[44:47], v[154:157], v[196:199], v[44:47]
	v_mfma_f32_16x16x32_bf16 v[36:39], v[146:149], v[204:207], v[36:39]
	v_mfma_f32_16x16x32_bf16 v[28:31], v[154:157], v[204:207], v[28:31]
	v_mfma_f32_16x16x32_bf16 v[20:23], v[146:149], v[212:215], v[20:23]
	v_mfma_f32_16x16x32_bf16 v[12:15], v[154:157], v[212:215], v[12:15]
	v_mfma_f32_16x16x32_bf16 v[4:7], v[146:149], v[220:223], v[4:7]
	v_mfma_f32_16x16x32_bf16 v[0:3], v[154:157], v[220:223], v[0:3]
	v_mfma_f32_16x16x32_bf16 v[52:55], v[150:153], v[200:203], v[52:55]
	v_mfma_f32_16x16x32_bf16 v[44:47], v[192:195], v[200:203], v[44:47]
	v_mfma_f32_16x16x32_bf16 v[36:39], v[150:153], v[208:211], v[36:39]
	v_mfma_f32_16x16x32_bf16 v[28:31], v[192:195], v[208:211], v[28:31]
	v_mfma_f32_16x16x32_bf16 v[20:23], v[150:153], v[216:219], v[20:23]
	v_mfma_f32_16x16x32_bf16 v[12:15], v[192:195], v[216:219], v[12:15]
	s_barrier
	s_setprio 2
	v_mfma_f32_16x16x32_bf16 v[4:7], v[150:153], v[224:227], v[4:7]
	v_mfma_f32_16x16x32_bf16 v[0:3], v[192:195], v[224:227], v[0:3]
	s_setprio 0
	s_add_i32 s62, 0, 0x18000
	v_add_u32_e32 v129, s62, v181
	s_add_i32 s63, 0, 0x1c000
	ds_read_b128 v[130:133], v129
	ds_read_b128 v[134:137], v129 offset:1024
	ds_read_b128 v[138:141], v129 offset:2048
	ds_read_b128 v[142:145], v129 offset:3072
	v_add_u32_e32 v129, s63, v181
	ds_read_b128 v[146:149], v129
	ds_read_b128 v[150:153], v129 offset:1024
	ds_read_b128 v[154:157], v129 offset:2048
	ds_read_b128 v[192:195], v129 offset:3072
	s_add_u32 s34, s34, 0x80000
	s_addc_u32 s35, s35, 0
	s_mov_b32 m0, s42
	v_lshl_add_u64 v[234:235], s[34:35], 0, v[160:161]
	ds_read_b128 v[196:199], v189 offset:32768
	ds_read_b128 v[200:203], v189 offset:33792
	ds_read_b128 v[204:207], v189 offset:34816
	ds_read_b128 v[208:211], v189 offset:35840
	ds_read_b128 v[212:215], v189 offset:36864
	ds_read_b128 v[216:219], v189 offset:37888
	ds_read_b128 v[220:223], v189 offset:38912
	ds_read_b128 v[224:227], v189 offset:39936
	global_load_lds_dwordx4 v[234:235], off
	v_lshl_add_u64 v[234:235], s[34:35], 0, v[164:165]
	s_mov_b32 m0, s43
	s_nop 0
	global_load_lds_dwordx4 v[234:235], off
	s_waitcnt vmcnt(8)
	s_waitcnt lgkmcnt(0)
	s_barrier
	s_setprio 1
	s_waitcnt lgkmcnt(0)
	v_mfma_f32_16x16x32_bf16 v[124:127], v[130:133], v[196:199], v[124:127]
	v_mfma_f32_16x16x32_bf16 v[120:123], v[138:141], v[196:199], v[120:123]
	v_mfma_f32_16x16x32_bf16 v[112:115], v[130:133], v[204:207], v[112:115]
	v_mfma_f32_16x16x32_bf16 v[104:107], v[138:141], v[204:207], v[104:107]
	v_mfma_f32_16x16x32_bf16 v[96:99], v[130:133], v[212:215], v[96:99]
	v_mfma_f32_16x16x32_bf16 v[88:91], v[138:141], v[212:215], v[88:91]
	v_mfma_f32_16x16x32_bf16 v[80:83], v[130:133], v[220:223], v[80:83]
	v_mfma_f32_16x16x32_bf16 v[72:75], v[138:141], v[220:223], v[72:75]
	v_mfma_f32_16x16x32_bf16 v[124:127], v[134:137], v[200:203], v[124:127]
	v_mfma_f32_16x16x32_bf16 v[120:123], v[142:145], v[200:203], v[120:123]
	v_mfma_f32_16x16x32_bf16 v[112:115], v[134:137], v[208:211], v[112:115]
	v_mfma_f32_16x16x32_bf16 v[104:107], v[142:145], v[208:211], v[104:107]
	v_mfma_f32_16x16x32_bf16 v[96:99], v[134:137], v[216:219], v[96:99]
	v_mfma_f32_16x16x32_bf16 v[88:91], v[142:145], v[216:219], v[88:91]
	v_mfma_f32_16x16x32_bf16 v[80:83], v[134:137], v[224:227], v[80:83]
	v_mfma_f32_16x16x32_bf16 v[72:75], v[142:145], v[224:227], v[72:75]
	s_setprio 0
	s_setprio 1
	v_mfma_f32_16x16x32_bf16 v[116:119], v[146:149], v[196:199], v[116:119]
	v_mfma_f32_16x16x32_bf16 v[108:111], v[154:157], v[196:199], v[108:111]
	v_mfma_f32_16x16x32_bf16 v[100:103], v[146:149], v[204:207], v[100:103]
	v_mfma_f32_16x16x32_bf16 v[92:95], v[154:157], v[204:207], v[92:95]
	v_mfma_f32_16x16x32_bf16 v[84:87], v[146:149], v[212:215], v[84:87]
	v_mfma_f32_16x16x32_bf16 v[76:79], v[154:157], v[212:215], v[76:79]
	v_mfma_f32_16x16x32_bf16 v[68:71], v[146:149], v[220:223], v[68:71]
	v_mfma_f32_16x16x32_bf16 v[64:67], v[154:157], v[220:223], v[64:67]
	v_mfma_f32_16x16x32_bf16 v[116:119], v[150:153], v[200:203], v[116:119]
	v_mfma_f32_16x16x32_bf16 v[108:111], v[192:195], v[200:203], v[108:111]
	v_mfma_f32_16x16x32_bf16 v[100:103], v[150:153], v[208:211], v[100:103]
	v_mfma_f32_16x16x32_bf16 v[92:95], v[192:195], v[208:211], v[92:95]
	v_mfma_f32_16x16x32_bf16 v[84:87], v[150:153], v[216:219], v[84:87]
	v_mfma_f32_16x16x32_bf16 v[76:79], v[192:195], v[216:219], v[76:79]
	s_barrier
	s_setprio 2
	v_mfma_f32_16x16x32_bf16 v[68:71], v[150:153], v[224:227], v[68:71]
	v_mfma_f32_16x16x32_bf16 v[64:67], v[192:195], v[224:227], v[64:67]
	s_setprio 0
	s_add_i32 s34, s62, s67
	v_lshl_add_u64 v[158:159], v[158:159], 0, s[12:13]
	s_mov_b32 m0, s34
	ds_read_b128 v[196:199], v189 offset:49152
	ds_read_b128 v[200:203], v189 offset:50176
	ds_read_b128 v[204:207], v189 offset:51200
	ds_read_b128 v[208:211], v189 offset:52224
	ds_read_b128 v[212:215], v189 offset:53248
	ds_read_b128 v[216:219], v189 offset:54272
	ds_read_b128 v[220:223], v189 offset:55296
	ds_read_b128 v[224:227], v189 offset:56320
	global_load_lds_dwordx4 v[158:159], off
	s_add_i32 m0, s34, 0x2000
	s_add_u32 s30, s30, 0x80080
	v_lshl_add_u64 v[158:159], v[228:229], 0, s[12:13]
	s_addc_u32 s31, s31, 0
	s_add_i32 s34, s63, s67
	global_load_lds_dwordx4 v[158:159], off
	v_lshl_add_u64 v[158:159], s[30:31], 0, v[162:163]
	s_mov_b32 m0, s34
	s_nop 0
	global_load_lds_dwordx4 v[158:159], off
	v_lshl_add_u64 v[158:159], s[30:31], 0, v[166:167]
	s_add_i32 m0, s34, 0x2000
	s_nop 0
	global_load_lds_dwordx4 v[158:159], off
	v_lshl_add_u64 v[158:159], v[230:231], 0, s[12:13]
	s_mov_b32 m0, s44
	s_nop 0
	global_load_lds_dwordx4 v[158:159], off
	v_lshl_add_u64 v[158:159], v[232:233], 0, s[12:13]
	s_mov_b32 m0, s45
	s_nop 0
	global_load_lds_dwordx4 v[158:159], off
	s_waitcnt vmcnt(8)
	s_waitcnt lgkmcnt(0)
	s_barrier
	s_setprio 1
	s_waitcnt lgkmcnt(0)
	v_mfma_f32_16x16x32_bf16 v[60:63], v[130:133], v[196:199], v[60:63]
	v_mfma_f32_16x16x32_bf16 v[56:59], v[138:141], v[196:199], v[56:59]
	v_mfma_f32_16x16x32_bf16 v[48:51], v[130:133], v[204:207], v[48:51]
	v_mfma_f32_16x16x32_bf16 v[40:43], v[138:141], v[204:207], v[40:43]
	v_mfma_f32_16x16x32_bf16 v[32:35], v[130:133], v[212:215], v[32:35]
	v_mfma_f32_16x16x32_bf16 v[24:27], v[138:141], v[212:215], v[24:27]
	v_mfma_f32_16x16x32_bf16 v[16:19], v[130:133], v[220:223], v[16:19]
	v_mfma_f32_16x16x32_bf16 v[8:11], v[138:141], v[220:223], v[8:11]
	v_mfma_f32_16x16x32_bf16 v[60:63], v[134:137], v[200:203], v[60:63]
	v_mfma_f32_16x16x32_bf16 v[56:59], v[142:145], v[200:203], v[56:59]
	v_mfma_f32_16x16x32_bf16 v[48:51], v[134:137], v[208:211], v[48:51]
	v_mfma_f32_16x16x32_bf16 v[40:43], v[142:145], v[208:211], v[40:43]
	v_mfma_f32_16x16x32_bf16 v[32:35], v[134:137], v[216:219], v[32:35]
	v_mfma_f32_16x16x32_bf16 v[24:27], v[142:145], v[216:219], v[24:27]
	v_mfma_f32_16x16x32_bf16 v[16:19], v[134:137], v[224:227], v[16:19]
	v_mfma_f32_16x16x32_bf16 v[8:11], v[142:145], v[224:227], v[8:11]
	s_setprio 0
	s_setprio 1
	v_mfma_f32_16x16x32_bf16 v[52:55], v[146:149], v[196:199], v[52:55]
	v_mfma_f32_16x16x32_bf16 v[44:47], v[154:157], v[196:199], v[44:47]
	v_mfma_f32_16x16x32_bf16 v[36:39], v[146:149], v[204:207], v[36:39]
	v_mfma_f32_16x16x32_bf16 v[28:31], v[154:157], v[204:207], v[28:31]
	v_mfma_f32_16x16x32_bf16 v[20:23], v[146:149], v[212:215], v[20:23]
	v_mfma_f32_16x16x32_bf16 v[12:15], v[154:157], v[212:215], v[12:15]
	v_mfma_f32_16x16x32_bf16 v[4:7], v[146:149], v[220:223], v[4:7]
	v_mfma_f32_16x16x32_bf16 v[0:3], v[154:157], v[220:223], v[0:3]
	v_mfma_f32_16x16x32_bf16 v[52:55], v[150:153], v[200:203], v[52:55]
	v_mfma_f32_16x16x32_bf16 v[44:47], v[192:195], v[200:203], v[44:47]
	v_mfma_f32_16x16x32_bf16 v[36:39], v[150:153], v[208:211], v[36:39]
	v_mfma_f32_16x16x32_bf16 v[28:31], v[192:195], v[208:211], v[28:31]
	v_mfma_f32_16x16x32_bf16 v[20:23], v[150:153], v[216:219], v[20:23]
	v_mfma_f32_16x16x32_bf16 v[12:15], v[192:195], v[216:219], v[12:15]
	s_barrier
	s_setprio 2
	v_mfma_f32_16x16x32_bf16 v[4:7], v[150:153], v[224:227], v[4:7]
	v_mfma_f32_16x16x32_bf16 v[0:3], v[192:195], v[224:227], v[0:3]
	s_setprio 0
	s_add_i32 s61, s61, 2
	s_add_u32 s59, s59, 0x100
	s_addc_u32 s60, s60, 0
	s_add_u32 s28, s28, 0x100
	s_addc_u32 s29, s29, 0
	s_cmp_gt_u32 s61, 29
	s_cbranch_scc0 .LBB0_1979
	s_and_b64 vcc, exec, s[14:15]
	s_cbranch_vccz .LBB0_1982
	s_barrier

.LBB0_2924:
	ds_read_b128 v[124:127], v163
	ds_read_b128 v[156:159], v163 offset:1024
	ds_read_b128 v[170:173], v163 offset:2048
	ds_read_b128 v[174:177], v163 offset:3072
	ds_read_b128 v[178:181], v165
	ds_read_b128 v[182:185], v165 offset:1024
	ds_read_b128 v[186:189], v165 offset:2048
	ds_read_b128 v[190:193], v165 offset:3072
	s_add_u32 s26, s24, 0xfff80080
	s_addc_u32 s27, s25, -1
	s_cmp_eq_u32 s56, 28
	s_cselect_b32 s29, s17, s27
	s_cselect_b32 s28, s52, s26
	s_cselect_b32 s27, s15, s55
	s_cselect_b32 s26, s53, s54
	v_lshl_add_u64 v[114:115], s[24:25], 0, v[148:149]
	s_add_i32 m0, s23, 0xc000
	ds_read_b128 v[194:197], v167
	ds_read_b128 v[198:201], v167 offset:1024
	ds_read_b128 v[202:205], v167 offset:2048
	ds_read_b128 v[206:209], v167 offset:3072
	ds_read_b128 v[210:213], v167 offset:4096
	ds_read_b128 v[214:217], v167 offset:5120
	ds_read_b128 v[218:221], v167 offset:6144
	ds_read_b128 v[222:225], v167 offset:7168
	global_load_lds_dwordx4 v[114:115], off
	v_lshl_add_u64 v[114:115], s[24:25], 0, v[146:147]
	s_add_i32 m0, s23, 0xe000
	s_nop 0
	global_load_lds_dwordx4 v[114:115], off
	s_waitcnt vmcnt(8)
	s_waitcnt lgkmcnt(0)
	s_barrier
	s_setprio 1
	s_waitcnt lgkmcnt(0)
	v_mfma_f32_16x16x32_bf16 v[132:135], v[124:127], v[194:197], v[132:135]
	v_mfma_f32_16x16x32_bf16 v[120:123], v[170:173], v[194:197], v[120:123]
	v_mfma_f32_16x16x32_bf16 v[108:111], v[124:127], v[202:205], v[108:111]
	v_mfma_f32_16x16x32_bf16 v[100:103], v[170:173], v[202:205], v[100:103]
	v_mfma_f32_16x16x32_bf16 v[92:95], v[124:127], v[210:213], v[92:95]
	v_mfma_f32_16x16x32_bf16 v[84:87], v[170:173], v[210:213], v[84:87]
	v_mfma_f32_16x16x32_bf16 v[76:79], v[124:127], v[218:221], v[76:79]
	v_mfma_f32_16x16x32_bf16 v[68:71], v[170:173], v[218:221], v[68:71]
	v_mfma_f32_16x16x32_bf16 v[132:135], v[156:159], v[198:201], v[132:135]
	v_mfma_f32_16x16x32_bf16 v[120:123], v[174:177], v[198:201], v[120:123]
	v_mfma_f32_16x16x32_bf16 v[108:111], v[156:159], v[206:209], v[108:111]
	v_mfma_f32_16x16x32_bf16 v[100:103], v[174:177], v[206:209], v[100:103]
	v_mfma_f32_16x16x32_bf16 v[92:95], v[156:159], v[214:217], v[92:95]
	v_mfma_f32_16x16x32_bf16 v[84:87], v[174:177], v[214:217], v[84:87]
	v_mfma_f32_16x16x32_bf16 v[76:79], v[156:159], v[222:225], v[76:79]
	v_mfma_f32_16x16x32_bf16 v[68:71], v[174:177], v[222:225], v[68:71]
	s_setprio 0
	s_setprio 1
	v_mfma_f32_16x16x32_bf16 v[128:131], v[178:181], v[194:197], v[128:131]
	v_mfma_f32_16x16x32_bf16 v[114:117], v[186:189], v[194:197], v[116:119]
	v_mfma_f32_16x16x32_bf16 v[104:107], v[178:181], v[202:205], v[104:107]
	v_mfma_f32_16x16x32_bf16 v[96:99], v[186:189], v[202:205], v[96:99]
	v_mfma_f32_16x16x32_bf16 v[88:91], v[178:181], v[210:213], v[88:91]
	v_mfma_f32_16x16x32_bf16 v[80:83], v[186:189], v[210:213], v[80:83]
	v_mfma_f32_16x16x32_bf16 v[72:75], v[178:181], v[218:221], v[72:75]
	v_mfma_f32_16x16x32_bf16 v[64:67], v[186:189], v[218:221], v[64:67]
	v_mfma_f32_16x16x32_bf16 v[128:131], v[182:185], v[198:201], v[128:131]
	v_mfma_f32_16x16x32_bf16 v[114:117], v[190:193], v[198:201], v[114:117]
	v_mfma_f32_16x16x32_bf16 v[104:107], v[182:185], v[206:209], v[104:107]
	v_mfma_f32_16x16x32_bf16 v[96:99], v[190:193], v[206:209], v[96:99]
	v_mfma_f32_16x16x32_bf16 v[88:91], v[182:185], v[214:217], v[88:91]
	v_mfma_f32_16x16x32_bf16 v[80:83], v[190:193], v[214:217], v[80:83]
	s_barrier
	s_setprio 2
	v_mfma_f32_16x16x32_bf16 v[72:75], v[182:185], v[222:225], v[72:75]
	v_mfma_f32_16x16x32_bf16 v[64:67], v[190:193], v[222:225], v[64:67]
	s_setprio 0
	s_add_i32 s57, s48, s67
	v_lshl_add_u64 v[226:227], s[26:27], 0, v[138:139]
	s_mov_b32 m0, s57
	ds_read_b128 v[194:197], v167 offset:16384
	ds_read_b128 v[198:201], v167 offset:17408
	ds_read_b128 v[202:205], v167 offset:18432
	ds_read_b128 v[206:209], v167 offset:19456
	ds_read_b128 v[210:213], v167 offset:20480
	ds_read_b128 v[214:217], v167 offset:21504
	ds_read_b128 v[218:221], v167 offset:22528
	ds_read_b128 v[222:225], v167 offset:23552
	global_load_lds_dwordx4 v[226:227], off
	s_add_i32 m0, s57, 0x2000
	s_add_u32 s58, s26, 0x80000
	v_lshl_add_u64 v[228:229], s[26:27], 0, v[142:143]
	s_addc_u32 s59, s27, 0
	s_add_i32 s57, s49, s67
	global_load_lds_dwordx4 v[228:229], off
	v_lshl_add_u64 v[118:119], s[58:59], 0, v[138:139]
	s_mov_b32 m0, s57
	v_lshl_add_u64 v[230:231], s[28:29], 0, v[136:137]
	global_load_lds_dwordx4 v[118:119], off
	v_lshl_add_u64 v[118:119], s[58:59], 0, v[142:143]
	s_add_i32 m0, s57, 0x2000
	v_lshl_add_u64 v[232:233], s[28:29], 0, v[140:141]
	global_load_lds_dwordx4 v[118:119], off
	s_mov_b32 m0, s23
	s_nop 0
	global_load_lds_dwordx4 v[230:231], off
	s_mov_b32 m0, s37
	s_nop 0
	global_load_lds_dwordx4 v[232:233], off
	s_waitcnt vmcnt(8)
	s_waitcnt lgkmcnt(0)
	s_barrier
	s_setprio 1
	s_waitcnt lgkmcnt(0)
	v_mfma_f32_16x16x32_bf16 v[60:63], v[124:127], v[194:197], v[60:63]
	v_mfma_f32_16x16x32_bf16 v[52:55], v[170:173], v[194:197], v[52:55]
	v_mfma_f32_16x16x32_bf16 v[44:47], v[124:127], v[202:205], v[44:47]
	v_mfma_f32_16x16x32_bf16 v[36:39], v[170:173], v[202:205], v[36:39]
	v_mfma_f32_16x16x32_bf16 v[28:31], v[124:127], v[210:213], v[28:31]
	v_mfma_f32_16x16x32_bf16 v[20:23], v[170:173], v[210:213], v[20:23]
	v_mfma_f32_16x16x32_bf16 v[12:15], v[124:127], v[218:221], v[12:15]
	v_mfma_f32_16x16x32_bf16 v[4:7], v[170:173], v[218:221], v[4:7]
	v_mfma_f32_16x16x32_bf16 v[60:63], v[156:159], v[198:201], v[60:63]
	v_mfma_f32_16x16x32_bf16 v[52:55], v[174:177], v[198:201], v[52:55]
	v_mfma_f32_16x16x32_bf16 v[44:47], v[156:159], v[206:209], v[44:47]
	v_mfma_f32_16x16x32_bf16 v[36:39], v[174:177], v[206:209], v[36:39]
	v_mfma_f32_16x16x32_bf16 v[28:31], v[156:159], v[214:217], v[28:31]
	v_mfma_f32_16x16x32_bf16 v[20:23], v[174:177], v[214:217], v[20:23]
	v_mfma_f32_16x16x32_bf16 v[12:15], v[156:159], v[222:225], v[12:15]
	v_mfma_f32_16x16x32_bf16 v[4:7], v[174:177], v[222:225], v[4:7]
	s_setprio 0
	s_setprio 1
	v_mfma_f32_16x16x32_bf16 v[56:59], v[178:181], v[194:197], v[56:59]
	v_mfma_f32_16x16x32_bf16 v[48:51], v[186:189], v[194:197], v[48:51]
	v_mfma_f32_16x16x32_bf16 v[40:43], v[178:181], v[202:205], v[40:43]
	v_mfma_f32_16x16x32_bf16 v[32:35], v[186:189], v[202:205], v[32:35]
	v_mfma_f32_16x16x32_bf16 v[24:27], v[178:181], v[210:213], v[24:27]
	v_mfma_f32_16x16x32_bf16 v[16:19], v[186:189], v[210:213], v[16:19]
	v_mfma_f32_16x16x32_bf16 v[8:11], v[178:181], v[218:221], v[8:11]
	v_mfma_f32_16x16x32_bf16 v[0:3], v[186:189], v[218:221], v[0:3]
	v_mfma_f32_16x16x32_bf16 v[56:59], v[182:185], v[198:201], v[56:59]
	v_mfma_f32_16x16x32_bf16 v[48:51], v[190:193], v[198:201], v[48:51]
	v_mfma_f32_16x16x32_bf16 v[40:43], v[182:185], v[206:209], v[40:43]
	v_mfma_f32_16x16x32_bf16 v[32:35], v[190:193], v[206:209], v[32:35]
	v_mfma_f32_16x16x32_bf16 v[24:27], v[182:185], v[214:217], v[24:27]
	v_mfma_f32_16x16x32_bf16 v[16:19], v[190:193], v[214:217], v[16:19]
	s_barrier
	s_setprio 2
	v_mfma_f32_16x16x32_bf16 v[8:11], v[182:185], v[222:225], v[8:11]
	v_mfma_f32_16x16x32_bf16 v[0:3], v[190:193], v[222:225], v[0:3]
	s_setprio 0
	s_add_i32 s57, 0, 0x18000
	v_add_u32_e32 v113, s57, v155
	s_add_i32 s58, 0, 0x1c000
	ds_read_b128 v[124:127], v113
	ds_read_b128 v[156:159], v113 offset:1024
	ds_read_b128 v[170:173], v113 offset:2048
	ds_read_b128 v[174:177], v113 offset:3072
	v_add_u32_e32 v113, s58, v155
	ds_read_b128 v[178:181], v113
	ds_read_b128 v[182:185], v113 offset:1024
	ds_read_b128 v[186:189], v113 offset:2048
	ds_read_b128 v[190:193], v113 offset:3072
	s_add_u32 s28, s28, 0x80000
	s_addc_u32 s29, s29, 0
	s_mov_b32 m0, s38
	v_lshl_add_u64 v[118:119], s[28:29], 0, v[136:137]
	ds_read_b128 v[194:197], v167 offset:32768
	ds_read_b128 v[198:201], v167 offset:33792
	ds_read_b128 v[202:205], v167 offset:34816
	ds_read_b128 v[206:209], v167 offset:35840
	ds_read_b128 v[210:213], v167 offset:36864
	ds_read_b128 v[214:217], v167 offset:37888
	ds_read_b128 v[218:221], v167 offset:38912
	ds_read_b128 v[222:225], v167 offset:39936
	global_load_lds_dwordx4 v[118:119], off
	v_lshl_add_u64 v[118:119], s[28:29], 0, v[140:141]
	s_mov_b32 m0, s39
	s_nop 0
	global_load_lds_dwordx4 v[118:119], off
	s_waitcnt vmcnt(8)
	s_waitcnt lgkmcnt(0)
	s_barrier
	s_setprio 1
	s_waitcnt lgkmcnt(0)
	v_mfma_f32_16x16x32_bf16 v[132:135], v[124:127], v[194:197], v[132:135]
	v_mfma_f32_16x16x32_bf16 v[118:121], v[170:173], v[194:197], v[120:123]
	v_mfma_f32_16x16x32_bf16 v[108:111], v[124:127], v[202:205], v[108:111]
	v_mfma_f32_16x16x32_bf16 v[100:103], v[170:173], v[202:205], v[100:103]
	v_mfma_f32_16x16x32_bf16 v[92:95], v[124:127], v[210:213], v[92:95]
	v_mfma_f32_16x16x32_bf16 v[84:87], v[170:173], v[210:213], v[84:87]
	v_mfma_f32_16x16x32_bf16 v[76:79], v[124:127], v[218:221], v[76:79]
	v_mfma_f32_16x16x32_bf16 v[68:71], v[170:173], v[218:221], v[68:71]
	v_mfma_f32_16x16x32_bf16 v[132:135], v[156:159], v[198:201], v[132:135]
	v_mfma_f32_16x16x32_bf16 v[120:123], v[174:177], v[198:201], v[118:121]
	v_mfma_f32_16x16x32_bf16 v[108:111], v[156:159], v[206:209], v[108:111]
	v_mfma_f32_16x16x32_bf16 v[100:103], v[174:177], v[206:209], v[100:103]
	v_mfma_f32_16x16x32_bf16 v[92:95], v[156:159], v[214:217], v[92:95]
	v_mfma_f32_16x16x32_bf16 v[84:87], v[174:177], v[214:217], v[84:87]
	v_mfma_f32_16x16x32_bf16 v[76:79], v[156:159], v[222:225], v[76:79]
	v_mfma_f32_16x16x32_bf16 v[68:71], v[174:177], v[222:225], v[68:71]
	s_setprio 0
	s_setprio 1
	v_mfma_f32_16x16x32_bf16 v[128:131], v[178:181], v[194:197], v[128:131]
	v_mfma_f32_16x16x32_bf16 v[114:117], v[186:189], v[194:197], v[114:117]
	v_mfma_f32_16x16x32_bf16 v[104:107], v[178:181], v[202:205], v[104:107]
	v_mfma_f32_16x16x32_bf16 v[96:99], v[186:189], v[202:205], v[96:99]
	v_mfma_f32_16x16x32_bf16 v[88:91], v[178:181], v[210:213], v[88:91]
	v_mfma_f32_16x16x32_bf16 v[80:83], v[186:189], v[210:213], v[80:83]
	v_mfma_f32_16x16x32_bf16 v[72:75], v[178:181], v[218:221], v[72:75]
	v_mfma_f32_16x16x32_bf16 v[64:67], v[186:189], v[218:221], v[64:67]
	v_mfma_f32_16x16x32_bf16 v[128:131], v[182:185], v[198:201], v[128:131]
	v_mfma_f32_16x16x32_bf16 v[116:119], v[190:193], v[198:201], v[114:117]
	v_mfma_f32_16x16x32_bf16 v[104:107], v[182:185], v[206:209], v[104:107]
	v_mfma_f32_16x16x32_bf16 v[96:99], v[190:193], v[206:209], v[96:99]
	v_mfma_f32_16x16x32_bf16 v[88:91], v[182:185], v[214:217], v[88:91]
	v_mfma_f32_16x16x32_bf16 v[80:83], v[190:193], v[214:217], v[80:83]
	s_barrier
	s_setprio 2
	v_mfma_f32_16x16x32_bf16 v[72:75], v[182:185], v[222:225], v[72:75]
	v_mfma_f32_16x16x32_bf16 v[64:67], v[190:193], v[222:225], v[64:67]
	s_setprio 0
	s_add_i32 s28, s57, s67
	v_lshl_add_u64 v[114:115], v[226:227], 0, s[10:11]
	s_mov_b32 m0, s28
	ds_read_b128 v[194:197], v167 offset:49152
	ds_read_b128 v[198:201], v167 offset:50176
	ds_read_b128 v[202:205], v167 offset:51200
	ds_read_b128 v[206:209], v167 offset:52224
	ds_read_b128 v[210:213], v167 offset:53248
	ds_read_b128 v[214:217], v167 offset:54272
	ds_read_b128 v[218:221], v167 offset:55296
	ds_read_b128 v[222:225], v167 offset:56320
	global_load_lds_dwordx4 v[114:115], off
	s_add_i32 m0, s28, 0x2000
	s_add_u32 s26, s26, 0x80080
	v_lshl_add_u64 v[114:115], v[228:229], 0, s[10:11]
	s_addc_u32 s27, s27, 0
	s_add_i32 s28, s58, s67
	global_load_lds_dwordx4 v[114:115], off
	v_lshl_add_u64 v[114:115], s[26:27], 0, v[138:139]
	s_mov_b32 m0, s28
	s_nop 0
	global_load_lds_dwordx4 v[114:115], off
	v_lshl_add_u64 v[114:115], s[26:27], 0, v[142:143]
	s_add_i32 m0, s28, 0x2000
	s_nop 0
	global_load_lds_dwordx4 v[114:115], off
	v_lshl_add_u64 v[114:115], v[230:231], 0, s[10:11]
	s_mov_b32 m0, s41
	s_nop 0
	global_load_lds_dwordx4 v[114:115], off
	v_lshl_add_u64 v[114:115], v[232:233], 0, s[10:11]
	s_mov_b32 m0, s42
	s_nop 0
	global_load_lds_dwordx4 v[114:115], off
	s_waitcnt vmcnt(8)
	s_waitcnt lgkmcnt(0)
	s_barrier
	s_setprio 1
	s_waitcnt lgkmcnt(0)
	v_mfma_f32_16x16x32_bf16 v[60:63], v[124:127], v[194:197], v[60:63]
	v_mfma_f32_16x16x32_bf16 v[52:55], v[170:173], v[194:197], v[52:55]
	v_mfma_f32_16x16x32_bf16 v[44:47], v[124:127], v[202:205], v[44:47]
	v_mfma_f32_16x16x32_bf16 v[36:39], v[170:173], v[202:205], v[36:39]
	v_mfma_f32_16x16x32_bf16 v[28:31], v[124:127], v[210:213], v[28:31]
	v_mfma_f32_16x16x32_bf16 v[20:23], v[170:173], v[210:213], v[20:23]
	v_mfma_f32_16x16x32_bf16 v[12:15], v[124:127], v[218:221], v[12:15]
	v_mfma_f32_16x16x32_bf16 v[4:7], v[170:173], v[218:221], v[4:7]
	v_mfma_f32_16x16x32_bf16 v[60:63], v[156:159], v[198:201], v[60:63]
	v_mfma_f32_16x16x32_bf16 v[52:55], v[174:177], v[198:201], v[52:55]
	v_mfma_f32_16x16x32_bf16 v[44:47], v[156:159], v[206:209], v[44:47]
	v_mfma_f32_16x16x32_bf16 v[36:39], v[174:177], v[206:209], v[36:39]
	v_mfma_f32_16x16x32_bf16 v[28:31], v[156:159], v[214:217], v[28:31]
	v_mfma_f32_16x16x32_bf16 v[20:23], v[174:177], v[214:217], v[20:23]
	v_mfma_f32_16x16x32_bf16 v[12:15], v[156:159], v[222:225], v[12:15]
	v_mfma_f32_16x16x32_bf16 v[4:7], v[174:177], v[222:225], v[4:7]
	s_setprio 0
	s_setprio 1
	v_mfma_f32_16x16x32_bf16 v[56:59], v[178:181], v[194:197], v[56:59]
	v_mfma_f32_16x16x32_bf16 v[48:51], v[186:189], v[194:197], v[48:51]
	v_mfma_f32_16x16x32_bf16 v[40:43], v[178:181], v[202:205], v[40:43]
	v_mfma_f32_16x16x32_bf16 v[32:35], v[186:189], v[202:205], v[32:35]
	v_mfma_f32_16x16x32_bf16 v[24:27], v[178:181], v[210:213], v[24:27]
	v_mfma_f32_16x16x32_bf16 v[16:19], v[186:189], v[210:213], v[16:19]
	v_mfma_f32_16x16x32_bf16 v[8:11], v[178:181], v[218:221], v[8:11]
	v_mfma_f32_16x16x32_bf16 v[0:3], v[186:189], v[218:221], v[0:3]
	v_mfma_f32_16x16x32_bf16 v[56:59], v[182:185], v[198:201], v[56:59]
	v_mfma_f32_16x16x32_bf16 v[48:51], v[190:193], v[198:201], v[48:51]
	v_mfma_f32_16x16x32_bf16 v[40:43], v[182:185], v[206:209], v[40:43]
	v_mfma_f32_16x16x32_bf16 v[32:35], v[190:193], v[206:209], v[32:35]
	v_mfma_f32_16x16x32_bf16 v[24:27], v[182:185], v[214:217], v[24:27]
	v_mfma_f32_16x16x32_bf16 v[16:19], v[190:193], v[214:217], v[16:19]
	s_barrier
	s_setprio 2
	v_mfma_f32_16x16x32_bf16 v[8:11], v[182:185], v[222:225], v[8:11]
	v_mfma_f32_16x16x32_bf16 v[0:3], v[190:193], v[222:225], v[0:3]
	s_setprio 0
	s_add_i32 s56, s56, 2
	s_add_u32 s54, s54, 0x100
	s_addc_u32 s55, s55, 0
	s_add_u32 s24, s24, 0x100
	s_addc_u32 s25, s25, 0
	s_cmp_gt_u32 s56, 29
	s_cbranch_scc0 .LBB0_2924
	s_and_b64 vcc, exec, s[12:13]
	s_cbranch_vccz .LBB0_2927
	s_barrier

.LBB0_3122:
	ds_read_b128 v[130:133], v177
	ds_read_b128 v[134:137], v177 offset:1024
	ds_read_b128 v[138:141], v177 offset:2048
	ds_read_b128 v[142:145], v177 offset:3072
	ds_read_b128 v[146:149], v179
	ds_read_b128 v[186:189], v179 offset:1024
	ds_read_b128 v[190:193], v179 offset:2048
	ds_read_b128 v[194:197], v179 offset:3072
	s_add_u32 s30, s28, 0xfff80080
	s_addc_u32 s31, s29, -1
	s_cmp_eq_u32 s72, 28
	s_cselect_b32 s35, s6, s31
	s_cselect_b32 s34, s21, s30
	s_cselect_b32 s31, s19, s71
	s_cselect_b32 s30, s27, s70
	v_lshl_add_u64 v[150:151], s[28:29], 0, v[166:167]
	s_add_i32 m0, s41, 0xc000
	ds_read_b128 v[198:201], v181
	ds_read_b128 v[202:205], v181 offset:1024
	ds_read_b128 v[206:209], v181 offset:2048
	ds_read_b128 v[210:213], v181 offset:3072
	ds_read_b128 v[214:217], v181 offset:4096
	ds_read_b128 v[218:221], v181 offset:5120
	ds_read_b128 v[222:225], v181 offset:6144
	ds_read_b128 v[226:229], v181 offset:7168
	global_load_lds_dwordx4 v[150:151], off
	v_lshl_add_u64 v[150:151], s[28:29], 0, v[164:165]
	s_add_i32 m0, s41, 0xe000
	s_nop 0
	global_load_lds_dwordx4 v[150:151], off
	s_waitcnt vmcnt(8)
	s_waitcnt lgkmcnt(0)
	s_barrier
	s_setprio 1
	s_waitcnt lgkmcnt(0)
	v_mfma_f32_16x16x32_bf16 v[124:127], v[130:133], v[198:201], v[124:127]
	v_mfma_f32_16x16x32_bf16 v[120:123], v[138:141], v[198:201], v[120:123]
	v_mfma_f32_16x16x32_bf16 v[108:111], v[130:133], v[206:209], v[108:111]
	v_mfma_f32_16x16x32_bf16 v[100:103], v[138:141], v[206:209], v[100:103]
	v_mfma_f32_16x16x32_bf16 v[92:95], v[130:133], v[214:217], v[92:95]
	v_mfma_f32_16x16x32_bf16 v[84:87], v[138:141], v[214:217], v[84:87]
	v_mfma_f32_16x16x32_bf16 v[76:79], v[130:133], v[222:225], v[76:79]
	v_mfma_f32_16x16x32_bf16 v[68:71], v[138:141], v[222:225], v[68:71]
	v_mfma_f32_16x16x32_bf16 v[124:127], v[134:137], v[202:205], v[124:127]
	v_mfma_f32_16x16x32_bf16 v[120:123], v[142:145], v[202:205], v[120:123]
	v_mfma_f32_16x16x32_bf16 v[108:111], v[134:137], v[210:213], v[108:111]
	v_mfma_f32_16x16x32_bf16 v[100:103], v[142:145], v[210:213], v[100:103]
	v_mfma_f32_16x16x32_bf16 v[92:95], v[134:137], v[218:221], v[92:95]
	v_mfma_f32_16x16x32_bf16 v[84:87], v[142:145], v[218:221], v[84:87]
	v_mfma_f32_16x16x32_bf16 v[76:79], v[134:137], v[226:229], v[76:79]
	v_mfma_f32_16x16x32_bf16 v[68:71], v[142:145], v[226:229], v[68:71]
	s_setprio 0
	s_setprio 1
	v_mfma_f32_16x16x32_bf16 v[116:119], v[146:149], v[198:201], v[116:119]
	v_mfma_f32_16x16x32_bf16 v[112:115], v[190:193], v[198:201], v[112:115]
	v_mfma_f32_16x16x32_bf16 v[104:107], v[146:149], v[206:209], v[104:107]
	v_mfma_f32_16x16x32_bf16 v[96:99], v[190:193], v[206:209], v[96:99]
	v_mfma_f32_16x16x32_bf16 v[88:91], v[146:149], v[214:217], v[88:91]
	v_mfma_f32_16x16x32_bf16 v[80:83], v[190:193], v[214:217], v[80:83]
	v_mfma_f32_16x16x32_bf16 v[72:75], v[146:149], v[222:225], v[72:75]
	v_mfma_f32_16x16x32_bf16 v[64:67], v[190:193], v[222:225], v[64:67]
	v_mfma_f32_16x16x32_bf16 v[116:119], v[186:189], v[202:205], v[116:119]
	v_mfma_f32_16x16x32_bf16 v[112:115], v[194:197], v[202:205], v[112:115]
	v_mfma_f32_16x16x32_bf16 v[104:107], v[186:189], v[210:213], v[104:107]
	v_mfma_f32_16x16x32_bf16 v[96:99], v[194:197], v[210:213], v[96:99]
	v_mfma_f32_16x16x32_bf16 v[88:91], v[186:189], v[218:221], v[88:91]
	v_mfma_f32_16x16x32_bf16 v[80:83], v[194:197], v[218:221], v[80:83]
	s_barrier
	s_setprio 2
	v_mfma_f32_16x16x32_bf16 v[72:75], v[186:189], v[226:229], v[72:75]
	v_mfma_f32_16x16x32_bf16 v[64:67], v[194:197], v[226:229], v[64:67]
	s_setprio 0
	s_add_i32 s73, s56, s67
	v_lshl_add_u64 v[150:151], s[30:31], 0, v[154:155]
	s_mov_b32 m0, s73
	ds_read_b128 v[198:201], v181 offset:16384
	ds_read_b128 v[202:205], v181 offset:17408
	ds_read_b128 v[206:209], v181 offset:18432
	ds_read_b128 v[210:213], v181 offset:19456
	ds_read_b128 v[214:217], v181 offset:20480
	ds_read_b128 v[218:221], v181 offset:21504
	ds_read_b128 v[222:225], v181 offset:22528
	ds_read_b128 v[226:229], v181 offset:23552
	global_load_lds_dwordx4 v[150:151], off
	s_add_i32 m0, s73, 0x2000
	s_add_u32 s74, s30, 0x80000
	v_lshl_add_u64 v[182:183], s[30:31], 0, v[158:159]
	s_addc_u32 s75, s31, 0
	s_add_i32 s73, s57, s67
	global_load_lds_dwordx4 v[182:183], off
	v_lshl_add_u64 v[230:231], s[74:75], 0, v[154:155]
	s_mov_b32 m0, s73
	v_lshl_add_u64 v[232:233], s[34:35], 0, v[156:157]
	global_load_lds_dwordx4 v[230:231], off
	v_lshl_add_u64 v[230:231], s[74:75], 0, v[158:159]
	s_add_i32 m0, s73, 0x2000
	s_nop 0
	global_load_lds_dwordx4 v[230:231], off
	v_lshl_add_u64 v[230:231], s[34:35], 0, v[152:153]
	s_mov_b32 m0, s41
	s_nop 0
	global_load_lds_dwordx4 v[230:231], off
	s_mov_b32 m0, s42
	s_nop 0
	global_load_lds_dwordx4 v[232:233], off
	s_waitcnt vmcnt(8)
	s_waitcnt lgkmcnt(0)
	s_barrier
	s_setprio 1
	s_waitcnt lgkmcnt(0)
	v_mfma_f32_16x16x32_bf16 v[60:63], v[130:133], v[198:201], v[60:63]
	v_mfma_f32_16x16x32_bf16 v[52:55], v[138:141], v[198:201], v[52:55]
	v_mfma_f32_16x16x32_bf16 v[44:47], v[130:133], v[206:209], v[44:47]
	v_mfma_f32_16x16x32_bf16 v[36:39], v[138:141], v[206:209], v[36:39]
	v_mfma_f32_16x16x32_bf16 v[28:31], v[130:133], v[214:217], v[28:31]
	v_mfma_f32_16x16x32_bf16 v[20:23], v[138:141], v[214:217], v[20:23]
	v_mfma_f32_16x16x32_bf16 v[12:15], v[130:133], v[222:225], v[12:15]
	v_mfma_f32_16x16x32_bf16 v[4:7], v[138:141], v[222:225], v[4:7]
	v_mfma_f32_16x16x32_bf16 v[60:63], v[134:137], v[202:205], v[60:63]
	v_mfma_f32_16x16x32_bf16 v[52:55], v[142:145], v[202:205], v[52:55]
	v_mfma_f32_16x16x32_bf16 v[44:47], v[134:137], v[210:213], v[44:47]
	v_mfma_f32_16x16x32_bf16 v[36:39], v[142:145], v[210:213], v[36:39]
	v_mfma_f32_16x16x32_bf16 v[28:31], v[134:137], v[218:221], v[28:31]
	v_mfma_f32_16x16x32_bf16 v[20:23], v[142:145], v[218:221], v[20:23]
	v_mfma_f32_16x16x32_bf16 v[12:15], v[134:137], v[226:229], v[12:15]
	v_mfma_f32_16x16x32_bf16 v[4:7], v[142:145], v[226:229], v[4:7]
	s_setprio 0
	s_setprio 1
	v_mfma_f32_16x16x32_bf16 v[56:59], v[146:149], v[198:201], v[56:59]
	v_mfma_f32_16x16x32_bf16 v[48:51], v[190:193], v[198:201], v[48:51]
	v_mfma_f32_16x16x32_bf16 v[40:43], v[146:149], v[206:209], v[40:43]
	v_mfma_f32_16x16x32_bf16 v[32:35], v[190:193], v[206:209], v[32:35]
	v_mfma_f32_16x16x32_bf16 v[24:27], v[146:149], v[214:217], v[24:27]
	v_mfma_f32_16x16x32_bf16 v[16:19], v[190:193], v[214:217], v[16:19]
	v_mfma_f32_16x16x32_bf16 v[8:11], v[146:149], v[222:225], v[8:11]
	v_mfma_f32_16x16x32_bf16 v[0:3], v[190:193], v[222:225], v[0:3]
	v_mfma_f32_16x16x32_bf16 v[56:59], v[186:189], v[202:205], v[56:59]
	v_mfma_f32_16x16x32_bf16 v[48:51], v[194:197], v[202:205], v[48:51]
	v_mfma_f32_16x16x32_bf16 v[40:43], v[186:189], v[210:213], v[40:43]
	v_mfma_f32_16x16x32_bf16 v[32:35], v[194:197], v[210:213], v[32:35]
	v_mfma_f32_16x16x32_bf16 v[24:27], v[186:189], v[218:221], v[24:27]
	v_mfma_f32_16x16x32_bf16 v[16:19], v[194:197], v[218:221], v[16:19]
	s_barrier
	s_setprio 2
	v_mfma_f32_16x16x32_bf16 v[8:11], v[186:189], v[226:229], v[8:11]
	v_mfma_f32_16x16x32_bf16 v[0:3], v[194:197], v[226:229], v[0:3]
	s_setprio 0
	s_add_i32 s73, 0, 0x18000
	v_add_u32_e32 v129, s73, v173
	s_add_i32 s74, 0, 0x1c000
	ds_read_b128 v[130:133], v129
	ds_read_b128 v[134:137], v129 offset:1024
	ds_read_b128 v[138:141], v129 offset:2048
	ds_read_b128 v[142:145], v129 offset:3072
	v_add_u32_e32 v129, s74, v173
	ds_read_b128 v[146:149], v129
	ds_read_b128 v[186:189], v129 offset:1024
	ds_read_b128 v[190:193], v129 offset:2048
	ds_read_b128 v[194:197], v129 offset:3072
	s_add_u32 s34, s34, 0x80000
	s_addc_u32 s35, s35, 0
	s_mov_b32 m0, s43
	v_lshl_add_u64 v[234:235], s[34:35], 0, v[152:153]
	ds_read_b128 v[198:201], v181 offset:32768
	ds_read_b128 v[202:205], v181 offset:33792
	ds_read_b128 v[206:209], v181 offset:34816
	ds_read_b128 v[210:213], v181 offset:35840
	ds_read_b128 v[214:217], v181 offset:36864
	ds_read_b128 v[218:221], v181 offset:37888
	ds_read_b128 v[222:225], v181 offset:38912
	ds_read_b128 v[226:229], v181 offset:39936
	global_load_lds_dwordx4 v[234:235], off
	v_lshl_add_u64 v[234:235], s[34:35], 0, v[156:157]
	s_mov_b32 m0, s44
	s_nop 0
	global_load_lds_dwordx4 v[234:235], off
	s_waitcnt vmcnt(8)
	s_waitcnt lgkmcnt(0)
	s_barrier
	s_setprio 1
	s_waitcnt lgkmcnt(0)
	v_mfma_f32_16x16x32_bf16 v[124:127], v[130:133], v[198:201], v[124:127]
	v_mfma_f32_16x16x32_bf16 v[120:123], v[138:141], v[198:201], v[120:123]
	v_mfma_f32_16x16x32_bf16 v[108:111], v[130:133], v[206:209], v[108:111]
	v_mfma_f32_16x16x32_bf16 v[100:103], v[138:141], v[206:209], v[100:103]
	v_mfma_f32_16x16x32_bf16 v[92:95], v[130:133], v[214:217], v[92:95]
	v_mfma_f32_16x16x32_bf16 v[84:87], v[138:141], v[214:217], v[84:87]
	v_mfma_f32_16x16x32_bf16 v[76:79], v[130:133], v[222:225], v[76:79]
	v_mfma_f32_16x16x32_bf16 v[68:71], v[138:141], v[222:225], v[68:71]
	v_mfma_f32_16x16x32_bf16 v[124:127], v[134:137], v[202:205], v[124:127]
	v_mfma_f32_16x16x32_bf16 v[120:123], v[142:145], v[202:205], v[120:123]
	v_mfma_f32_16x16x32_bf16 v[108:111], v[134:137], v[210:213], v[108:111]
	v_mfma_f32_16x16x32_bf16 v[100:103], v[142:145], v[210:213], v[100:103]
	v_mfma_f32_16x16x32_bf16 v[92:95], v[134:137], v[218:221], v[92:95]
	v_mfma_f32_16x16x32_bf16 v[84:87], v[142:145], v[218:221], v[84:87]
	v_mfma_f32_16x16x32_bf16 v[76:79], v[134:137], v[226:229], v[76:79]
	v_mfma_f32_16x16x32_bf16 v[68:71], v[142:145], v[226:229], v[68:71]
	s_setprio 0
	s_setprio 1
	v_mfma_f32_16x16x32_bf16 v[116:119], v[146:149], v[198:201], v[116:119]
	v_mfma_f32_16x16x32_bf16 v[112:115], v[190:193], v[198:201], v[112:115]
	v_mfma_f32_16x16x32_bf16 v[104:107], v[146:149], v[206:209], v[104:107]
	v_mfma_f32_16x16x32_bf16 v[96:99], v[190:193], v[206:209], v[96:99]
	v_mfma_f32_16x16x32_bf16 v[88:91], v[146:149], v[214:217], v[88:91]
	v_mfma_f32_16x16x32_bf16 v[80:83], v[190:193], v[214:217], v[80:83]
	v_mfma_f32_16x16x32_bf16 v[72:75], v[146:149], v[222:225], v[72:75]
	v_mfma_f32_16x16x32_bf16 v[64:67], v[190:193], v[222:225], v[64:67]
	v_mfma_f32_16x16x32_bf16 v[116:119], v[186:189], v[202:205], v[116:119]
	v_mfma_f32_16x16x32_bf16 v[112:115], v[194:197], v[202:205], v[112:115]
	v_mfma_f32_16x16x32_bf16 v[104:107], v[186:189], v[210:213], v[104:107]
	v_mfma_f32_16x16x32_bf16 v[96:99], v[194:197], v[210:213], v[96:99]
	v_mfma_f32_16x16x32_bf16 v[88:91], v[186:189], v[218:221], v[88:91]
	v_mfma_f32_16x16x32_bf16 v[80:83], v[194:197], v[218:221], v[80:83]
	s_barrier
	s_setprio 2
	v_mfma_f32_16x16x32_bf16 v[72:75], v[186:189], v[226:229], v[72:75]
	v_mfma_f32_16x16x32_bf16 v[64:67], v[194:197], v[226:229], v[64:67]
	s_setprio 0
	s_add_i32 s34, s73, s67
	v_lshl_add_u64 v[150:151], v[150:151], 0, s[12:13]
	s_mov_b32 m0, s34
	ds_read_b128 v[198:201], v181 offset:49152
	ds_read_b128 v[202:205], v181 offset:50176
	ds_read_b128 v[206:209], v181 offset:51200
	ds_read_b128 v[210:213], v181 offset:52224
	ds_read_b128 v[214:217], v181 offset:53248
	ds_read_b128 v[218:221], v181 offset:54272
	ds_read_b128 v[222:225], v181 offset:55296
	ds_read_b128 v[226:229], v181 offset:56320
	global_load_lds_dwordx4 v[150:151], off
	s_add_i32 m0, s34, 0x2000
	s_add_u32 s30, s30, 0x80080
	v_lshl_add_u64 v[150:151], v[182:183], 0, s[12:13]
	s_addc_u32 s31, s31, 0
	s_add_i32 s34, s74, s67
	global_load_lds_dwordx4 v[150:151], off
	v_lshl_add_u64 v[150:151], s[30:31], 0, v[154:155]
	s_mov_b32 m0, s34
	s_nop 0
	global_load_lds_dwordx4 v[150:151], off
	v_lshl_add_u64 v[150:151], s[30:31], 0, v[158:159]
	s_add_i32 m0, s34, 0x2000
	s_nop 0
	global_load_lds_dwordx4 v[150:151], off
	v_lshl_add_u64 v[150:151], v[230:231], 0, s[12:13]
	s_mov_b32 m0, s49
	s_nop 0
	global_load_lds_dwordx4 v[150:151], off
	v_lshl_add_u64 v[150:151], v[232:233], 0, s[12:13]
	s_mov_b32 m0, s50
	s_nop 0
	global_load_lds_dwordx4 v[150:151], off
	s_waitcnt vmcnt(8)
	s_waitcnt lgkmcnt(0)
	s_barrier
	s_setprio 1
	s_waitcnt lgkmcnt(0)
	v_mfma_f32_16x16x32_bf16 v[60:63], v[130:133], v[198:201], v[60:63]
	v_mfma_f32_16x16x32_bf16 v[52:55], v[138:141], v[198:201], v[52:55]
	v_mfma_f32_16x16x32_bf16 v[44:47], v[130:133], v[206:209], v[44:47]
	v_mfma_f32_16x16x32_bf16 v[36:39], v[138:141], v[206:209], v[36:39]
	v_mfma_f32_16x16x32_bf16 v[28:31], v[130:133], v[214:217], v[28:31]
	v_mfma_f32_16x16x32_bf16 v[20:23], v[138:141], v[214:217], v[20:23]
	v_mfma_f32_16x16x32_bf16 v[12:15], v[130:133], v[222:225], v[12:15]
	v_mfma_f32_16x16x32_bf16 v[4:7], v[138:141], v[222:225], v[4:7]
	v_mfma_f32_16x16x32_bf16 v[60:63], v[134:137], v[202:205], v[60:63]
	v_mfma_f32_16x16x32_bf16 v[52:55], v[142:145], v[202:205], v[52:55]
	v_mfma_f32_16x16x32_bf16 v[44:47], v[134:137], v[210:213], v[44:47]
	v_mfma_f32_16x16x32_bf16 v[36:39], v[142:145], v[210:213], v[36:39]
	v_mfma_f32_16x16x32_bf16 v[28:31], v[134:137], v[218:221], v[28:31]
	v_mfma_f32_16x16x32_bf16 v[20:23], v[142:145], v[218:221], v[20:23]
	v_mfma_f32_16x16x32_bf16 v[12:15], v[134:137], v[226:229], v[12:15]
	v_mfma_f32_16x16x32_bf16 v[4:7], v[142:145], v[226:229], v[4:7]
	s_setprio 0
	s_setprio 1
	v_mfma_f32_16x16x32_bf16 v[56:59], v[146:149], v[198:201], v[56:59]
	v_mfma_f32_16x16x32_bf16 v[48:51], v[190:193], v[198:201], v[48:51]
	v_mfma_f32_16x16x32_bf16 v[40:43], v[146:149], v[206:209], v[40:43]
	v_mfma_f32_16x16x32_bf16 v[32:35], v[190:193], v[206:209], v[32:35]
	v_mfma_f32_16x16x32_bf16 v[24:27], v[146:149], v[214:217], v[24:27]
	v_mfma_f32_16x16x32_bf16 v[16:19], v[190:193], v[214:217], v[16:19]
	v_mfma_f32_16x16x32_bf16 v[8:11], v[146:149], v[222:225], v[8:11]
	v_mfma_f32_16x16x32_bf16 v[0:3], v[190:193], v[222:225], v[0:3]
	v_mfma_f32_16x16x32_bf16 v[56:59], v[186:189], v[202:205], v[56:59]
	v_mfma_f32_16x16x32_bf16 v[48:51], v[194:197], v[202:205], v[48:51]
	v_mfma_f32_16x16x32_bf16 v[40:43], v[186:189], v[210:213], v[40:43]
	v_mfma_f32_16x16x32_bf16 v[32:35], v[194:197], v[210:213], v[32:35]
	v_mfma_f32_16x16x32_bf16 v[24:27], v[186:189], v[218:221], v[24:27]
	v_mfma_f32_16x16x32_bf16 v[16:19], v[194:197], v[218:221], v[16:19]
	s_barrier
	s_setprio 2
	v_mfma_f32_16x16x32_bf16 v[8:11], v[186:189], v[226:229], v[8:11]
	v_mfma_f32_16x16x32_bf16 v[0:3], v[194:197], v[226:229], v[0:3]
	s_setprio 0
	s_add_i32 s72, s72, 2
	s_add_u32 s70, s70, 0x100
	s_addc_u32 s71, s71, 0
	s_add_u32 s28, s28, 0x100
	s_addc_u32 s29, s29, 0
	s_cmp_gt_u32 s72, 29
	s_cbranch_scc0 .LBB0_3122
	s_and_b64 vcc, exec, s[14:15]
	s_cbranch_vccz .LBB0_3125
	s_barrier

.LBB0_3281:
	ds_read_b128 v[128:131], v231
	ds_read_b128 v[132:135], v231 offset:1024
	ds_read_b128 v[136:139], v231 offset:2048
	ds_read_b128 v[140:143], v231 offset:3072
	ds_read_b128 v[144:147], v232
	ds_read_b128 v[148:151], v232 offset:1024
	ds_read_b128 v[152:155], v232 offset:2048
	ds_read_b128 v[174:177], v232 offset:3072
	s_add_u32 s24, s22, 0xfff80080
	s_addc_u32 s25, s23, -1
	s_cmp_eq_u32 s30, 28
	s_cselect_b32 s27, s3, s25
	s_cselect_b32 s26, s15, s24
	s_cselect_b32 s25, s13, s29
	s_cselect_b32 s24, s21, s28
	v_lshl_add_u64 v[210:211], s[22:23], 0, v[168:169]
	s_add_i32 m0, s40, 0xc000
	ds_read_b128 v[178:181], v233
	ds_read_b128 v[182:185], v233 offset:1024
	ds_read_b128 v[186:189], v233 offset:2048
	ds_read_b128 v[190:193], v233 offset:3072
	ds_read_b128 v[194:197], v233 offset:4096
	ds_read_b128 v[198:201], v233 offset:5120
	ds_read_b128 v[202:205], v233 offset:6144
	ds_read_b128 v[206:209], v233 offset:7168
	global_load_lds_dwordx4 v[210:211], off
	v_lshl_add_u64 v[210:211], s[22:23], 0, v[166:167]
	s_add_i32 m0, s40, 0xe000
	s_nop 0
	global_load_lds_dwordx4 v[210:211], off
	s_waitcnt vmcnt(8)
	s_waitcnt lgkmcnt(0)
	s_barrier
	s_setprio 1
	s_waitcnt lgkmcnt(0)
	v_mfma_f32_16x16x32_bf16 v[124:127], v[128:131], v[178:181], v[124:127]
	v_mfma_f32_16x16x32_bf16 v[120:123], v[136:139], v[178:181], v[120:123]
	v_mfma_f32_16x16x32_bf16 v[116:119], v[128:131], v[186:189], v[116:119]
	v_mfma_f32_16x16x32_bf16 v[112:115], v[136:139], v[186:189], v[112:115]
	v_mfma_f32_16x16x32_bf16 v[108:111], v[128:131], v[194:197], v[108:111]
	v_mfma_f32_16x16x32_bf16 v[104:107], v[136:139], v[194:197], v[104:107]
	v_mfma_f32_16x16x32_bf16 v[100:103], v[128:131], v[202:205], v[100:103]
	v_mfma_f32_16x16x32_bf16 v[96:99], v[136:139], v[202:205], v[96:99]
	v_mfma_f32_16x16x32_bf16 v[124:127], v[132:135], v[182:185], v[124:127]
	v_mfma_f32_16x16x32_bf16 v[120:123], v[140:143], v[182:185], v[120:123]
	v_mfma_f32_16x16x32_bf16 v[116:119], v[132:135], v[190:193], v[116:119]
	v_mfma_f32_16x16x32_bf16 v[112:115], v[140:143], v[190:193], v[112:115]
	v_mfma_f32_16x16x32_bf16 v[108:111], v[132:135], v[198:201], v[108:111]
	v_mfma_f32_16x16x32_bf16 v[104:107], v[140:143], v[198:201], v[104:107]
	v_mfma_f32_16x16x32_bf16 v[100:103], v[132:135], v[206:209], v[100:103]
	v_mfma_f32_16x16x32_bf16 v[96:99], v[140:143], v[206:209], v[96:99]
	s_setprio 0
	s_setprio 1
	v_mfma_f32_16x16x32_bf16 v[60:63], v[144:147], v[178:181], v[60:63]
	v_mfma_f32_16x16x32_bf16 v[56:59], v[152:155], v[178:181], v[56:59]
	v_mfma_f32_16x16x32_bf16 v[52:55], v[144:147], v[186:189], v[52:55]
	v_mfma_f32_16x16x32_bf16 v[48:51], v[152:155], v[186:189], v[48:51]
	v_mfma_f32_16x16x32_bf16 v[44:47], v[144:147], v[194:197], v[44:47]
	v_mfma_f32_16x16x32_bf16 v[40:43], v[152:155], v[194:197], v[40:43]
	v_mfma_f32_16x16x32_bf16 v[36:39], v[144:147], v[202:205], v[36:39]
	v_mfma_f32_16x16x32_bf16 v[32:35], v[152:155], v[202:205], v[32:35]
	v_mfma_f32_16x16x32_bf16 v[60:63], v[148:151], v[182:185], v[60:63]
	v_mfma_f32_16x16x32_bf16 v[56:59], v[174:177], v[182:185], v[56:59]
	v_mfma_f32_16x16x32_bf16 v[52:55], v[148:151], v[190:193], v[52:55]
	v_mfma_f32_16x16x32_bf16 v[48:51], v[174:177], v[190:193], v[48:51]
	v_mfma_f32_16x16x32_bf16 v[44:47], v[148:151], v[198:201], v[44:47]
	v_mfma_f32_16x16x32_bf16 v[40:43], v[174:177], v[198:201], v[40:43]
	s_barrier
	s_setprio 2
	v_mfma_f32_16x16x32_bf16 v[36:39], v[148:151], v[206:209], v[36:39]
	v_mfma_f32_16x16x32_bf16 v[32:35], v[174:177], v[206:209], v[32:35]
	s_setprio 0
	s_add_i32 s31, s64, s67
	v_lshl_add_u64 v[210:211], s[24:25], 0, v[158:159]
	s_mov_b32 m0, s31
	ds_read_b128 v[178:181], v233 offset:16384
	ds_read_b128 v[182:185], v233 offset:17408
	ds_read_b128 v[186:189], v233 offset:18432
	ds_read_b128 v[190:193], v233 offset:19456
	ds_read_b128 v[194:197], v233 offset:20480
	ds_read_b128 v[198:201], v233 offset:21504
	ds_read_b128 v[202:205], v233 offset:22528
	ds_read_b128 v[206:209], v233 offset:23552
	global_load_lds_dwordx4 v[210:211], off
	s_add_i32 m0, s31, 0x2000
	s_add_u32 s34, s24, 0x80000
	v_lshl_add_u64 v[212:213], s[24:25], 0, v[162:163]
	s_addc_u32 s35, s25, 0
	s_add_i32 s31, s65, s67
	global_load_lds_dwordx4 v[212:213], off
	v_lshl_add_u64 v[214:215], s[34:35], 0, v[158:159]
	s_mov_b32 m0, s31
	v_lshl_add_u64 v[216:217], s[26:27], 0, v[160:161]
	global_load_lds_dwordx4 v[214:215], off
	v_lshl_add_u64 v[214:215], s[34:35], 0, v[162:163]
	s_add_i32 m0, s31, 0x2000
	s_nop 0
	global_load_lds_dwordx4 v[214:215], off
	v_lshl_add_u64 v[214:215], s[26:27], 0, v[156:157]
	s_mov_b32 m0, s40
	s_nop 0
	global_load_lds_dwordx4 v[214:215], off
	s_mov_b32 m0, s41
	s_nop 0
	global_load_lds_dwordx4 v[216:217], off
	s_waitcnt vmcnt(8)
	s_waitcnt lgkmcnt(0)
	s_barrier
	s_setprio 1
	s_waitcnt lgkmcnt(0)
	v_mfma_f32_16x16x32_bf16 v[92:95], v[128:131], v[178:181], v[92:95]
	v_mfma_f32_16x16x32_bf16 v[88:91], v[136:139], v[178:181], v[88:91]
	v_mfma_f32_16x16x32_bf16 v[84:87], v[128:131], v[186:189], v[84:87]
	v_mfma_f32_16x16x32_bf16 v[80:83], v[136:139], v[186:189], v[80:83]
	v_mfma_f32_16x16x32_bf16 v[76:79], v[128:131], v[194:197], v[76:79]
	v_mfma_f32_16x16x32_bf16 v[72:75], v[136:139], v[194:197], v[72:75]
	v_mfma_f32_16x16x32_bf16 v[68:71], v[128:131], v[202:205], v[68:71]
	v_mfma_f32_16x16x32_bf16 v[64:67], v[136:139], v[202:205], v[64:67]
	v_mfma_f32_16x16x32_bf16 v[92:95], v[132:135], v[182:185], v[92:95]
	v_mfma_f32_16x16x32_bf16 v[88:91], v[140:143], v[182:185], v[88:91]
	v_mfma_f32_16x16x32_bf16 v[84:87], v[132:135], v[190:193], v[84:87]
	v_mfma_f32_16x16x32_bf16 v[80:83], v[140:143], v[190:193], v[80:83]
	v_mfma_f32_16x16x32_bf16 v[76:79], v[132:135], v[198:201], v[76:79]
	v_mfma_f32_16x16x32_bf16 v[72:75], v[140:143], v[198:201], v[72:75]
	v_mfma_f32_16x16x32_bf16 v[68:71], v[132:135], v[206:209], v[68:71]
	v_mfma_f32_16x16x32_bf16 v[64:67], v[140:143], v[206:209], v[64:67]
	s_setprio 0
	s_setprio 1
	v_mfma_f32_16x16x32_bf16 v[28:31], v[144:147], v[178:181], v[28:31]
	v_mfma_f32_16x16x32_bf16 v[24:27], v[152:155], v[178:181], v[24:27]
	v_mfma_f32_16x16x32_bf16 v[20:23], v[144:147], v[186:189], v[20:23]
	v_mfma_f32_16x16x32_bf16 v[16:19], v[152:155], v[186:189], v[16:19]
	v_mfma_f32_16x16x32_bf16 v[12:15], v[144:147], v[194:197], v[12:15]
	v_mfma_f32_16x16x32_bf16 v[8:11], v[152:155], v[194:197], v[8:11]
	v_mfma_f32_16x16x32_bf16 v[4:7], v[144:147], v[202:205], v[4:7]
	v_mfma_f32_16x16x32_bf16 v[0:3], v[152:155], v[202:205], v[0:3]
	v_mfma_f32_16x16x32_bf16 v[28:31], v[148:151], v[182:185], v[28:31]
	v_mfma_f32_16x16x32_bf16 v[24:27], v[174:177], v[182:185], v[24:27]
	v_mfma_f32_16x16x32_bf16 v[20:23], v[148:151], v[190:193], v[20:23]
	v_mfma_f32_16x16x32_bf16 v[16:19], v[174:177], v[190:193], v[16:19]
	v_mfma_f32_16x16x32_bf16 v[12:15], v[148:151], v[198:201], v[12:15]
	v_mfma_f32_16x16x32_bf16 v[8:11], v[174:177], v[198:201], v[8:11]
	s_barrier
	s_setprio 2
	v_mfma_f32_16x16x32_bf16 v[4:7], v[148:151], v[206:209], v[4:7]
	v_mfma_f32_16x16x32_bf16 v[0:3], v[174:177], v[206:209], v[0:3]
	s_setprio 0
	s_add_i32 s31, 0, 0x18000
	s_add_i32 s34, 0, 0x1c000
	v_add_u32_e32 v140, s31, v230
	v_add_u32_e32 v164, s34, v230
	ds_read_b128 v[128:131], v140
	ds_read_b128 v[132:135], v140 offset:1024
	ds_read_b128 v[136:139], v140 offset:2048
	ds_read_b128 v[140:143], v140 offset:3072
	ds_read_b128 v[144:147], v164
	ds_read_b128 v[148:151], v164 offset:1024
	ds_read_b128 v[152:155], v164 offset:2048
	ds_read_b128 v[174:177], v164 offset:3072
	s_add_u32 s26, s26, 0x80000
	s_addc_u32 s27, s27, 0
	s_mov_b32 m0, s42
	v_lshl_add_u64 v[218:219], s[26:27], 0, v[156:157]
	ds_read_b128 v[178:181], v233 offset:32768
	ds_read_b128 v[182:185], v233 offset:33792
	ds_read_b128 v[186:189], v233 offset:34816
	ds_read_b128 v[190:193], v233 offset:35840
	ds_read_b128 v[194:197], v233 offset:36864
	ds_read_b128 v[198:201], v233 offset:37888
	ds_read_b128 v[202:205], v233 offset:38912
	ds_read_b128 v[206:209], v233 offset:39936
	global_load_lds_dwordx4 v[218:219], off
	v_lshl_add_u64 v[218:219], s[26:27], 0, v[160:161]
	s_mov_b32 m0, s43
	s_nop 0
	global_load_lds_dwordx4 v[218:219], off
	s_waitcnt vmcnt(8)
	s_waitcnt lgkmcnt(0)
	s_barrier
	s_setprio 1
	s_waitcnt lgkmcnt(0)
	v_mfma_f32_16x16x32_bf16 v[124:127], v[128:131], v[178:181], v[124:127]
	v_mfma_f32_16x16x32_bf16 v[120:123], v[136:139], v[178:181], v[120:123]
	v_mfma_f32_16x16x32_bf16 v[116:119], v[128:131], v[186:189], v[116:119]
	v_mfma_f32_16x16x32_bf16 v[112:115], v[136:139], v[186:189], v[112:115]
	v_mfma_f32_16x16x32_bf16 v[108:111], v[128:131], v[194:197], v[108:111]
	v_mfma_f32_16x16x32_bf16 v[104:107], v[136:139], v[194:197], v[104:107]
	v_mfma_f32_16x16x32_bf16 v[100:103], v[128:131], v[202:205], v[100:103]
	v_mfma_f32_16x16x32_bf16 v[96:99], v[136:139], v[202:205], v[96:99]
	v_mfma_f32_16x16x32_bf16 v[124:127], v[132:135], v[182:185], v[124:127]
	v_mfma_f32_16x16x32_bf16 v[120:123], v[140:143], v[182:185], v[120:123]
	v_mfma_f32_16x16x32_bf16 v[116:119], v[132:135], v[190:193], v[116:119]
	v_mfma_f32_16x16x32_bf16 v[112:115], v[140:143], v[190:193], v[112:115]
	v_mfma_f32_16x16x32_bf16 v[108:111], v[132:135], v[198:201], v[108:111]
	v_mfma_f32_16x16x32_bf16 v[104:107], v[140:143], v[198:201], v[104:107]
	v_mfma_f32_16x16x32_bf16 v[100:103], v[132:135], v[206:209], v[100:103]
	v_mfma_f32_16x16x32_bf16 v[96:99], v[140:143], v[206:209], v[96:99]
	s_setprio 0
	s_setprio 1
	v_mfma_f32_16x16x32_bf16 v[60:63], v[144:147], v[178:181], v[60:63]
	v_mfma_f32_16x16x32_bf16 v[56:59], v[152:155], v[178:181], v[56:59]
	v_mfma_f32_16x16x32_bf16 v[52:55], v[144:147], v[186:189], v[52:55]
	v_mfma_f32_16x16x32_bf16 v[48:51], v[152:155], v[186:189], v[48:51]
	v_mfma_f32_16x16x32_bf16 v[44:47], v[144:147], v[194:197], v[44:47]
	v_mfma_f32_16x16x32_bf16 v[40:43], v[152:155], v[194:197], v[40:43]
	v_mfma_f32_16x16x32_bf16 v[36:39], v[144:147], v[202:205], v[36:39]
	v_mfma_f32_16x16x32_bf16 v[32:35], v[152:155], v[202:205], v[32:35]
	v_mfma_f32_16x16x32_bf16 v[60:63], v[148:151], v[182:185], v[60:63]
	v_mfma_f32_16x16x32_bf16 v[56:59], v[174:177], v[182:185], v[56:59]
	v_mfma_f32_16x16x32_bf16 v[52:55], v[148:151], v[190:193], v[52:55]
	v_mfma_f32_16x16x32_bf16 v[48:51], v[174:177], v[190:193], v[48:51]
	v_mfma_f32_16x16x32_bf16 v[44:47], v[148:151], v[198:201], v[44:47]
	v_mfma_f32_16x16x32_bf16 v[40:43], v[174:177], v[198:201], v[40:43]
	s_barrier
	s_setprio 2
	v_mfma_f32_16x16x32_bf16 v[36:39], v[148:151], v[206:209], v[36:39]
	v_mfma_f32_16x16x32_bf16 v[32:35], v[174:177], v[206:209], v[32:35]
	s_setprio 0
	s_add_i32 s26, s31, s67
	v_lshl_add_u64 v[210:211], v[210:211], 0, s[6:7]
	s_mov_b32 m0, s26
	ds_read_b128 v[178:181], v233 offset:49152
	ds_read_b128 v[182:185], v233 offset:50176
	ds_read_b128 v[186:189], v233 offset:51200
	ds_read_b128 v[190:193], v233 offset:52224
	ds_read_b128 v[194:197], v233 offset:53248
	ds_read_b128 v[198:201], v233 offset:54272
	ds_read_b128 v[202:205], v233 offset:55296
	ds_read_b128 v[206:209], v233 offset:56320
	global_load_lds_dwordx4 v[210:211], off
	s_add_i32 m0, s26, 0x2000
	s_add_u32 s24, s24, 0x80080
	v_lshl_add_u64 v[210:211], v[212:213], 0, s[6:7]
	s_addc_u32 s25, s25, 0
	s_add_i32 s26, s34, s67
	global_load_lds_dwordx4 v[210:211], off
	v_lshl_add_u64 v[210:211], s[24:25], 0, v[158:159]
	s_mov_b32 m0, s26
	s_nop 0
	global_load_lds_dwordx4 v[210:211], off
	v_lshl_add_u64 v[210:211], s[24:25], 0, v[162:163]
	s_add_i32 m0, s26, 0x2000
	s_nop 0
	global_load_lds_dwordx4 v[210:211], off
	v_lshl_add_u64 v[210:211], v[214:215], 0, s[6:7]
	s_mov_b32 m0, s57
	s_nop 0
	global_load_lds_dwordx4 v[210:211], off
	v_lshl_add_u64 v[210:211], v[216:217], 0, s[6:7]
	s_mov_b32 m0, s58
	s_nop 0
	global_load_lds_dwordx4 v[210:211], off
	s_waitcnt vmcnt(8)
	s_waitcnt lgkmcnt(0)
	s_barrier
	s_setprio 1
	s_waitcnt lgkmcnt(0)
	v_mfma_f32_16x16x32_bf16 v[92:95], v[128:131], v[178:181], v[92:95]
	v_mfma_f32_16x16x32_bf16 v[88:91], v[136:139], v[178:181], v[88:91]
	v_mfma_f32_16x16x32_bf16 v[84:87], v[128:131], v[186:189], v[84:87]
	v_mfma_f32_16x16x32_bf16 v[80:83], v[136:139], v[186:189], v[80:83]
	v_mfma_f32_16x16x32_bf16 v[76:79], v[128:131], v[194:197], v[76:79]
	v_mfma_f32_16x16x32_bf16 v[72:75], v[136:139], v[194:197], v[72:75]
	v_mfma_f32_16x16x32_bf16 v[68:71], v[128:131], v[202:205], v[68:71]
	v_mfma_f32_16x16x32_bf16 v[64:67], v[136:139], v[202:205], v[64:67]
	v_mfma_f32_16x16x32_bf16 v[92:95], v[132:135], v[182:185], v[92:95]
	v_mfma_f32_16x16x32_bf16 v[88:91], v[140:143], v[182:185], v[88:91]
	v_mfma_f32_16x16x32_bf16 v[84:87], v[132:135], v[190:193], v[84:87]
	v_mfma_f32_16x16x32_bf16 v[80:83], v[140:143], v[190:193], v[80:83]
	v_mfma_f32_16x16x32_bf16 v[76:79], v[132:135], v[198:201], v[76:79]
	v_mfma_f32_16x16x32_bf16 v[72:75], v[140:143], v[198:201], v[72:75]
	v_mfma_f32_16x16x32_bf16 v[68:71], v[132:135], v[206:209], v[68:71]
	v_mfma_f32_16x16x32_bf16 v[64:67], v[140:143], v[206:209], v[64:67]
	s_setprio 0
	s_setprio 1
	v_mfma_f32_16x16x32_bf16 v[28:31], v[144:147], v[178:181], v[28:31]
	v_mfma_f32_16x16x32_bf16 v[24:27], v[152:155], v[178:181], v[24:27]
	v_mfma_f32_16x16x32_bf16 v[20:23], v[144:147], v[186:189], v[20:23]
	v_mfma_f32_16x16x32_bf16 v[16:19], v[152:155], v[186:189], v[16:19]
	v_mfma_f32_16x16x32_bf16 v[12:15], v[144:147], v[194:197], v[12:15]
	v_mfma_f32_16x16x32_bf16 v[8:11], v[152:155], v[194:197], v[8:11]
	v_mfma_f32_16x16x32_bf16 v[4:7], v[144:147], v[202:205], v[4:7]
	v_mfma_f32_16x16x32_bf16 v[0:3], v[152:155], v[202:205], v[0:3]
	v_mfma_f32_16x16x32_bf16 v[28:31], v[148:151], v[182:185], v[28:31]
	v_mfma_f32_16x16x32_bf16 v[24:27], v[174:177], v[182:185], v[24:27]
	v_mfma_f32_16x16x32_bf16 v[20:23], v[148:151], v[190:193], v[20:23]
	v_mfma_f32_16x16x32_bf16 v[16:19], v[174:177], v[190:193], v[16:19]
	v_mfma_f32_16x16x32_bf16 v[12:15], v[148:151], v[198:201], v[12:15]
	v_mfma_f32_16x16x32_bf16 v[8:11], v[174:177], v[198:201], v[8:11]
	s_barrier
	s_setprio 2
	v_mfma_f32_16x16x32_bf16 v[4:7], v[148:151], v[206:209], v[4:7]
	v_mfma_f32_16x16x32_bf16 v[0:3], v[174:177], v[206:209], v[0:3]
	s_setprio 0
	s_add_i32 s30, s30, 2
	s_add_u32 s28, s28, 0x100
	s_addc_u32 s29, s29, 0
	s_add_u32 s22, s22, 0x100
	s_addc_u32 s23, s23, 0
	s_cmp_gt_u32 s30, 29
	s_cbranch_scc0 .LBB0_3281
	s_and_b64 vcc, exec, s[8:9]
	s_cbranch_vccz .LBB0_3284
	s_barrier

.LBB0_3501:
	ds_read_b128 v[128:131], v201
	ds_read_b128 v[132:135], v201 offset:1024
	ds_read_b128 v[136:139], v201 offset:2048
	ds_read_b128 v[140:143], v201 offset:3072
	ds_read_b128 v[144:147], v202
	ds_read_b128 v[148:151], v202 offset:1024
	ds_read_b128 v[170:173], v202 offset:2048
	ds_read_b128 v[174:177], v202 offset:3072
	s_add_u32 s18, s16, 0x100
	s_addc_u32 s19, s17, 0
	s_cmpk_eq_i32 s68, 0x54
	s_cselect_b32 s23, s3, s19
	s_cselect_b32 s22, s2, s18
	s_cselect_b32 s21, s15, s25
	s_cselect_b32 s20, s14, s24
	v_lshl_add_u64 v[198:199], s[16:17], 0, v[164:165]
	s_add_i32 m0, s30, 0xc000
	ds_read_b128 v[178:181], v203
	ds_read_b128 v[182:185], v203 offset:1024
	ds_read_b128 v[186:189], v203 offset:2048
	ds_read_b128 v[190:193], v203 offset:3072
	ds_read_b128 v[194:197], v203 offset:4096
	ds_read_b128 v[206:209], v203 offset:5120
	ds_read_b128 v[210:213], v203 offset:6144
	ds_read_b128 v[214:217], v203 offset:7168
	global_load_lds_dwordx4 v[198:199], off
	v_lshl_add_u64 v[198:199], s[16:17], 0, v[162:163]
	s_add_i32 m0, s30, 0xe000
	s_nop 0
	global_load_lds_dwordx4 v[198:199], off
	s_waitcnt vmcnt(8)
	s_waitcnt lgkmcnt(0)
	s_barrier
	s_setprio 1
	s_waitcnt lgkmcnt(0)
	v_mfma_f32_16x16x32_bf16 v[124:127], v[128:131], v[178:181], v[124:127]
	v_mfma_f32_16x16x32_bf16 v[120:123], v[136:139], v[178:181], v[120:123]
	v_mfma_f32_16x16x32_bf16 v[116:119], v[128:131], v[186:189], v[116:119]
	v_mfma_f32_16x16x32_bf16 v[112:115], v[136:139], v[186:189], v[112:115]
	v_mfma_f32_16x16x32_bf16 v[108:111], v[128:131], v[194:197], v[108:111]
	v_mfma_f32_16x16x32_bf16 v[104:107], v[136:139], v[194:197], v[104:107]
	v_mfma_f32_16x16x32_bf16 v[100:103], v[128:131], v[210:213], v[100:103]
	v_mfma_f32_16x16x32_bf16 v[96:99], v[136:139], v[210:213], v[96:99]
	v_mfma_f32_16x16x32_bf16 v[124:127], v[132:135], v[182:185], v[124:127]
	v_mfma_f32_16x16x32_bf16 v[120:123], v[140:143], v[182:185], v[120:123]
	v_mfma_f32_16x16x32_bf16 v[116:119], v[132:135], v[190:193], v[116:119]
	v_mfma_f32_16x16x32_bf16 v[112:115], v[140:143], v[190:193], v[112:115]
	v_mfma_f32_16x16x32_bf16 v[108:111], v[132:135], v[206:209], v[108:111]
	v_mfma_f32_16x16x32_bf16 v[104:107], v[140:143], v[206:209], v[104:107]
	v_mfma_f32_16x16x32_bf16 v[100:103], v[132:135], v[214:217], v[100:103]
	v_mfma_f32_16x16x32_bf16 v[96:99], v[140:143], v[214:217], v[96:99]
	s_setprio 0
	s_setprio 1
	v_mfma_f32_16x16x32_bf16 v[60:63], v[144:147], v[178:181], v[60:63]
	v_mfma_f32_16x16x32_bf16 v[56:59], v[170:173], v[178:181], v[56:59]
	v_mfma_f32_16x16x32_bf16 v[52:55], v[144:147], v[186:189], v[52:55]
	v_mfma_f32_16x16x32_bf16 v[48:51], v[170:173], v[186:189], v[48:51]
	v_mfma_f32_16x16x32_bf16 v[44:47], v[144:147], v[194:197], v[44:47]
	v_mfma_f32_16x16x32_bf16 v[40:43], v[170:173], v[194:197], v[40:43]
	v_mfma_f32_16x16x32_bf16 v[36:39], v[144:147], v[210:213], v[36:39]
	v_mfma_f32_16x16x32_bf16 v[32:35], v[170:173], v[210:213], v[32:35]
	v_mfma_f32_16x16x32_bf16 v[60:63], v[148:151], v[182:185], v[60:63]
	v_mfma_f32_16x16x32_bf16 v[56:59], v[174:177], v[182:185], v[56:59]
	v_mfma_f32_16x16x32_bf16 v[52:55], v[148:151], v[190:193], v[52:55]
	v_mfma_f32_16x16x32_bf16 v[48:51], v[174:177], v[190:193], v[48:51]
	v_mfma_f32_16x16x32_bf16 v[44:47], v[148:151], v[206:209], v[44:47]
	v_mfma_f32_16x16x32_bf16 v[40:43], v[174:177], v[206:209], v[40:43]
	s_barrier
	s_setprio 2
	v_mfma_f32_16x16x32_bf16 v[36:39], v[148:151], v[214:217], v[36:39]
	v_mfma_f32_16x16x32_bf16 v[32:35], v[174:177], v[214:217], v[32:35]
	s_setprio 0
	s_add_i32 s16, s52, s67
	v_lshl_add_u64 v[198:199], s[20:21], 0, v[154:155]
	s_mov_b32 m0, s16
	ds_read_b128 v[178:181], v203 offset:16384
	ds_read_b128 v[182:185], v203 offset:17408
	ds_read_b128 v[186:189], v203 offset:18432
	ds_read_b128 v[190:193], v203 offset:19456
	ds_read_b128 v[194:197], v203 offset:20480
	ds_read_b128 v[206:209], v203 offset:21504
	ds_read_b128 v[210:213], v203 offset:22528
	ds_read_b128 v[214:217], v203 offset:23552
	global_load_lds_dwordx4 v[198:199], off
	s_add_i32 m0, s16, 0x2000
	s_add_u32 s16, s20, 0x160000
	v_lshl_add_u64 v[218:219], s[20:21], 0, v[158:159]
	s_addc_u32 s17, s21, 0
	s_add_i32 s69, s53, s67
	global_load_lds_dwordx4 v[218:219], off
	v_lshl_add_u64 v[220:221], s[16:17], 0, v[154:155]
	s_mov_b32 m0, s69
	v_lshl_add_u64 v[222:223], s[22:23], 0, v[156:157]
	global_load_lds_dwordx4 v[220:221], off
	v_lshl_add_u64 v[220:221], s[16:17], 0, v[158:159]
	s_add_i32 m0, s69, 0x2000
	s_nop 0
	global_load_lds_dwordx4 v[220:221], off
	v_lshl_add_u64 v[220:221], s[22:23], 0, v[152:153]
	s_mov_b32 m0, s30
	s_nop 0
	global_load_lds_dwordx4 v[220:221], off
	s_mov_b32 m0, s31
	s_nop 0
	global_load_lds_dwordx4 v[222:223], off
	s_waitcnt vmcnt(8)
	s_waitcnt lgkmcnt(0)
	s_barrier
	s_setprio 1
	s_waitcnt lgkmcnt(0)
	v_mfma_f32_16x16x32_bf16 v[92:95], v[128:131], v[178:181], v[92:95]
	v_mfma_f32_16x16x32_bf16 v[88:91], v[136:139], v[178:181], v[88:91]
	v_mfma_f32_16x16x32_bf16 v[84:87], v[128:131], v[186:189], v[84:87]
	v_mfma_f32_16x16x32_bf16 v[80:83], v[136:139], v[186:189], v[80:83]
	v_mfma_f32_16x16x32_bf16 v[76:79], v[128:131], v[194:197], v[76:79]
	v_mfma_f32_16x16x32_bf16 v[72:75], v[136:139], v[194:197], v[72:75]
	v_mfma_f32_16x16x32_bf16 v[68:71], v[128:131], v[210:213], v[68:71]
	v_mfma_f32_16x16x32_bf16 v[64:67], v[136:139], v[210:213], v[64:67]
	v_mfma_f32_16x16x32_bf16 v[92:95], v[132:135], v[182:185], v[92:95]
	v_mfma_f32_16x16x32_bf16 v[88:91], v[140:143], v[182:185], v[88:91]
	v_mfma_f32_16x16x32_bf16 v[84:87], v[132:135], v[190:193], v[84:87]
	v_mfma_f32_16x16x32_bf16 v[80:83], v[140:143], v[190:193], v[80:83]
	v_mfma_f32_16x16x32_bf16 v[76:79], v[132:135], v[206:209], v[76:79]
	v_mfma_f32_16x16x32_bf16 v[72:75], v[140:143], v[206:209], v[72:75]
	v_mfma_f32_16x16x32_bf16 v[68:71], v[132:135], v[214:217], v[68:71]
	v_mfma_f32_16x16x32_bf16 v[64:67], v[140:143], v[214:217], v[64:67]
	s_setprio 0
	s_setprio 1
	v_mfma_f32_16x16x32_bf16 v[28:31], v[144:147], v[178:181], v[28:31]
	v_mfma_f32_16x16x32_bf16 v[24:27], v[170:173], v[178:181], v[24:27]
	v_mfma_f32_16x16x32_bf16 v[20:23], v[144:147], v[186:189], v[20:23]
	v_mfma_f32_16x16x32_bf16 v[16:19], v[170:173], v[186:189], v[16:19]
	v_mfma_f32_16x16x32_bf16 v[12:15], v[144:147], v[194:197], v[12:15]
	v_mfma_f32_16x16x32_bf16 v[8:11], v[170:173], v[194:197], v[8:11]
	v_mfma_f32_16x16x32_bf16 v[4:7], v[144:147], v[210:213], v[4:7]
	v_mfma_f32_16x16x32_bf16 v[0:3], v[170:173], v[210:213], v[0:3]
	v_mfma_f32_16x16x32_bf16 v[28:31], v[148:151], v[182:185], v[28:31]
	v_mfma_f32_16x16x32_bf16 v[24:27], v[174:177], v[182:185], v[24:27]
	v_mfma_f32_16x16x32_bf16 v[20:23], v[148:151], v[190:193], v[20:23]
	v_mfma_f32_16x16x32_bf16 v[16:19], v[174:177], v[190:193], v[16:19]
	v_mfma_f32_16x16x32_bf16 v[12:15], v[148:151], v[206:209], v[12:15]
	v_mfma_f32_16x16x32_bf16 v[8:11], v[174:177], v[206:209], v[8:11]
	s_barrier
	s_setprio 2
	v_mfma_f32_16x16x32_bf16 v[4:7], v[148:151], v[214:217], v[4:7]
	v_mfma_f32_16x16x32_bf16 v[0:3], v[174:177], v[214:217], v[0:3]
	s_setprio 0
	s_add_i32 s69, 0, 0x18000
	s_add_i32 s70, 0, 0x1c000
	v_add_u32_e32 v140, s69, v200
	v_add_u32_e32 v160, s70, v200
	ds_read_b128 v[128:131], v140
	ds_read_b128 v[132:135], v140 offset:1024
	ds_read_b128 v[136:139], v140 offset:2048
	ds_read_b128 v[140:143], v140 offset:3072
	ds_read_b128 v[144:147], v160
	ds_read_b128 v[148:151], v160 offset:1024
	ds_read_b128 v[170:173], v160 offset:2048
	ds_read_b128 v[174:177], v160 offset:3072
	s_add_u32 s16, s22, 0x160000
	s_addc_u32 s17, s23, 0
	s_mov_b32 m0, s34
	v_lshl_add_u64 v[224:225], s[16:17], 0, v[152:153]
	ds_read_b128 v[178:181], v203 offset:32768
	ds_read_b128 v[182:185], v203 offset:33792
	ds_read_b128 v[186:189], v203 offset:34816
	ds_read_b128 v[190:193], v203 offset:35840
	ds_read_b128 v[194:197], v203 offset:36864
	ds_read_b128 v[206:209], v203 offset:37888
	ds_read_b128 v[210:213], v203 offset:38912
	ds_read_b128 v[214:217], v203 offset:39936
	global_load_lds_dwordx4 v[224:225], off
	v_lshl_add_u64 v[224:225], s[16:17], 0, v[156:157]
	s_mov_b32 m0, s35
	s_nop 0
	global_load_lds_dwordx4 v[224:225], off
	s_waitcnt vmcnt(8)
	s_waitcnt lgkmcnt(0)
	s_barrier
	s_setprio 1
	s_waitcnt lgkmcnt(0)
	v_mfma_f32_16x16x32_bf16 v[124:127], v[128:131], v[178:181], v[124:127]
	v_mfma_f32_16x16x32_bf16 v[120:123], v[136:139], v[178:181], v[120:123]
	v_mfma_f32_16x16x32_bf16 v[116:119], v[128:131], v[186:189], v[116:119]
	v_mfma_f32_16x16x32_bf16 v[112:115], v[136:139], v[186:189], v[112:115]
	v_mfma_f32_16x16x32_bf16 v[108:111], v[128:131], v[194:197], v[108:111]
	v_mfma_f32_16x16x32_bf16 v[104:107], v[136:139], v[194:197], v[104:107]
	v_mfma_f32_16x16x32_bf16 v[100:103], v[128:131], v[210:213], v[100:103]
	v_mfma_f32_16x16x32_bf16 v[96:99], v[136:139], v[210:213], v[96:99]
	v_mfma_f32_16x16x32_bf16 v[124:127], v[132:135], v[182:185], v[124:127]
	v_mfma_f32_16x16x32_bf16 v[120:123], v[140:143], v[182:185], v[120:123]
	v_mfma_f32_16x16x32_bf16 v[116:119], v[132:135], v[190:193], v[116:119]
	v_mfma_f32_16x16x32_bf16 v[112:115], v[140:143], v[190:193], v[112:115]
	v_mfma_f32_16x16x32_bf16 v[108:111], v[132:135], v[206:209], v[108:111]
	v_mfma_f32_16x16x32_bf16 v[104:107], v[140:143], v[206:209], v[104:107]
	v_mfma_f32_16x16x32_bf16 v[100:103], v[132:135], v[214:217], v[100:103]
	v_mfma_f32_16x16x32_bf16 v[96:99], v[140:143], v[214:217], v[96:99]
	s_setprio 0
	s_setprio 1
	v_mfma_f32_16x16x32_bf16 v[60:63], v[144:147], v[178:181], v[60:63]
	v_mfma_f32_16x16x32_bf16 v[56:59], v[170:173], v[178:181], v[56:59]
	v_mfma_f32_16x16x32_bf16 v[52:55], v[144:147], v[186:189], v[52:55]
	v_mfma_f32_16x16x32_bf16 v[48:51], v[170:173], v[186:189], v[48:51]
	v_mfma_f32_16x16x32_bf16 v[44:47], v[144:147], v[194:197], v[44:47]
	v_mfma_f32_16x16x32_bf16 v[40:43], v[170:173], v[194:197], v[40:43]
	v_mfma_f32_16x16x32_bf16 v[36:39], v[144:147], v[210:213], v[36:39]
	v_mfma_f32_16x16x32_bf16 v[32:35], v[170:173], v[210:213], v[32:35]
	v_mfma_f32_16x16x32_bf16 v[60:63], v[148:151], v[182:185], v[60:63]
	v_mfma_f32_16x16x32_bf16 v[56:59], v[174:177], v[182:185], v[56:59]
	v_mfma_f32_16x16x32_bf16 v[52:55], v[148:151], v[190:193], v[52:55]
	v_mfma_f32_16x16x32_bf16 v[48:51], v[174:177], v[190:193], v[48:51]
	v_mfma_f32_16x16x32_bf16 v[44:47], v[148:151], v[206:209], v[44:47]
	v_mfma_f32_16x16x32_bf16 v[40:43], v[174:177], v[206:209], v[40:43]
	s_barrier
	s_setprio 2
	v_mfma_f32_16x16x32_bf16 v[36:39], v[148:151], v[214:217], v[36:39]
	v_mfma_f32_16x16x32_bf16 v[32:35], v[174:177], v[214:217], v[32:35]
	s_setprio 0
	s_add_i32 s16, s69, s67
	v_lshl_add_u64 v[198:199], v[198:199], 0, s[8:9]
	s_mov_b32 m0, s16
	ds_read_b128 v[178:181], v203 offset:49152
	ds_read_b128 v[182:185], v203 offset:50176
	ds_read_b128 v[186:189], v203 offset:51200
	ds_read_b128 v[190:193], v203 offset:52224
	ds_read_b128 v[194:197], v203 offset:53248
	ds_read_b128 v[206:209], v203 offset:54272
	ds_read_b128 v[210:213], v203 offset:55296
	ds_read_b128 v[214:217], v203 offset:56320
	global_load_lds_dwordx4 v[198:199], off
	s_add_i32 m0, s16, 0x2000
	s_add_u32 s16, s20, 0x160080
	v_lshl_add_u64 v[198:199], v[218:219], 0, s[8:9]
	s_addc_u32 s17, s21, 0
	s_add_i32 s20, s70, s67
	global_load_lds_dwordx4 v[198:199], off
	v_lshl_add_u64 v[198:199], s[16:17], 0, v[154:155]
	s_mov_b32 m0, s20
	s_nop 0
	global_load_lds_dwordx4 v[198:199], off
	v_lshl_add_u64 v[198:199], s[16:17], 0, v[158:159]
	s_add_i32 m0, s20, 0x2000
	s_nop 0
	global_load_lds_dwordx4 v[198:199], off
	v_lshl_add_u64 v[198:199], v[220:221], 0, s[8:9]
	s_mov_b32 m0, s47
	s_nop 0
	global_load_lds_dwordx4 v[198:199], off
	v_lshl_add_u64 v[198:199], v[222:223], 0, s[8:9]
	s_mov_b32 m0, s48
	s_nop 0
	global_load_lds_dwordx4 v[198:199], off
	s_waitcnt vmcnt(8)
	s_waitcnt lgkmcnt(0)
	s_barrier
	s_setprio 1
	s_waitcnt lgkmcnt(0)
	v_mfma_f32_16x16x32_bf16 v[92:95], v[128:131], v[178:181], v[92:95]
	v_mfma_f32_16x16x32_bf16 v[88:91], v[136:139], v[178:181], v[88:91]
	v_mfma_f32_16x16x32_bf16 v[84:87], v[128:131], v[186:189], v[84:87]
	v_mfma_f32_16x16x32_bf16 v[80:83], v[136:139], v[186:189], v[80:83]
	v_mfma_f32_16x16x32_bf16 v[76:79], v[128:131], v[194:197], v[76:79]
	v_mfma_f32_16x16x32_bf16 v[72:75], v[136:139], v[194:197], v[72:75]
	v_mfma_f32_16x16x32_bf16 v[68:71], v[128:131], v[210:213], v[68:71]
	v_mfma_f32_16x16x32_bf16 v[64:67], v[136:139], v[210:213], v[64:67]
	v_mfma_f32_16x16x32_bf16 v[92:95], v[132:135], v[182:185], v[92:95]
	v_mfma_f32_16x16x32_bf16 v[88:91], v[140:143], v[182:185], v[88:91]
	v_mfma_f32_16x16x32_bf16 v[84:87], v[132:135], v[190:193], v[84:87]
	v_mfma_f32_16x16x32_bf16 v[80:83], v[140:143], v[190:193], v[80:83]
	v_mfma_f32_16x16x32_bf16 v[76:79], v[132:135], v[206:209], v[76:79]
	v_mfma_f32_16x16x32_bf16 v[72:75], v[140:143], v[206:209], v[72:75]
	v_mfma_f32_16x16x32_bf16 v[68:71], v[132:135], v[214:217], v[68:71]
	v_mfma_f32_16x16x32_bf16 v[64:67], v[140:143], v[214:217], v[64:67]
	s_setprio 0
	s_setprio 1
	v_mfma_f32_16x16x32_bf16 v[28:31], v[144:147], v[178:181], v[28:31]
	v_mfma_f32_16x16x32_bf16 v[24:27], v[170:173], v[178:181], v[24:27]
	v_mfma_f32_16x16x32_bf16 v[20:23], v[144:147], v[186:189], v[20:23]
	v_mfma_f32_16x16x32_bf16 v[16:19], v[170:173], v[186:189], v[16:19]
	v_mfma_f32_16x16x32_bf16 v[12:15], v[144:147], v[194:197], v[12:15]
	v_mfma_f32_16x16x32_bf16 v[8:11], v[170:173], v[194:197], v[8:11]
	v_mfma_f32_16x16x32_bf16 v[4:7], v[144:147], v[210:213], v[4:7]
	v_mfma_f32_16x16x32_bf16 v[0:3], v[170:173], v[210:213], v[0:3]
	v_mfma_f32_16x16x32_bf16 v[28:31], v[148:151], v[182:185], v[28:31]
	v_mfma_f32_16x16x32_bf16 v[24:27], v[174:177], v[182:185], v[24:27]
	v_mfma_f32_16x16x32_bf16 v[20:23], v[148:151], v[190:193], v[20:23]
	v_mfma_f32_16x16x32_bf16 v[16:19], v[174:177], v[190:193], v[16:19]
	v_mfma_f32_16x16x32_bf16 v[12:15], v[148:151], v[206:209], v[12:15]
	v_mfma_f32_16x16x32_bf16 v[8:11], v[174:177], v[206:209], v[8:11]
	s_barrier
	s_setprio 2
	v_mfma_f32_16x16x32_bf16 v[4:7], v[148:151], v[214:217], v[4:7]
	v_mfma_f32_16x16x32_bf16 v[0:3], v[174:177], v[214:217], v[0:3]
	s_setprio 0
	s_add_i32 s68, s68, 2
	s_add_u32 s24, s24, 0x100
	s_addc_u32 s25, s25, 0
	s_cmpk_gt_u32 s68, 0x55
	s_mov_b64 s[16:17], s[18:19]
	s_cbranch_scc0 .LBB0_3501
	s_and_b64 vcc, exec, s[10:11]
	s_cbranch_vccz .LBB0_3504
	s_barrier
